# combo26 + FFT forward twiddle multiplies folded the same way (60 sites: -(c,s) pair + v_mov + v_pk_mul -> one v_pk_mul with neg_hi)
# speedup vs baseline: 1.0073x; 1.0043x over previous
.Lmy_fft_kj:
	v_mov_b32 v66, 0
	v_mov_b32_e32 v68, v1
	v_add_u32_e32 v0, v66, v0
	v_cvt_f32_i32_e32 v70, v0
	v_ashrrev_i32_e32 v66, 5, v0
	v_lshlrev_b32_e32 v69, 3, v0
	v_add_u32_e32 v73, 0x400, v0
	v_add_u32_e32 v75, 0x800, v0
	v_add_u32_e32 v76, 0xc00, v0
	v_add_u32_e32 v78, 0x1000, v0
	v_add_u32_e32 v80, 0x1400, v0
	v_add_u32_e32 v82, 0x1800, v0
	v_add_u32_e32 v85, 0x1c00, v0
	v_add_u32_e32 v87, 0x2000, v0
	v_add_u32_e32 v89, 0x2400, v0
	v_add_u32_e32 v91, 0x2800, v0
	v_add_u32_e32 v92, 0x2c00, v0
	v_add_u32_e32 v95, 0x3000, v0
	v_add_u32_e32 v96, 0x3400, v0
	v_add_u32_e32 v99, 0x3800, v0
	v_add_u32_e32 v0, 0x3c00, v0
	v_lshlrev_b32_e32 v66, 3, v66
	v_ashrrev_i32_e32 v73, 5, v73
	v_ashrrev_i32_e32 v75, 5, v75
	v_ashrrev_i32_e32 v76, 5, v76
	v_ashrrev_i32_e32 v78, 5, v78
	v_ashrrev_i32_e32 v80, 5, v80
	v_ashrrev_i32_e32 v82, 5, v82
	v_ashrrev_i32_e32 v85, 5, v85
	v_ashrrev_i32_e32 v100, 5, v87
	v_ashrrev_i32_e32 v103, 5, v89
	v_ashrrev_i32_e32 v105, 5, v91
	v_ashrrev_i32_e32 v106, 5, v92
	v_ashrrev_i32_e32 v107, 5, v95
	v_ashrrev_i32_e32 v124, 5, v96
	v_ashrrev_i32_e32 v125, 5, v99
	v_ashrrev_i32_e32 v126, 5, v0
	v_lshlrev_b32_e32 v0, 3, v0
	v_add3_u32 v127, 0, v66, v69
	v_lshlrev_b32_e32 v66, 3, v73
	v_lshlrev_b32_e32 v73, 3, v75
	v_lshlrev_b32_e32 v75, 3, v76
	v_lshlrev_b32_e32 v76, 3, v78
	v_lshlrev_b32_e32 v78, 3, v80
	v_lshlrev_b32_e32 v80, 3, v82
	v_lshlrev_b32_e32 v82, 3, v85
	v_lshlrev_b32_e32 v85, 3, v100
	v_lshlrev_b32_e32 v100, 3, v103
	v_lshlrev_b32_e32 v103, 3, v105
	v_lshlrev_b32_e32 v105, 3, v106
	v_lshlrev_b32_e32 v106, 3, v107
	v_lshlrev_b32_e32 v107, 3, v124
	v_lshlrev_b32_e32 v124, 3, v125
	v_lshlrev_b32_e32 v125, 3, v126
	v_lshlrev_b32_e32 v96, 3, v96
	v_add3_u32 v196, 0, v125, v0
	v_mul_f32_e32 v0, 0x38800000, v70
	v_lshlrev_b32_e32 v95, 3, v95
	v_add3_u32 v194, 0, v107, v96
	v_sin_f32_e32 v107, v0
	v_add3_u32 v193, 0, v106, v95
	v_cos_f32_e32 v106, v0
	v_lshlrev_b32_e32 v99, 3, v99
	v_add3_u32 v195, 0, v124, v99
	v_xor_b32_e32 v124, 0x80000000, v107
	v_mov_b32_e32 v125, v107
	v_pk_mul_f32 v[128:129], v[124:125], v[106:107] op_sel:[0,1] op_sel_hi:[1,0]
	v_lshlrev_b32_e32 v87, 3, v87
	v_pk_fma_f32 v[128:129], v[106:107], v[106:107], v[128:129] op_sel_hi:[1,0,1]
	v_add3_u32 v186, 0, v76, v69
	v_pk_mul_f32 v[132:133], v[124:125], v[128:129] op_sel:[0,1] op_sel_hi:[1,0]
	s_waitcnt vmcnt(21)
	v_sub_f32_e32 v70, v112, v120
	v_pk_fma_f32 v[132:133], v[128:129], v[106:107], v[132:133] op_sel_hi:[1,0,1]
	s_waitcnt vmcnt(20)
	v_sub_f32_e32 v76, v113, v121
	v_pk_mul_f32 v[136:137], v[124:125], v[132:133] op_sel:[0,1] op_sel_hi:[1,0]
	v_add3_u32 v171, 0, v66, v69
	v_pk_fma_f32 v[136:137], v[132:133], v[106:107], v[136:137] op_sel_hi:[1,0,1]
	v_add3_u32 v184, 0, v73, v69
	v_pk_mul_f32 v[140:141], v[124:125], v[136:137] op_sel:[0,1] op_sel_hi:[1,0]
	v_add3_u32 v190, 0, v85, v87
	v_pk_fma_f32 v[140:141], v[136:137], v[106:107], v[140:141] op_sel_hi:[1,0,1]
	v_sub_f32_e32 v66, v109, v119
	v_pk_mul_f32 v[144:145], v[124:125], v[140:141] op_sel:[0,1] op_sel_hi:[1,0]
	v_mul_f32_e32 v73, 0xbf3504f3, v70
	v_pk_fma_f32 v[144:145], v[140:141], v[106:107], v[144:145] op_sel_hi:[1,0,1]
	v_mul_f32_e32 v85, 0xbf6c835e, v76
	v_pk_mul_f32 v[148:149], v[124:125], v[144:145] op_sel:[0,1] op_sel_hi:[1,0]
	v_lshlrev_b32_e32 v91, 3, v91
	v_pk_fma_f32 v[148:149], v[144:145], v[106:107], v[148:149] op_sel_hi:[1,0,1]
	v_add3_u32 v185, 0, v75, v69
	v_pk_mul_f32 v[152:153], v[124:125], v[148:149] op_sel:[0,1] op_sel_hi:[1,0]
	v_add3_u32 v187, 0, v78, v69
	v_pk_fma_f32 v[152:153], v[148:149], v[106:107], v[152:153] op_sel_hi:[1,0,1]
	v_add3_u32 v188, 0, v80, v69
	v_pk_mul_f32 v[156:157], v[124:125], v[152:153] op_sel:[0,1] op_sel_hi:[1,0]
	v_add3_u32 v189, 0, v82, v69
	v_pk_fma_f32 v[156:157], v[152:153], v[106:107], v[156:157] op_sel_hi:[1,0,1]
	v_sub_f32_e32 v0, v108, v118
	v_pk_mul_f32 v[160:161], v[124:125], v[156:157] op_sel:[0,1] op_sel_hi:[1,0]
	v_pk_add_f32 v[108:109], v[108:109], v[118:119]
	v_pk_fma_f32 v[160:161], v[156:157], v[106:107], v[160:161] op_sel_hi:[1,0,1]
	v_mul_f32_e32 v69, 0xbec3ef15, v66
	v_pk_mul_f32 v[164:165], v[124:125], v[160:161] op_sel:[0,1] op_sel_hi:[1,0]
	v_pk_fma_f32 v[70:71], v[70:71], s[10:11], v[72:73] op_sel_hi:[1,0,1]
	v_pk_fma_f32 v[72:73], v[76:77], s[14:15], v[84:85] op_sel_hi:[1,0,1]
	s_waitcnt vmcnt(18)
	v_sub_f32_e32 v82, v115, v123
	v_pk_add_f32 v[76:77], v[114:115], v[122:123]
	v_mov_b32_e32 v83, v1
	v_mov_b32_e32 v90, v1
	s_movk_i32 s5, 0x200
	v_lshlrev_b32_e32 v89, 3, v89
	v_add3_u32 v192, 0, v103, v91
	v_pk_fma_f32 v[164:165], v[160:161], v[106:107], v[164:165] op_sel_hi:[1,0,1]
	v_pk_fma_f32 v[66:67], v[66:67], s[6:7], v[68:69] op_sel_hi:[1,0,1]
	v_pk_add_f32 v[68:69], v[112:113], v[120:121]
	v_mul_f32_e32 v91, 0xbf6c835e, v82
	s_waitcnt vmcnt(17)
	v_sub_f32_e32 v80, v116, v110
	v_pk_add_f32 v[112:113], v[108:109], v[76:77] neg_lo:[0,1] neg_hi:[0,1]
	v_mov_b32_e32 v81, v1
	v_mov_b32_e32 v88, v1
	v_mov_b32_e32 v101, v1
	v_mov_b32_e32 v102, v1
	v_add3_u32 v191, 0, v100, v89
	v_pk_mul_f32 v[168:169], v[124:125], v[164:165] op_sel:[0,1] op_sel_hi:[1,0]
	v_pk_fma_f32 v[82:83], v[82:83], s[4:5], v[90:91] op_sel_hi:[1,0,1]
	v_mul_f32_e32 v89, 0xbf3504f3, v80
	s_waitcnt vmcnt(16)
	v_sub_f32_e32 v78, v117, v111
	v_pk_add_f32 v[90:91], v[116:117], v[110:111]
	v_mov_b32_e32 v100, v113
	v_mul_f32_e32 v103, 0xbf3504f3, v113
	v_mov_b32_e32 v79, v1
	v_mov_b32_e32 v86, v1
	v_pk_fma_f32 v[168:169], v[164:165], v[106:107], v[168:169] op_sel_hi:[1,0,1]
	v_sub_f32_e32 v75, v114, v122
	v_pk_fma_f32 v[80:81], v[80:81], s[8:9], v[88:89] op_sel_hi:[1,0,1]
	v_mul_f32_e32 v87, 0xbec3ef15, v78
	v_pk_add_f32 v[88:89], v[66:67], v[82:83]
	v_pk_add_f32 v[66:67], v[66:67], v[82:83] neg_lo:[0,1] neg_hi:[0,1]
	v_pk_fma_f32 v[82:83], v[100:101], s[10:11], v[102:103] op_sel_hi:[1,0,1]
	v_pk_add_f32 v[100:101], v[68:69], v[90:91] neg_lo:[0,1] neg_hi:[0,1]
	v_mov_b32_e32 v74, v1
	v_mov_b32_e32 v97, v1
	v_mov_b32_e32 v98, v1
	v_pk_mul_f32 v[174:175], v[124:125], v[168:169] op_sel:[0,1] op_sel_hi:[1,0]
	v_xor_b32_e32 v75, 0x80000000, v75
	v_pk_add_f32 v[76:77], v[108:109], v[76:77]
	v_pk_add_f32 v[68:69], v[68:69], v[90:91]
	v_pk_fma_f32 v[78:79], v[78:79], s[12:13], v[86:87] op_sel_hi:[1,0,1]
	v_pk_add_f32 v[90:91], v[70:71], v[80:81]
	v_pk_add_f32 v[70:71], v[70:71], v[80:81] neg_lo:[0,1] neg_hi:[0,1]
	v_mov_b32_e32 v96, v101
	v_mul_f32_e32 v99, 0xbf3504f3, v101
	v_lshlrev_b32_e32 v92, 3, v92
	v_pk_fma_f32 v[174:175], v[168:169], v[106:107], v[174:175] op_sel_hi:[1,0,1]
	v_pk_add_f32 v[84:85], v[0:1], v[74:75]
	v_pk_add_f32 v[80:81], v[76:77], v[68:69] neg_lo:[0,1] neg_hi:[0,1]
	v_pk_add_f32 v[68:69], v[76:77], v[68:69]
	v_xor_b32_e32 v77, 0x80000000, v70
	v_mov_b32_e32 v76, v71
	v_pk_add_f32 v[70:71], v[72:73], v[78:79]
	v_pk_add_f32 v[72:73], v[72:73], v[78:79] neg_lo:[0,1] neg_hi:[0,1]
	v_pk_fma_f32 v[78:79], v[96:97], s[8:9], v[98:99] op_sel_hi:[1,0,1]
	v_mov_b32_e32 v94, v1
	v_add3_u32 v105, 0, v105, v92
	v_pk_mul_f32 v[178:179], v[124:125], v[174:175] op_sel:[0,1] op_sel_hi:[1,0]
	v_pk_add_f32 v[74:75], v[0:1], v[74:75] neg_lo:[0,1] neg_hi:[0,1]
	v_mov_b32_e32 v0, v112
	v_pk_mul_f32 v[86:87], v[66:67], s[16:17]
	v_xor_b32_e32 v95, 0x80000000, v100
	v_mov_b32_e32 v92, v80
	v_pk_add_f32 v[80:81], v[80:81], 0 neg_lo:[1,1] neg_hi:[1,1]
	v_pk_add_f32 v[96:97], v[84:85], v[90:91]
	v_pk_add_f32 v[84:85], v[84:85], v[90:91] neg_lo:[0,1] neg_hi:[0,1]
	v_pk_add_f32 v[90:91], v[68:69], v[68:69] op_sel:[0,1] op_sel_hi:[1,0]
	v_pk_mul_f32 v[98:99], v[72:73], s[16:17]
	v_pk_add_f32 v[100:101], v[82:83], v[78:79]
	v_pk_add_f32 v[78:79], v[82:83], v[78:79] neg_lo:[0,1] neg_hi:[0,1]
	v_pk_add_f32 v[82:83], v[88:89], v[70:71]
	v_pk_add_f32 v[70:71], v[88:89], v[70:71] neg_lo:[0,1] neg_hi:[0,1]
	v_mov_b32_e32 v93, v1
	v_mov_b32_e32 v126, v107
	v_pk_add_f32 v[130:131], v[128:129], 0 neg_lo:[1,1] neg_hi:[1,1]
	v_pk_add_f32 v[158:159], v[156:157], 0 neg_lo:[1,1] neg_hi:[1,1]
	v_pk_fma_f32 v[178:179], v[174:175], v[106:107], v[178:179] op_sel_hi:[1,0,1]
	v_pk_fma_f32 v[66:67], v[66:67], s[10:11], v[86:87] op_sel:[0,0,1] op_sel_hi:[1,0,0]
	v_pk_add_f32 v[86:87], v[0:1], v[94:95]
	v_pk_add_f32 v[94:95], v[0:1], v[94:95] neg_lo:[0,1] neg_hi:[0,1]
	v_mov_b32_e32 v80, v1
	v_pk_add_f32 v[88:89], v[74:75], v[76:77]
	v_pk_add_f32 v[74:75], v[74:75], v[76:77] neg_lo:[0,1] neg_hi:[0,1]
	v_mov_b32_e32 v91, v1
	v_pk_fma_f32 v[72:73], v[72:73], s[8:9], v[98:99] op_sel:[0,0,1] op_sel_hi:[1,0,0]
	v_xor_b32_e32 v77, 0x80000000, v78
	v_mov_b32_e32 v76, v79
	v_xor_b32_e32 v79, 0x80000000, v70
	v_mov_b32_e32 v78, v71
	v_pk_add_f32 v[98:99], v[96:97], v[82:83]
	v_mov_b32_e32 v130, v129
	v_pk_add_f32 v[134:135], v[132:133], 0 neg_lo:[1,1] neg_hi:[1,1]
	v_pk_add_f32 v[142:143], v[140:141], 0 neg_lo:[1,1] neg_hi:[1,1]
	v_mov_b32_e32 v158, v157
	v_pk_mul_f32 v[124:125], v[124:125], v[178:179] op_sel:[0,1] op_sel_hi:[1,0]
	v_pk_add_f32 v[70:71], v[92:93], v[80:81]
	v_pk_add_f32 v[80:81], v[92:93], v[80:81] neg_lo:[0,1] neg_hi:[0,1]
	v_pk_add_f32 v[92:93], v[86:87], v[100:101]
	v_pk_add_f32 v[82:83], v[96:97], v[82:83] neg_lo:[0,1] neg_hi:[0,1]
	ds_write_b64 v127, v[90:91]
	v_pk_add_f32 v[90:91], v[66:67], v[72:73]
	v_pk_add_f32 v[112:113], v[66:67], v[72:73] op_sel:[1,1] op_sel_hi:[0,0] neg_lo:[0,1] neg_hi:[1,0]
	v_pk_add_f32 v[72:73], v[94:95], v[76:77]
	v_pk_add_f32 v[76:77], v[94:95], v[76:77] neg_lo:[0,1] neg_hi:[0,1]
	v_pk_add_f32 v[94:95], v[84:85], v[78:79]
	v_pk_add_f32 v[78:79], v[84:85], v[78:79] neg_lo:[0,1] neg_hi:[0,1]
	v_pk_mul_f32 v[84:85], v[126:127], v[98:99] op_sel:[0,1] op_sel_hi:[0,0] neg_hi:[1,0]
	v_mov_b32_e32 v134, v133
	v_pk_add_f32 v[138:139], v[136:137], 0 neg_lo:[1,1] neg_hi:[1,1]
	v_mov_b32_e32 v142, v141
	v_pk_add_f32 v[146:147], v[144:145], 0 neg_lo:[1,1] neg_hi:[1,1]
	v_pk_add_f32 v[150:151], v[148:149], 0 neg_lo:[1,1] neg_hi:[1,1]
	v_pk_add_f32 v[166:167], v[164:165], 0 neg_lo:[1,1] neg_hi:[1,1]
	v_pk_fma_f32 v[124:125], v[178:179], v[106:107], v[124:125] op_sel_hi:[1,0,1]
	v_pk_mul_f32 v[96:97], v[92:93], v[130:131] op_sel:[1,0] op_sel_hi:[0,1]
	v_pk_mul_f32 v[102:103], v[82:83], v[158:159] op_sel:[1,0] op_sel_hi:[0,1]
	v_pk_add_f32 v[66:67], v[88:89], v[90:91]
	v_pk_fma_f32 v[84:85], v[98:99], v[106:107], v[84:85] op_sel_hi:[1,0,1]
	v_mov_b32_e32 v138, v137
	v_mov_b32_e32 v146, v145
	v_mov_b32_e32 v150, v149
	v_pk_add_f32 v[154:155], v[152:153], 0 neg_lo:[1,1] neg_hi:[1,1]
	v_pk_add_f32 v[162:163], v[160:161], 0 neg_lo:[1,1] neg_hi:[1,1]
	v_mov_b32_e32 v166, v165
	v_pk_add_f32 v[172:173], v[168:169], 0 neg_lo:[1,1] neg_hi:[1,1]
	v_pk_add_f32 v[176:177], v[174:175], 0 neg_lo:[1,1] neg_hi:[1,1]
	v_pk_add_f32 v[180:181], v[178:179], 0 neg_lo:[1,1] neg_hi:[1,1]
	v_pk_add_f32 v[182:183], v[124:125], 0 neg_lo:[1,1] neg_hi:[1,1]
	v_pk_add_f32 v[68:69], v[68:69], v[68:69] op_sel:[0,1] op_sel_hi:[1,0] neg_lo:[0,1] neg_hi:[0,1]
	v_pk_add_f32 v[88:89], v[88:89], v[90:91] neg_lo:[0,1] neg_hi:[0,1]
	v_pk_fma_f32 v[90:91], v[92:93], v[128:129], v[96:97] op_sel_hi:[1,0,1]
	v_pk_mul_f32 v[92:93], v[94:95], v[142:143] op_sel:[1,0] op_sel_hi:[0,1]
	v_pk_fma_f32 v[82:83], v[82:83], v[156:157], v[102:103] op_sel_hi:[1,0,1]
	v_pk_add_f32 v[102:103], v[74:75], v[112:113]
	ds_write_b64 v171, v[84:85] offset:8192
	ds_write_b64 v184, v[90:91] offset:16384
	v_pk_mul_f32 v[84:85], v[66:67], v[134:135] op_sel:[1,0] op_sel_hi:[0,1]
	v_mov_b32_e32 v154, v153
	v_mov_b32_e32 v162, v161
	v_mov_b32_e32 v172, v169
	v_mov_b32_e32 v176, v175
	v_mov_b32_e32 v180, v179
	v_mov_b32_e32 v182, v125
	v_mov_b32_e32 v0, v68
	v_pk_mov_b32 v[68:69], s[2:3], v[68:69] op_sel:[1,0]
	v_pk_add_f32 v[86:87], v[86:87], v[100:101] neg_lo:[0,1] neg_hi:[0,1]
	v_pk_mul_f32 v[100:101], v[70:71], v[138:139] op_sel:[1,0] op_sel_hi:[0,1]
	v_pk_mul_f32 v[96:97], v[72:73], v[146:147] op_sel:[1,0] op_sel_hi:[0,1]
	v_pk_add_f32 v[74:75], v[74:75], v[112:113] neg_lo:[0,1] neg_hi:[0,1]
	v_pk_fma_f32 v[90:91], v[94:95], v[140:141], v[92:93] op_sel_hi:[1,0,1]
	v_pk_mul_f32 v[92:93], v[88:89], v[166:167] op_sel:[1,0] op_sel_hi:[0,1]
	v_pk_fma_f32 v[66:67], v[66:67], v[132:133], v[84:85] op_sel_hi:[1,0,1]
	v_pk_mul_f32 v[84:85], v[102:103], v[150:151] op_sel:[1,0] op_sel_hi:[0,1]
	s_mov_b64 s[46:47], 0
	s_and_b64 vcc, exec, s[0:1]
	v_pk_mul_f32 v[68:69], v[68:69], v[154:155]
	v_pk_mul_f32 v[108:109], v[86:87], v[162:163] op_sel:[1,0] op_sel_hi:[0,1]
	v_pk_mul_f32 v[110:111], v[80:81], v[172:173] op_sel:[1,0] op_sel_hi:[0,1]
	v_pk_fma_f32 v[70:71], v[70:71], v[136:137], v[100:101] op_sel_hi:[1,0,1]
	v_pk_mul_f32 v[98:99], v[78:79], v[176:177] op_sel:[1,0] op_sel_hi:[0,1]
	v_pk_mul_f32 v[100:101], v[76:77], v[180:181] op_sel:[1,0] op_sel_hi:[0,1]
	v_pk_fma_f32 v[72:73], v[72:73], v[144:145], v[96:97] op_sel_hi:[1,0,1]
	v_pk_fma_f32 v[88:89], v[88:89], v[164:165], v[92:93] op_sel_hi:[1,0,1]
	v_pk_mul_f32 v[92:93], v[74:75], v[182:183] op_sel:[1,0] op_sel_hi:[0,1]
	ds_write_b64 v185, v[66:67] offset:24576
	ds_write_b64 v186, v[70:71] offset:32768
	ds_write_b64 v187, v[90:91] offset:40960
	ds_write_b64 v188, v[72:73] offset:49152
	v_pk_fma_f32 v[66:67], v[102:103], v[148:149], v[84:85] op_sel_hi:[1,0,1]
	v_pk_fma_f32 v[68:69], v[0:1], v[152:153], v[68:69] op_sel_hi:[1,0,1]
	v_pk_fma_f32 v[86:87], v[86:87], v[160:161], v[108:109] op_sel_hi:[1,0,1]
	v_pk_fma_f32 v[80:81], v[80:81], v[168:169], v[110:111] op_sel_hi:[1,0,1]
	v_pk_fma_f32 v[78:79], v[78:79], v[174:175], v[98:99] op_sel_hi:[1,0,1]
	v_pk_fma_f32 v[76:77], v[76:77], v[178:179], v[100:101] op_sel_hi:[1,0,1]
	v_pk_fma_f32 v[70:71], v[74:75], v[124:125], v[92:93] op_sel_hi:[1,0,1]
	ds_write_b64 v189, v[66:67] offset:57344
	ds_write_b64 v190, v[68:69]
	ds_write_b64 v191, v[82:83]
	ds_write_b64 v192, v[86:87]
	ds_write_b64 v105, v[88:89]
	ds_write_b64 v193, v[80:81]
	ds_write_b64 v194, v[78:79]
	ds_write_b64 v195, v[76:77]
	ds_write_b64 v196, v[70:71]
	s_cbranch_vccz .LBB0_359
	s_waitcnt lgkmcnt(0)
	s_barrier
	v_mov_b32 v0, 0
	s_mov_b32 s5, s14
	v_add_u32_e32 v74, v0, v170
	v_lshlrev_b32_e32 v0, 5, v74
	v_and_b32_e32 v71, 0xfffffc00, v0
	v_or_b32_e32 v75, 0x80, v71
	v_and_b32_e32 v70, 31, v74
	v_ashrrev_i32_e32 v75, 2, v75
	v_lshlrev_b32_e32 v78, 3, v71
	v_lshlrev_b32_e32 v79, 3, v70
	v_add_u32_e32 v75, 0, v75
	v_add3_u32 v111, v75, v78, v79
	v_or_b32_e32 v75, 0xa0, v71
	v_ashrrev_i32_e32 v75, 2, v75
	v_add_u32_e32 v75, 0, v75
	v_add3_u32 v110, v75, v78, v79
	v_or_b32_e32 v75, 0xc0, v71
	v_ashrrev_i32_e32 v75, 2, v75
	v_add_u32_e32 v75, 0, v75
	v_add3_u32 v109, v75, v78, v79
	v_or_b32_e32 v75, 0xe0, v71
	v_ashrrev_i32_e32 v75, 2, v75
	v_add_u32_e32 v75, 0, v75
	v_add3_u32 v108, v75, v78, v79
	v_or_b32_e32 v75, 0x100, v71
	v_ashrrev_i32_e32 v75, 2, v75
	v_add_u32_e32 v75, 0, v75
	v_add3_u32 v107, v75, v78, v79
	v_or_b32_e32 v75, 0x120, v71
	v_ashrrev_i32_e32 v75, 2, v75
	v_add_u32_e32 v75, 0, v75
	v_add3_u32 v106, v75, v78, v79
	v_or_b32_e32 v75, 0x140, v71
	v_ashrrev_i32_e32 v75, 2, v75
	v_add_u32_e32 v75, 0, v75
	v_add3_u32 v105, v75, v78, v79
	v_or_b32_e32 v75, 0x160, v71
	v_ashrrev_i32_e32 v75, 2, v75
	v_add_u32_e32 v75, 0, v75
	v_add3_u32 v103, v75, v78, v79
	v_or_b32_e32 v75, 0x180, v71
	v_ashrrev_i32_e32 v75, 2, v75
	v_add_u32_e32 v75, 0, v75
	v_add3_u32 v102, v75, v78, v79
	v_or_b32_e32 v75, 0x1a0, v71
	v_ashrrev_i32_e32 v75, 2, v75
	v_add_u32_e32 v75, 0, v75
	v_add3_u32 v101, v75, v78, v79
	v_or_b32_e32 v75, 0x1c0, v71
	v_ashrrev_i32_e32 v75, 2, v75
	v_add_u32_e32 v75, 0, v75
	v_add3_u32 v100, v75, v78, v79
	v_or_b32_e32 v75, 0x1e0, v71
	v_ashrrev_i32_e32 v75, 2, v75
	v_add_u32_e32 v75, 0, v75
	v_add3_u32 v99, v75, v78, v79
	v_or_b32_e32 v75, 0x200, v71
	v_ashrrev_i32_e32 v75, 2, v75
	v_add_u32_e32 v75, 0, v75
	v_add3_u32 v98, v75, v78, v79
	v_or_b32_e32 v75, 0x220, v71
	v_ashrrev_i32_e32 v75, 2, v75
	v_add_u32_e32 v75, 0, v75
	v_add3_u32 v97, v75, v78, v79
	v_or_b32_e32 v75, 0x240, v71
	v_ashrrev_i32_e32 v75, 2, v75
	v_add_u32_e32 v75, 0, v75
	v_add3_u32 v96, v75, v78, v79
	v_or_b32_e32 v75, 0x260, v71
	v_ashrrev_i32_e32 v75, 2, v75
	v_add_u32_e32 v75, 0, v75
	v_add3_u32 v95, v75, v78, v79
	v_or_b32_e32 v75, 0x280, v71
	v_or_b32_e32 v67, 32, v71
	v_ashrrev_i32_e32 v75, 2, v75
	v_ashrrev_i32_e32 v67, 2, v67
	v_add_u32_e32 v75, 0, v75
	v_add_u32_e32 v67, 0, v67
	v_add3_u32 v94, v75, v78, v79
	v_or_b32_e32 v75, 0x2a0, v71
	v_add3_u32 v114, v67, v78, v79
	v_or_b32_e32 v67, 64, v71
	v_ashrrev_i32_e32 v75, 2, v75
	v_ashrrev_i32_e32 v67, 2, v67
	v_add_u32_e32 v75, 0, v75
	v_add_u32_e32 v67, 0, v67
	v_add3_u32 v93, v75, v78, v79
	v_or_b32_e32 v75, 0x2c0, v71
	v_ashrrev_i32_e32 v66, 2, v71
	v_add3_u32 v113, v67, v78, v79
	v_or_b32_e32 v67, 0x60, v71
	v_ashrrev_i32_e32 v75, 2, v75
	v_add_u32_e32 v66, 0, v66
	v_ashrrev_i32_e32 v67, 2, v67
	v_add_u32_e32 v75, 0, v75
	v_add3_u32 v66, v66, v78, v79
	v_add_u32_e32 v67, 0, v67
	v_add3_u32 v92, v75, v78, v79
	v_or_b32_e32 v75, 0x2e0, v71
	v_add3_u32 v112, v67, v78, v79
	ds_read_b64 v[66:67], v66
	ds_read_b64 v[68:69], v114 offset:256
	ds_read_b64 v[72:73], v113 offset:512
	ds_read_b64 v[76:77], v112 offset:768
	ds_read_b64 v[80:81], v111 offset:1024
	ds_read_b64 v[82:83], v110 offset:1280
	ds_read_b64 v[116:117], v109 offset:1536
	ds_read_b64 v[118:119], v108 offset:1792
	ds_read_b64 v[120:121], v107 offset:2048
	ds_read_b64 v[122:123], v106 offset:2304
	ds_read_b64 v[124:125], v105 offset:2560
	ds_read_b64 v[126:127], v103 offset:2816
	ds_read_b64 v[128:129], v102 offset:3072
	ds_read_b64 v[130:131], v101 offset:3328
	ds_read_b64 v[132:133], v100 offset:3584
	ds_read_b64 v[134:135], v99 offset:3840
	ds_read_b64 v[136:137], v98 offset:4096
	ds_read_b64 v[138:139], v97 offset:4352
	ds_read_b64 v[140:141], v96 offset:4608
	ds_read_b64 v[142:143], v95 offset:4864
	v_ashrrev_i32_e32 v75, 2, v75
	v_add_u32_e32 v75, 0, v75
	v_add3_u32 v91, v75, v78, v79
	v_or_b32_e32 v75, 0x300, v71
	v_ashrrev_i32_e32 v75, 2, v75
	s_waitcnt lgkmcnt(3)
	v_pk_add_f32 v[168:169], v[66:67], v[136:137]
	v_pk_add_f32 v[66:67], v[66:67], v[136:137] neg_lo:[0,1] neg_hi:[0,1]
	s_waitcnt lgkmcnt(2)
	v_pk_add_f32 v[136:137], v[68:69], v[138:139]
	v_pk_add_f32 v[68:69], v[68:69], v[138:139] neg_lo:[0,1] neg_hi:[0,1]
	v_add_u32_e32 v75, 0, v75
	v_pk_mul_f32 v[138:139], v[68:69], s[18:19]
	v_add3_u32 v90, v75, v78, v79
	v_or_b32_e32 v75, 0x320, v71
	v_pk_fma_f32 v[68:69], v[68:69], s[20:21], v[138:139] op_sel:[0,0,1] op_sel_hi:[1,0,0]
	s_waitcnt lgkmcnt(1)
	v_pk_add_f32 v[138:139], v[72:73], v[140:141]
	v_pk_add_f32 v[72:73], v[72:73], v[140:141] neg_lo:[0,1] neg_hi:[0,1]
	v_ashrrev_i32_e32 v75, 2, v75
	v_pk_mul_f32 v[140:141], v[72:73], s[4:5]
	ds_read_b64 v[144:145], v94 offset:5120
	ds_read_b64 v[146:147], v93 offset:5376
	ds_read_b64 v[148:149], v92 offset:5632
	ds_read_b64 v[150:151], v91 offset:5888
	v_add_u32_e32 v75, 0, v75
	v_pk_fma_f32 v[72:73], v[72:73], s[6:7], v[140:141] op_sel:[0,0,1] op_sel_hi:[1,0,0]
	s_waitcnt lgkmcnt(4)
	v_pk_add_f32 v[140:141], v[76:77], v[142:143]
	v_pk_add_f32 v[76:77], v[76:77], v[142:143] neg_lo:[0,1] neg_hi:[0,1]
	v_add3_u32 v89, v75, v78, v79
	v_or_b32_e32 v75, 0x340, v71
	v_pk_mul_f32 v[142:143], v[76:77], s[22:23]
	v_ashrrev_i32_e32 v75, 2, v75
	v_pk_fma_f32 v[76:77], v[76:77], s[24:25], v[142:143] op_sel:[0,0,1] op_sel_hi:[1,0,0]
	s_waitcnt lgkmcnt(3)
	v_pk_add_f32 v[142:143], v[80:81], v[144:145]
	v_pk_add_f32 v[80:81], v[80:81], v[144:145] neg_lo:[0,1] neg_hi:[0,1]
	s_mov_b32 s9, s10
	v_add_u32_e32 v75, 0, v75
	v_pk_mul_f32 v[144:145], v[80:81], s[8:9]
	v_add3_u32 v88, v75, v78, v79
	v_or_b32_e32 v75, 0x360, v71
	v_pk_fma_f32 v[80:81], v[80:81], s[10:11], v[144:145] op_sel:[0,0,1] op_sel_hi:[1,0,0]
	s_waitcnt lgkmcnt(2)
	v_pk_add_f32 v[144:145], v[82:83], v[146:147]
	v_pk_add_f32 v[82:83], v[82:83], v[146:147] neg_lo:[0,1] neg_hi:[0,1]
	s_mov_b32 s27, s24
	v_ashrrev_i32_e32 v75, 2, v75
	v_pk_mul_f32 v[146:147], v[82:83], s[26:27]
	s_mov_b32 s0, s23
	v_add_u32_e32 v75, 0, v75
	v_pk_fma_f32 v[82:83], v[82:83], s[0:1], v[146:147] op_sel:[0,0,1] op_sel_hi:[1,0,0]
	s_waitcnt lgkmcnt(1)
	v_pk_add_f32 v[146:147], v[116:117], v[148:149]
	v_pk_add_f32 v[116:117], v[116:117], v[148:149] neg_lo:[0,1] neg_hi:[0,1]
	s_mov_b32 s13, s6
	v_add3_u32 v87, v75, v78, v79
	v_or_b32_e32 v75, 0x380, v71
	v_pk_mul_f32 v[148:149], v[116:117], s[12:13]
	ds_read_b64 v[152:153], v90 offset:6144
	ds_read_b64 v[154:155], v89 offset:6400
	ds_read_b64 v[156:157], v88 offset:6656
	ds_read_b64 v[158:159], v87 offset:6912
	v_ashrrev_i32_e32 v75, 2, v75
	v_pk_fma_f32 v[116:117], v[116:117], s[14:15], v[148:149] op_sel:[0,0,1] op_sel_hi:[1,0,0]
	s_waitcnt lgkmcnt(4)
	v_pk_add_f32 v[148:149], v[118:119], v[150:151]
	v_pk_add_f32 v[118:119], v[118:119], v[150:151] neg_lo:[0,1] neg_hi:[0,1]
	s_mov_b32 s35, s20
	v_add_u32_e32 v75, 0, v75
	v_pk_mul_f32 v[150:151], v[118:119], s[34:35]
	s_mov_b32 s44, s19
	v_add3_u32 v86, v75, v78, v79
	v_or_b32_e32 v75, 0x3a0, v71
	v_or_b32_e32 v71, 0x3c0, v71
	v_pk_fma_f32 v[118:119], v[118:119], s[44:45], v[150:151] op_sel:[0,0,1] op_sel_hi:[1,0,0]
	s_waitcnt lgkmcnt(3)
	v_pk_add_f32 v[150:151], v[120:121], v[152:153]
	v_pk_add_f32 v[152:153], v[120:121], v[152:153] op_sel:[1,1] op_sel_hi:[0,0] neg_lo:[0,1] neg_hi:[1,0]
	v_ashrrev_i32_e32 v71, 2, v71
	s_waitcnt lgkmcnt(2)
	v_pk_add_f32 v[120:121], v[122:123], v[154:155]
	v_pk_add_f32 v[122:123], v[122:123], v[154:155] neg_lo:[0,1] neg_hi:[0,1]
	v_add_u32_e32 v71, 0, v71
	v_or_b32_e32 v0, 0x3e0, v0
	v_pk_mul_f32 v[154:155], v[122:123], s[34:35]
	v_ashrrev_i32_e32 v75, 2, v75
	v_add3_u32 v84, v71, v78, v79
	v_ashrrev_i32_e32 v71, 2, v0
	v_pk_fma_f32 v[122:123], v[122:123], s[18:19], v[154:155] op_sel:[0,0,1] op_sel_hi:[1,0,0]
	s_waitcnt lgkmcnt(1)
	v_pk_add_f32 v[154:155], v[124:125], v[156:157]
	v_pk_add_f32 v[124:125], v[124:125], v[156:157] neg_lo:[0,1] neg_hi:[0,1]
	v_add_u32_e32 v75, 0, v75
	v_add_u32_e32 v71, 0, v71
	v_lshlrev_b32_e32 v0, 3, v0
	v_pk_mul_f32 v[156:157], v[124:125], s[12:13]
	v_add3_u32 v85, v75, v78, v79
	v_add3_u32 v0, v71, v0, v79
	ds_read_b64 v[160:161], v86 offset:7168
	ds_read_b64 v[162:163], v85 offset:7424
	ds_read_b64 v[164:165], v84 offset:7680
	ds_read_b64 v[166:167], v0
	v_pk_fma_f32 v[124:125], v[124:125], s[4:5], v[156:157] op_sel:[0,0,1] op_sel_hi:[1,0,0]
	s_waitcnt lgkmcnt(4)
	v_pk_add_f32 v[156:157], v[126:127], v[158:159]
	v_pk_add_f32 v[126:127], v[126:127], v[158:159] neg_lo:[0,1] neg_hi:[0,1]
	v_lshlrev_b32_e32 v70, 4, v70
	v_pk_mul_f32 v[158:159], v[126:127], s[26:27]
	v_cvt_f32_u32_e32 v75, v70
	v_pk_fma_f32 v[126:127], v[126:127], s[22:23], v[158:159] op_sel:[0,0,1] op_sel_hi:[1,0,0]
	s_waitcnt lgkmcnt(3)
	v_pk_add_f32 v[158:159], v[128:129], v[160:161]
	v_pk_add_f32 v[128:129], v[128:129], v[160:161] neg_lo:[0,1] neg_hi:[0,1]
	v_and_b32_e32 v74, 0x1fffffe0, v74
	v_pk_mul_f32 v[160:161], v[128:129], s[8:9]
	v_mul_f32_e32 v115, 0x38800000, v75
	v_pk_fma_f32 v[128:129], v[128:129], s[8:9], v[160:161] op_sel:[0,0,1] op_sel_hi:[1,0,0]
	s_waitcnt lgkmcnt(2)
	v_pk_add_f32 v[160:161], v[130:131], v[162:163]
	v_pk_add_f32 v[130:131], v[130:131], v[162:163] neg_lo:[0,1] neg_hi:[0,1]
	v_lshl_add_u32 v74, v74, 3, 0
	v_pk_mul_f32 v[162:163], v[130:131], s[22:23]
	v_sin_f32_e32 v75, v115
	v_pk_fma_f32 v[130:131], v[130:131], s[26:27], v[162:163] op_sel:[0,0,1] op_sel_hi:[1,0,0]
	s_waitcnt lgkmcnt(1)
	v_pk_add_f32 v[162:163], v[132:133], v[164:165]
	v_pk_add_f32 v[132:133], v[132:133], v[164:165] neg_lo:[0,1] neg_hi:[0,1]
	v_add3_u32 v74, v74, v78, v79
	v_pk_mul_f32 v[164:165], v[132:133], s[4:5]
	v_xor_b32_e32 v78, 0x80000000, v75
	v_pk_fma_f32 v[132:133], v[132:133], s[12:13], v[164:165] op_sel:[0,0,1] op_sel_hi:[1,0,0]
	s_waitcnt lgkmcnt(0)
	v_pk_add_f32 v[164:165], v[134:135], v[166:167]
	v_pk_add_f32 v[134:135], v[134:135], v[166:167] neg_lo:[0,1] neg_hi:[0,1]
	v_mov_b32_e32 v79, v75
	v_pk_mul_f32 v[166:167], v[134:135], s[18:19]
	s_add_u32 s41, s56, s42
	v_pk_fma_f32 v[134:135], v[134:135], s[34:35], v[166:167] op_sel:[0,0,1] op_sel_hi:[1,0,0]
	v_pk_add_f32 v[166:167], v[168:169], v[150:151]
	v_pk_add_f32 v[150:151], v[168:169], v[150:151] neg_lo:[0,1] neg_hi:[0,1]
	v_pk_add_f32 v[168:169], v[136:137], v[120:121]
	v_pk_add_f32 v[120:121], v[136:137], v[120:121] neg_lo:[0,1] neg_hi:[0,1]
	s_addc_u32 s61, s57, s43
	v_pk_mul_f32 v[136:137], v[120:121], s[4:5]
	s_nop 0
	v_pk_fma_f32 v[120:121], v[120:121], s[6:7], v[136:137] op_sel:[0,0,1] op_sel_hi:[1,0,0]
	v_pk_add_f32 v[136:137], v[138:139], v[154:155]
	v_pk_add_f32 v[138:139], v[138:139], v[154:155] neg_lo:[0,1] neg_hi:[0,1]
	s_nop 0
	v_pk_mul_f32 v[154:155], v[138:139], s[8:9]
	s_nop 0
	v_pk_fma_f32 v[138:139], v[138:139], s[10:11], v[154:155] op_sel:[0,0,1] op_sel_hi:[1,0,0]
	v_pk_add_f32 v[154:155], v[140:141], v[156:157]
	v_pk_add_f32 v[140:141], v[140:141], v[156:157] neg_lo:[0,1] neg_hi:[0,1]
	s_nop 0
	v_pk_mul_f32 v[156:157], v[140:141], s[12:13]
	s_nop 0
	v_pk_fma_f32 v[140:141], v[140:141], s[14:15], v[156:157] op_sel:[0,0,1] op_sel_hi:[1,0,0]
	v_pk_add_f32 v[156:157], v[142:143], v[158:159]
	v_pk_add_f32 v[158:159], v[142:143], v[158:159] op_sel:[1,1] op_sel_hi:[0,0] neg_lo:[0,1] neg_hi:[1,0]
	s_nop 0
	v_pk_add_f32 v[142:143], v[144:145], v[160:161]
	v_pk_add_f32 v[144:145], v[144:145], v[160:161] neg_lo:[0,1] neg_hi:[0,1]
	s_nop 0
	v_pk_mul_f32 v[160:161], v[144:145], s[12:13]
	s_nop 0
	v_pk_fma_f32 v[144:145], v[144:145], s[4:5], v[160:161] op_sel:[0,0,1] op_sel_hi:[1,0,0]
	v_pk_add_f32 v[160:161], v[146:147], v[162:163]
	v_pk_add_f32 v[146:147], v[146:147], v[162:163] neg_lo:[0,1] neg_hi:[0,1]
	s_nop 0
	v_pk_mul_f32 v[162:163], v[146:147], s[8:9]
	s_nop 0
	v_pk_fma_f32 v[146:147], v[146:147], s[8:9], v[162:163] op_sel:[0,0,1] op_sel_hi:[1,0,0]
	v_pk_add_f32 v[162:163], v[148:149], v[164:165]
	v_pk_add_f32 v[148:149], v[148:149], v[164:165] neg_lo:[0,1] neg_hi:[0,1]
	s_nop 0
	v_pk_mul_f32 v[164:165], v[148:149], s[4:5]
	s_nop 0
	v_pk_fma_f32 v[148:149], v[148:149], s[12:13], v[164:165] op_sel:[0,0,1] op_sel_hi:[1,0,0]
	v_pk_add_f32 v[164:165], v[66:67], v[152:153]
	v_pk_add_f32 v[66:67], v[66:67], v[152:153] neg_lo:[0,1] neg_hi:[0,1]
	v_pk_add_f32 v[152:153], v[68:69], v[122:123]
	v_pk_add_f32 v[68:69], v[68:69], v[122:123] neg_lo:[0,1] neg_hi:[0,1]
	s_nop 0
	v_pk_mul_f32 v[122:123], v[68:69], s[4:5]
	s_nop 0
	v_pk_fma_f32 v[68:69], v[68:69], s[6:7], v[122:123] op_sel:[0,0,1] op_sel_hi:[1,0,0]
	v_pk_add_f32 v[122:123], v[72:73], v[124:125]
	v_pk_add_f32 v[72:73], v[72:73], v[124:125] neg_lo:[0,1] neg_hi:[0,1]
	s_nop 0
	v_pk_mul_f32 v[124:125], v[72:73], s[8:9]
	s_nop 0
	v_pk_fma_f32 v[72:73], v[72:73], s[10:11], v[124:125] op_sel:[0,0,1] op_sel_hi:[1,0,0]
	v_pk_add_f32 v[124:125], v[76:77], v[126:127]
	v_pk_add_f32 v[76:77], v[76:77], v[126:127] neg_lo:[0,1] neg_hi:[0,1]
	s_nop 0
	v_pk_mul_f32 v[126:127], v[76:77], s[12:13]
	s_nop 0
	v_pk_fma_f32 v[76:77], v[76:77], s[14:15], v[126:127] op_sel:[0,0,1] op_sel_hi:[1,0,0]
	v_pk_add_f32 v[126:127], v[80:81], v[128:129]
	v_pk_add_f32 v[128:129], v[80:81], v[128:129] op_sel:[1,1] op_sel_hi:[0,0] neg_lo:[0,1] neg_hi:[1,0]
	s_nop 0
	v_pk_add_f32 v[80:81], v[82:83], v[130:131]
	v_pk_add_f32 v[82:83], v[82:83], v[130:131] neg_lo:[0,1] neg_hi:[0,1]
	s_nop 0
	v_pk_mul_f32 v[130:131], v[82:83], s[12:13]
	s_nop 0
	v_pk_fma_f32 v[82:83], v[82:83], s[4:5], v[130:131] op_sel:[0,0,1] op_sel_hi:[1,0,0]
	v_pk_add_f32 v[130:131], v[116:117], v[132:133]
	v_pk_add_f32 v[116:117], v[116:117], v[132:133] neg_lo:[0,1] neg_hi:[0,1]
	s_nop 0
	v_pk_mul_f32 v[132:133], v[116:117], s[8:9]
	s_nop 0
	v_pk_fma_f32 v[116:117], v[116:117], s[8:9], v[132:133] op_sel:[0,0,1] op_sel_hi:[1,0,0]
	v_pk_add_f32 v[132:133], v[118:119], v[134:135]
	v_pk_add_f32 v[118:119], v[118:119], v[134:135] neg_lo:[0,1] neg_hi:[0,1]
	s_nop 0
	v_pk_mul_f32 v[134:135], v[118:119], s[4:5]
	s_nop 0
	v_pk_fma_f32 v[118:119], v[118:119], s[12:13], v[134:135] op_sel:[0,0,1] op_sel_hi:[1,0,0]
	v_pk_add_f32 v[134:135], v[166:167], v[156:157]
	v_pk_add_f32 v[156:157], v[166:167], v[156:157] neg_lo:[0,1] neg_hi:[0,1]
	v_pk_add_f32 v[166:167], v[168:169], v[142:143]
	v_pk_add_f32 v[142:143], v[168:169], v[142:143] neg_lo:[0,1] neg_hi:[0,1]
	s_nop 0
	v_pk_mul_f32 v[168:169], v[142:143], s[8:9]
	s_nop 0
	v_pk_fma_f32 v[142:143], v[142:143], s[10:11], v[168:169] op_sel:[0,0,1] op_sel_hi:[1,0,0]
	v_pk_add_f32 v[168:169], v[136:137], v[160:161]
	v_pk_add_f32 v[160:161], v[136:137], v[160:161] op_sel:[1,1] op_sel_hi:[0,0] neg_lo:[0,1] neg_hi:[1,0]
	s_nop 0
	v_pk_add_f32 v[136:137], v[154:155], v[162:163]
	v_pk_add_f32 v[154:155], v[154:155], v[162:163] neg_lo:[0,1] neg_hi:[0,1]
	s_nop 0
	v_pk_mul_f32 v[162:163], v[154:155], s[8:9]
	s_nop 0
	v_pk_fma_f32 v[154:155], v[154:155], s[8:9], v[162:163] op_sel:[0,0,1] op_sel_hi:[1,0,0]
	v_pk_add_f32 v[162:163], v[150:151], v[158:159]
	v_pk_add_f32 v[150:151], v[150:151], v[158:159] neg_lo:[0,1] neg_hi:[0,1]
	v_pk_add_f32 v[158:159], v[120:121], v[144:145]
	v_pk_add_f32 v[120:121], v[120:121], v[144:145] neg_lo:[0,1] neg_hi:[0,1]
	s_nop 0
	v_pk_mul_f32 v[144:145], v[120:121], s[8:9]
	s_nop 0
	v_pk_fma_f32 v[120:121], v[120:121], s[10:11], v[144:145] op_sel:[0,0,1] op_sel_hi:[1,0,0]
	v_pk_add_f32 v[144:145], v[138:139], v[146:147]
	v_pk_add_f32 v[146:147], v[138:139], v[146:147] op_sel:[1,1] op_sel_hi:[0,0] neg_lo:[0,1] neg_hi:[1,0]
	s_nop 0
	v_pk_add_f32 v[138:139], v[140:141], v[148:149]
	v_pk_add_f32 v[140:141], v[140:141], v[148:149] neg_lo:[0,1] neg_hi:[0,1]
	s_nop 0
	v_pk_mul_f32 v[148:149], v[140:141], s[8:9]
	s_nop 0
	v_pk_fma_f32 v[140:141], v[140:141], s[8:9], v[148:149] op_sel:[0,0,1] op_sel_hi:[1,0,0]
	v_pk_add_f32 v[148:149], v[164:165], v[126:127]
	v_pk_add_f32 v[126:127], v[164:165], v[126:127] neg_lo:[0,1] neg_hi:[0,1]
	v_pk_add_f32 v[164:165], v[152:153], v[80:81]
	v_pk_add_f32 v[80:81], v[152:153], v[80:81] neg_lo:[0,1] neg_hi:[0,1]
	s_nop 0
	v_pk_mul_f32 v[152:153], v[80:81], s[8:9]
	s_nop 0
	v_pk_fma_f32 v[80:81], v[80:81], s[10:11], v[152:153] op_sel:[0,0,1] op_sel_hi:[1,0,0]
	v_pk_add_f32 v[152:153], v[122:123], v[130:131]
	v_pk_add_f32 v[130:131], v[122:123], v[130:131] op_sel:[1,1] op_sel_hi:[0,0] neg_lo:[0,1] neg_hi:[1,0]
	s_nop 0
	v_pk_add_f32 v[122:123], v[124:125], v[132:133]
	v_pk_add_f32 v[124:125], v[124:125], v[132:133] neg_lo:[0,1] neg_hi:[0,1]
	s_nop 0
	v_pk_mul_f32 v[132:133], v[124:125], s[8:9]
	s_nop 0
	v_pk_fma_f32 v[124:125], v[124:125], s[8:9], v[132:133] op_sel:[0,0,1] op_sel_hi:[1,0,0]
	v_pk_add_f32 v[132:133], v[66:67], v[128:129]
	v_pk_add_f32 v[66:67], v[66:67], v[128:129] neg_lo:[0,1] neg_hi:[0,1]
	v_pk_add_f32 v[128:129], v[68:69], v[82:83]
	v_pk_add_f32 v[68:69], v[68:69], v[82:83] neg_lo:[0,1] neg_hi:[0,1]
	s_nop 0
	v_pk_mul_f32 v[82:83], v[68:69], s[8:9]
	s_nop 0
	v_pk_fma_f32 v[68:69], v[68:69], s[10:11], v[82:83] op_sel:[0,0,1] op_sel_hi:[1,0,0]
	v_pk_add_f32 v[82:83], v[72:73], v[116:117]
	v_pk_add_f32 v[116:117], v[72:73], v[116:117] op_sel:[1,1] op_sel_hi:[0,0] neg_lo:[0,1] neg_hi:[1,0]
	s_nop 0
	v_pk_add_f32 v[72:73], v[76:77], v[118:119]
	v_pk_add_f32 v[76:77], v[76:77], v[118:119] neg_lo:[0,1] neg_hi:[0,1]
	v_pk_add_f32 v[174:175], v[66:67], v[116:117]
	v_pk_mul_f32 v[118:119], v[76:77], s[8:9]
	v_pk_add_f32 v[116:117], v[66:67], v[116:117] neg_lo:[0,1] neg_hi:[0,1]
	v_pk_fma_f32 v[76:77], v[76:77], s[8:9], v[118:119] op_sel:[0,0,1] op_sel_hi:[1,0,0]
	v_pk_add_f32 v[118:119], v[134:135], v[168:169]
	v_pk_add_f32 v[134:135], v[134:135], v[168:169] neg_lo:[0,1] neg_hi:[0,1]
	v_pk_add_f32 v[168:169], v[166:167], v[136:137]
	v_pk_add_f32 v[166:167], v[166:167], v[136:137] op_sel:[1,1] op_sel_hi:[0,0] neg_lo:[0,1] neg_hi:[1,0]
	v_pk_add_f32 v[180:181], v[118:119], v[168:169]
	v_pk_add_f32 v[136:137], v[156:157], v[160:161]
	v_pk_add_f32 v[156:157], v[156:157], v[160:161] neg_lo:[0,1] neg_hi:[0,1]
	v_pk_add_f32 v[160:161], v[142:143], v[154:155]
	v_pk_add_f32 v[154:155], v[142:143], v[154:155] op_sel:[1,1] op_sel_hi:[0,0] neg_lo:[0,1] neg_hi:[1,0]
	v_pk_add_f32 v[66:67], v[68:69], v[76:77] neg_lo:[0,1] neg_hi:[0,1]
	v_pk_add_f32 v[142:143], v[162:163], v[144:145]
	v_pk_add_f32 v[144:145], v[162:163], v[144:145] neg_lo:[0,1] neg_hi:[0,1]
	v_pk_add_f32 v[162:163], v[158:159], v[138:139]
	v_pk_add_f32 v[158:159], v[158:159], v[138:139] op_sel:[1,1] op_sel_hi:[0,0] neg_lo:[0,1] neg_hi:[1,0]
	ds_write_b64 v74, v[180:181]
	v_pk_add_f32 v[138:139], v[150:151], v[146:147]
	v_pk_add_f32 v[146:147], v[150:151], v[146:147] neg_lo:[0,1] neg_hi:[0,1]
	v_pk_add_f32 v[150:151], v[120:121], v[140:141]
	v_pk_add_f32 v[140:141], v[120:121], v[140:141] op_sel:[1,1] op_sel_hi:[0,0] neg_lo:[0,1] neg_hi:[1,0]
	v_cos_f32_e32 v74, v115
	v_pk_add_f32 v[120:121], v[148:149], v[152:153]
	v_pk_add_f32 v[148:149], v[148:149], v[152:153] neg_lo:[0,1] neg_hi:[0,1]
	v_pk_add_f32 v[152:153], v[164:165], v[122:123]
	v_pk_add_f32 v[164:165], v[164:165], v[122:123] op_sel:[1,1] op_sel_hi:[0,0] neg_lo:[0,1] neg_hi:[1,0]
	v_xor_b32_e32 v179, 0x80000000, v66
	v_pk_add_f32 v[122:123], v[126:127], v[130:131]
	v_pk_add_f32 v[126:127], v[126:127], v[130:131] neg_lo:[0,1] neg_hi:[0,1]
	v_pk_add_f32 v[130:131], v[80:81], v[124:125]
	v_pk_add_f32 v[124:125], v[80:81], v[124:125] op_sel:[1,1] op_sel_hi:[0,0] neg_lo:[0,1] neg_hi:[1,0]
	v_mov_b32_e32 v178, v67
	v_pk_add_f32 v[80:81], v[132:133], v[82:83]
	v_pk_add_f32 v[132:133], v[132:133], v[82:83] neg_lo:[0,1] neg_hi:[0,1]
	v_pk_add_f32 v[176:177], v[68:69], v[76:77]
	v_pk_add_f32 v[118:119], v[118:119], v[168:169] neg_lo:[0,1] neg_hi:[0,1]
	v_pk_add_f32 v[168:169], v[134:135], v[166:167]
	v_pk_add_f32 v[82:83], v[134:135], v[166:167] neg_lo:[0,1] neg_hi:[0,1]
	v_pk_add_f32 v[134:135], v[136:137], v[160:161]
	v_pk_add_f32 v[136:137], v[136:137], v[160:161] neg_lo:[0,1] neg_hi:[0,1]
	v_pk_add_f32 v[160:161], v[156:157], v[154:155]
	v_pk_add_f32 v[68:69], v[156:157], v[154:155] neg_lo:[0,1] neg_hi:[0,1]
	v_pk_add_f32 v[154:155], v[142:143], v[162:163]
	v_pk_add_f32 v[142:143], v[142:143], v[162:163] neg_lo:[0,1] neg_hi:[0,1]
	v_pk_add_f32 v[156:157], v[144:145], v[158:159]
	v_pk_add_f32 v[76:77], v[144:145], v[158:159] neg_lo:[0,1] neg_hi:[0,1]
	v_pk_add_f32 v[144:145], v[138:139], v[150:151]
	v_pk_add_f32 v[138:139], v[138:139], v[150:151] neg_lo:[0,1] neg_hi:[0,1]
	v_pk_add_f32 v[150:151], v[146:147], v[140:141]
	v_pk_add_f32 v[66:67], v[146:147], v[140:141] neg_lo:[0,1] neg_hi:[0,1]
	v_pk_add_f32 v[140:141], v[120:121], v[152:153]
	v_pk_add_f32 v[162:163], v[116:117], v[178:179]
	v_pk_add_f32 v[70:71], v[116:117], v[178:179] neg_lo:[0,1] neg_hi:[0,1]
	v_mov_b32_e32 v116, v75
	v_pk_mul_f32 v[116:117], v[116:117], v[140:141] op_sel:[0,1] op_sel_hi:[0,0] neg_hi:[1,0]
	v_pk_fma_f32 v[116:117], v[140:141], v[74:75], v[116:117] op_sel_hi:[1,0,1]
	ds_write_b64 v114, v[116:117] offset:256
	v_pk_mul_f32 v[114:115], v[78:79], v[74:75] op_sel:[0,1] op_sel_hi:[1,0]
	v_pk_add_f32 v[172:173], v[128:129], v[72:73]
	v_pk_fma_f32 v[114:115], v[74:75], v[74:75], v[114:115] op_sel_hi:[1,0,1]
	v_pk_add_f32 v[128:129], v[128:129], v[72:73] op_sel:[1,1] op_sel_hi:[0,0] neg_lo:[0,1] neg_hi:[1,0]
	v_pk_mul_f32 v[116:117], v[154:155], v[114:115] op_sel:[1,1] op_sel_hi:[0,1] neg_hi:[0,1]
	v_pk_fma_f32 v[116:117], v[154:155], v[114:115], v[116:117] op_sel_hi:[1,0,1]
	ds_write_b64 v113, v[116:117] offset:512
	v_pk_mul_f32 v[116:117], v[78:79], v[114:115] op_sel:[0,1] op_sel_hi:[1,0]
	v_pk_add_f32 v[120:121], v[120:121], v[152:153] neg_lo:[0,1] neg_hi:[0,1]
	v_pk_fma_f32 v[114:115], v[114:115], v[74:75], v[116:117] op_sel_hi:[1,0,1]
	v_pk_add_f32 v[152:153], v[122:123], v[130:131]
	v_pk_add_f32 v[122:123], v[122:123], v[130:131] neg_lo:[0,1] neg_hi:[0,1]
	v_pk_add_f32 v[130:131], v[126:127], v[124:125]
	v_pk_add_f32 v[72:73], v[126:127], v[124:125] neg_lo:[0,1] neg_hi:[0,1]
	v_pk_add_f32 v[124:125], v[80:81], v[172:173]
	v_pk_mul_f32 v[116:117], v[124:125], v[114:115] op_sel:[1,1] op_sel_hi:[0,1] neg_hi:[0,1]
	v_pk_add_f32 v[126:127], v[80:81], v[172:173] neg_lo:[0,1] neg_hi:[0,1]
	v_pk_fma_f32 v[116:117], v[124:125], v[114:115], v[116:117] op_sel_hi:[1,0,1]
	ds_write_b64 v112, v[116:117] offset:768
	v_pk_mul_f32 v[112:113], v[78:79], v[114:115] op_sel:[0,1] op_sel_hi:[1,0]
	v_pk_add_f32 v[158:159], v[132:133], v[128:129]
	v_pk_fma_f32 v[112:113], v[114:115], v[74:75], v[112:113] op_sel_hi:[1,0,1]
	v_pk_add_f32 v[80:81], v[132:133], v[128:129] neg_lo:[0,1] neg_hi:[0,1]
	v_pk_add_f32 v[128:129], v[174:175], v[176:177]
	v_pk_mul_f32 v[114:115], v[134:135], v[112:113] op_sel:[1,1] op_sel_hi:[0,1] neg_hi:[0,1]
	v_pk_add_f32 v[146:147], v[148:149], v[164:165]
	v_pk_fma_f32 v[114:115], v[134:135], v[112:113], v[114:115] op_sel_hi:[1,0,1]
	ds_write_b64 v111, v[114:115] offset:1024
	v_pk_mul_f32 v[114:115], v[78:79], v[112:113] op_sel:[0,1] op_sel_hi:[1,0]
	v_pk_add_f32 v[132:133], v[174:175], v[176:177] neg_lo:[0,1] neg_hi:[0,1]
	v_pk_fma_f32 v[112:113], v[112:113], v[74:75], v[114:115] op_sel_hi:[1,0,1]
	v_pk_add_f32 v[148:149], v[148:149], v[164:165] neg_lo:[0,1] neg_hi:[0,1]
	s_nop 0
	v_pk_mul_f32 v[114:115], v[152:153], v[112:113] op_sel:[1,1] op_sel_hi:[0,1] neg_hi:[0,1]
	s_nop 0
	v_pk_fma_f32 v[114:115], v[152:153], v[112:113], v[114:115] op_sel_hi:[1,0,1]
	ds_write_b64 v110, v[114:115] offset:1280
	v_pk_mul_f32 v[110:111], v[78:79], v[112:113] op_sel:[0,1] op_sel_hi:[1,0]
	s_nop 0
	v_pk_fma_f32 v[110:111], v[112:113], v[74:75], v[110:111] op_sel_hi:[1,0,1]
	s_nop 0
	s_nop 0
	v_pk_mul_f32 v[112:113], v[144:145], v[110:111] op_sel:[1,1] op_sel_hi:[0,1] neg_hi:[0,1]
	s_nop 0
	v_pk_fma_f32 v[112:113], v[144:145], v[110:111], v[112:113] op_sel_hi:[1,0,1]
	ds_write_b64 v109, v[112:113] offset:1536
	v_pk_mul_f32 v[112:113], v[78:79], v[110:111] op_sel:[0,1] op_sel_hi:[1,0]
	s_nop 0
	v_pk_fma_f32 v[110:111], v[110:111], v[74:75], v[112:113] op_sel_hi:[1,0,1]
	s_nop 0
	s_nop 0
	v_pk_mul_f32 v[112:113], v[128:129], v[110:111] op_sel:[1,1] op_sel_hi:[0,1] neg_hi:[0,1]
	s_nop 0
	v_pk_fma_f32 v[112:113], v[128:129], v[110:111], v[112:113] op_sel_hi:[1,0,1]
	ds_write_b64 v108, v[112:113] offset:1792
	v_pk_mul_f32 v[108:109], v[78:79], v[110:111] op_sel:[0,1] op_sel_hi:[1,0]
	s_nop 0
	v_pk_fma_f32 v[108:109], v[110:111], v[74:75], v[108:109] op_sel_hi:[1,0,1]
	s_nop 0
	s_nop 0
	v_pk_mul_f32 v[110:111], v[168:169], v[108:109] op_sel:[1,1] op_sel_hi:[0,1] neg_hi:[0,1]
	s_nop 0
	v_pk_fma_f32 v[110:111], v[168:169], v[108:109], v[110:111] op_sel_hi:[1,0,1]
	ds_write_b64 v107, v[110:111] offset:2048
	v_pk_mul_f32 v[110:111], v[78:79], v[108:109] op_sel:[0,1] op_sel_hi:[1,0]
	s_nop 0
	v_pk_fma_f32 v[108:109], v[108:109], v[74:75], v[110:111] op_sel_hi:[1,0,1]
	s_nop 0
	s_nop 0
	v_pk_mul_f32 v[110:111], v[146:147], v[108:109] op_sel:[1,1] op_sel_hi:[0,1] neg_hi:[0,1]
	s_nop 0
	v_pk_fma_f32 v[110:111], v[146:147], v[108:109], v[110:111] op_sel_hi:[1,0,1]
	ds_write_b64 v106, v[110:111] offset:2304
	v_pk_mul_f32 v[106:107], v[78:79], v[108:109] op_sel:[0,1] op_sel_hi:[1,0]
	s_nop 0
	v_pk_fma_f32 v[106:107], v[108:109], v[74:75], v[106:107] op_sel_hi:[1,0,1]
	s_nop 0
	s_nop 0
	v_pk_mul_f32 v[108:109], v[156:157], v[106:107] op_sel:[1,1] op_sel_hi:[0,1] neg_hi:[0,1]
	s_nop 0
	v_pk_fma_f32 v[108:109], v[156:157], v[106:107], v[108:109] op_sel_hi:[1,0,1]
	ds_write_b64 v105, v[108:109] offset:2560
	v_pk_mul_f32 v[108:109], v[78:79], v[106:107] op_sel:[0,1] op_sel_hi:[1,0]
	s_nop 0
	v_pk_fma_f32 v[106:107], v[106:107], v[74:75], v[108:109] op_sel_hi:[1,0,1]
	s_nop 0
	s_nop 0
	v_pk_mul_f32 v[108:109], v[158:159], v[106:107] op_sel:[1,1] op_sel_hi:[0,1] neg_hi:[0,1]
	s_nop 0
	v_pk_fma_f32 v[108:109], v[158:159], v[106:107], v[108:109] op_sel_hi:[1,0,1]
	ds_write_b64 v103, v[108:109] offset:2816
	v_pk_mul_f32 v[108:109], v[78:79], v[106:107] op_sel:[0,1] op_sel_hi:[1,0]
	s_nop 0
	v_pk_fma_f32 v[106:107], v[106:107], v[74:75], v[108:109] op_sel_hi:[1,0,1]
	s_nop 0
	s_nop 0
	v_pk_mul_f32 v[108:109], v[160:161], v[106:107] op_sel:[1,1] op_sel_hi:[0,1] neg_hi:[0,1]
	s_nop 0
	v_pk_fma_f32 v[108:109], v[160:161], v[106:107], v[108:109] op_sel_hi:[1,0,1]
	ds_write_b64 v102, v[108:109] offset:3072
	v_pk_mul_f32 v[102:103], v[78:79], v[106:107] op_sel:[0,1] op_sel_hi:[1,0]
	s_nop 0
	v_pk_fma_f32 v[102:103], v[106:107], v[74:75], v[102:103] op_sel_hi:[1,0,1]
	s_nop 0
	s_nop 0
	v_pk_mul_f32 v[106:107], v[130:131], v[102:103] op_sel:[1,1] op_sel_hi:[0,1] neg_hi:[0,1]
	s_nop 0
	v_pk_fma_f32 v[106:107], v[130:131], v[102:103], v[106:107] op_sel_hi:[1,0,1]
	ds_write_b64 v101, v[106:107] offset:3328
	v_pk_mul_f32 v[106:107], v[78:79], v[102:103] op_sel:[0,1] op_sel_hi:[1,0]
	s_nop 0
	v_pk_fma_f32 v[102:103], v[102:103], v[74:75], v[106:107] op_sel_hi:[1,0,1]
	s_nop 0
	s_nop 0
	v_pk_mul_f32 v[106:107], v[150:151], v[102:103] op_sel:[1,1] op_sel_hi:[0,1] neg_hi:[0,1]
	v_pk_fma_f32 v[106:107], v[150:151], v[102:103], v[106:107] op_sel_hi:[1,0,1]
	ds_write_b64 v100, v[106:107] offset:3584
	v_pk_mul_f32 v[100:101], v[78:79], v[102:103] op_sel:[0,1] op_sel_hi:[1,0]
	s_nop 0
	v_pk_fma_f32 v[100:101], v[102:103], v[74:75], v[100:101] op_sel_hi:[1,0,1]
	s_nop 0
	s_nop 0
	v_pk_mul_f32 v[102:103], v[162:163], v[100:101] op_sel:[1,1] op_sel_hi:[0,1] neg_hi:[0,1]
	v_pk_fma_f32 v[102:103], v[162:163], v[100:101], v[102:103] op_sel_hi:[1,0,1]
	ds_write_b64 v99, v[102:103] offset:3840
	v_pk_mul_f32 v[102:103], v[78:79], v[100:101] op_sel:[0,1] op_sel_hi:[1,0]
	s_nop 0
	v_pk_fma_f32 v[100:101], v[100:101], v[74:75], v[102:103] op_sel_hi:[1,0,1]
	s_nop 0
	s_nop 0
	v_pk_mul_f32 v[102:103], v[118:119], v[100:101] op_sel:[1,1] op_sel_hi:[0,1] neg_hi:[0,1]
	v_pk_fma_f32 v[102:103], v[118:119], v[100:101], v[102:103] op_sel_hi:[1,0,1]
	ds_write_b64 v98, v[102:103] offset:4096
	v_pk_mul_f32 v[98:99], v[78:79], v[100:101] op_sel:[0,1] op_sel_hi:[1,0]
	s_nop 0
	v_pk_fma_f32 v[98:99], v[100:101], v[74:75], v[98:99] op_sel_hi:[1,0,1]
	s_nop 0
	s_nop 0
	v_pk_mul_f32 v[100:101], v[120:121], v[98:99] op_sel:[1,1] op_sel_hi:[0,1] neg_hi:[0,1]
	v_pk_fma_f32 v[100:101], v[120:121], v[98:99], v[100:101] op_sel_hi:[1,0,1]
	ds_write_b64 v97, v[100:101] offset:4352
	v_pk_mul_f32 v[100:101], v[78:79], v[98:99] op_sel:[0,1] op_sel_hi:[1,0]
	s_nop 0
	v_pk_fma_f32 v[98:99], v[98:99], v[74:75], v[100:101] op_sel_hi:[1,0,1]
	s_nop 0
	s_nop 0
	v_pk_mul_f32 v[100:101], v[142:143], v[98:99] op_sel:[1,1] op_sel_hi:[0,1] neg_hi:[0,1]
	v_pk_fma_f32 v[100:101], v[142:143], v[98:99], v[100:101] op_sel_hi:[1,0,1]
	ds_write_b64 v96, v[100:101] offset:4608
	v_pk_mul_f32 v[96:97], v[78:79], v[98:99] op_sel:[0,1] op_sel_hi:[1,0]
	s_nop 0
	v_pk_fma_f32 v[96:97], v[98:99], v[74:75], v[96:97] op_sel_hi:[1,0,1]
	s_nop 0
	s_nop 0
	v_pk_mul_f32 v[98:99], v[126:127], v[96:97] op_sel:[1,1] op_sel_hi:[0,1] neg_hi:[0,1]
	v_pk_fma_f32 v[98:99], v[126:127], v[96:97], v[98:99] op_sel_hi:[1,0,1]
	ds_write_b64 v95, v[98:99] offset:4864
	v_pk_mul_f32 v[98:99], v[78:79], v[96:97] op_sel:[0,1] op_sel_hi:[1,0]
	s_nop 0
	v_pk_fma_f32 v[96:97], v[96:97], v[74:75], v[98:99] op_sel_hi:[1,0,1]
	s_nop 0
	s_nop 0
	v_pk_mul_f32 v[98:99], v[136:137], v[96:97] op_sel:[1,1] op_sel_hi:[0,1] neg_hi:[0,1]
	v_pk_fma_f32 v[98:99], v[136:137], v[96:97], v[98:99] op_sel_hi:[1,0,1]
	ds_write_b64 v94, v[98:99] offset:5120
	v_pk_mul_f32 v[94:95], v[78:79], v[96:97] op_sel:[0,1] op_sel_hi:[1,0]
	s_nop 0
	v_pk_fma_f32 v[94:95], v[96:97], v[74:75], v[94:95] op_sel_hi:[1,0,1]
	s_nop 0
	s_nop 0
	v_pk_mul_f32 v[96:97], v[122:123], v[94:95] op_sel:[1,1] op_sel_hi:[0,1] neg_hi:[0,1]
	v_pk_fma_f32 v[96:97], v[122:123], v[94:95], v[96:97] op_sel_hi:[1,0,1]
	ds_write_b64 v93, v[96:97] offset:5376
	v_pk_mul_f32 v[96:97], v[78:79], v[94:95] op_sel:[0,1] op_sel_hi:[1,0]
	s_nop 0
	v_pk_fma_f32 v[94:95], v[94:95], v[74:75], v[96:97] op_sel_hi:[1,0,1]
	s_nop 0
	s_nop 0
	v_pk_mul_f32 v[96:97], v[138:139], v[94:95] op_sel:[1,1] op_sel_hi:[0,1] neg_hi:[0,1]
	v_pk_fma_f32 v[96:97], v[138:139], v[94:95], v[96:97] op_sel_hi:[1,0,1]
	ds_write_b64 v92, v[96:97] offset:5632
	v_pk_mul_f32 v[92:93], v[78:79], v[94:95] op_sel:[0,1] op_sel_hi:[1,0]
	s_nop 0
	v_pk_fma_f32 v[92:93], v[94:95], v[74:75], v[92:93] op_sel_hi:[1,0,1]
	s_nop 0
	s_nop 0
	v_pk_mul_f32 v[94:95], v[132:133], v[92:93] op_sel:[1,1] op_sel_hi:[0,1] neg_hi:[0,1]
	v_pk_fma_f32 v[94:95], v[132:133], v[92:93], v[94:95] op_sel_hi:[1,0,1]
	ds_write_b64 v91, v[94:95] offset:5888
	v_pk_mul_f32 v[94:95], v[78:79], v[92:93] op_sel:[0,1] op_sel_hi:[1,0]
	s_nop 0
	v_pk_fma_f32 v[92:93], v[92:93], v[74:75], v[94:95] op_sel_hi:[1,0,1]
	s_nop 0
	s_nop 0
	v_pk_mul_f32 v[94:95], v[82:83], v[92:93] op_sel:[1,1] op_sel_hi:[0,1] neg_hi:[0,1]
	v_pk_fma_f32 v[82:83], v[82:83], v[92:93], v[94:95] op_sel_hi:[1,0,1]
	ds_write_b64 v90, v[82:83] offset:6144
	v_pk_mul_f32 v[82:83], v[78:79], v[92:93] op_sel:[0,1] op_sel_hi:[1,0]
	s_nop 0
	v_pk_fma_f32 v[82:83], v[92:93], v[74:75], v[82:83] op_sel_hi:[1,0,1]
	s_nop 0
	s_nop 0
	v_pk_mul_f32 v[90:91], v[148:149], v[82:83] op_sel:[1,1] op_sel_hi:[0,1] neg_hi:[0,1]
	v_pk_fma_f32 v[90:91], v[148:149], v[82:83], v[90:91] op_sel_hi:[1,0,1]
	ds_write_b64 v89, v[90:91] offset:6400
	v_pk_mul_f32 v[90:91], v[78:79], v[82:83] op_sel:[0,1] op_sel_hi:[1,0]
	s_nop 0
	v_pk_fma_f32 v[82:83], v[82:83], v[74:75], v[90:91] op_sel_hi:[1,0,1]
	s_nop 0
	s_nop 0
	v_pk_mul_f32 v[90:91], v[76:77], v[82:83] op_sel:[1,1] op_sel_hi:[0,1] neg_hi:[0,1]
	v_pk_fma_f32 v[76:77], v[76:77], v[82:83], v[90:91] op_sel_hi:[1,0,1]
	ds_write_b64 v88, v[76:77] offset:6656
	v_pk_mul_f32 v[76:77], v[78:79], v[82:83] op_sel:[0,1] op_sel_hi:[1,0]
	s_nop 0
	v_pk_fma_f32 v[76:77], v[82:83], v[74:75], v[76:77] op_sel_hi:[1,0,1]
	s_nop 0
	s_nop 0
	v_pk_mul_f32 v[82:83], v[80:81], v[76:77] op_sel:[1,1] op_sel_hi:[0,1] neg_hi:[0,1]
	v_pk_fma_f32 v[80:81], v[80:81], v[76:77], v[82:83] op_sel_hi:[1,0,1]
	ds_write_b64 v87, v[80:81] offset:6912
	v_pk_mul_f32 v[80:81], v[78:79], v[76:77] op_sel:[0,1] op_sel_hi:[1,0]
	s_nop 0
	v_pk_fma_f32 v[76:77], v[76:77], v[74:75], v[80:81] op_sel_hi:[1,0,1]
	s_nop 0
	s_nop 0
	v_pk_mul_f32 v[80:81], v[68:69], v[76:77] op_sel:[1,1] op_sel_hi:[0,1] neg_hi:[0,1]
	v_pk_fma_f32 v[68:69], v[68:69], v[76:77], v[80:81] op_sel_hi:[1,0,1]
	ds_write_b64 v86, v[68:69] offset:7168
	v_pk_mul_f32 v[68:69], v[78:79], v[76:77] op_sel:[0,1] op_sel_hi:[1,0]
	s_nop 0
	v_pk_fma_f32 v[68:69], v[76:77], v[74:75], v[68:69] op_sel_hi:[1,0,1]
	s_nop 0
	s_nop 0
	v_pk_mul_f32 v[76:77], v[72:73], v[68:69] op_sel:[1,1] op_sel_hi:[0,1] neg_hi:[0,1]
	v_pk_fma_f32 v[72:73], v[72:73], v[68:69], v[76:77] op_sel_hi:[1,0,1]
	ds_write_b64 v85, v[72:73] offset:7424
	v_pk_mul_f32 v[72:73], v[78:79], v[68:69] op_sel:[0,1] op_sel_hi:[1,0]
	s_nop 0
	v_pk_fma_f32 v[68:69], v[68:69], v[74:75], v[72:73] op_sel_hi:[1,0,1]
	s_nop 0
	s_nop 0
	v_pk_mul_f32 v[72:73], v[66:67], v[68:69] op_sel:[1,1] op_sel_hi:[0,1] neg_hi:[0,1]
	v_pk_fma_f32 v[66:67], v[66:67], v[68:69], v[72:73] op_sel_hi:[1,0,1]
	ds_write_b64 v84, v[66:67] offset:7680
	v_pk_mul_f32 v[66:67], v[78:79], v[68:69] op_sel:[0,1] op_sel_hi:[1,0]
	s_nop 0
	v_pk_fma_f32 v[66:67], v[68:69], v[74:75], v[66:67] op_sel_hi:[1,0,1]
	s_nop 0
	s_nop 0
	v_pk_mul_f32 v[68:69], v[70:71], v[66:67] op_sel:[1,1] op_sel_hi:[0,1] neg_hi:[0,1]
	v_pk_fma_f32 v[66:67], v[70:71], v[66:67], v[68:69] op_sel_hi:[1,0,1]
	ds_write_b64 v0, v[66:67]
	s_waitcnt lgkmcnt(0)
	s_barrier
	ds_read2_b64 v[66:69], v104 offset1:1
	ds_read2_b64 v[70:73], v104 offset0:2 offset1:3
	ds_read2_b64 v[74:77], v104 offset0:4 offset1:5
	ds_read2_b64 v[78:81], v104 offset0:6 offset1:7
	ds_read2_b64 v[82:85], v104 offset0:8 offset1:9
	ds_read2_b64 v[86:89], v104 offset0:10 offset1:11
	ds_read2_b64 v[90:93], v104 offset0:12 offset1:13
	ds_read2_b64 v[94:97], v104 offset0:14 offset1:15
	ds_read2_b64 v[98:101], v104 offset0:16 offset1:17
	ds_read2_b64 v[106:109], v104 offset0:18 offset1:19
	ds_read2_b64 v[110:113], v104 offset0:20 offset1:21
	ds_read2_b64 v[114:117], v104 offset0:22 offset1:23
	ds_read2_b64 v[118:121], v104 offset0:24 offset1:25
	ds_read2_b64 v[122:125], v104 offset0:26 offset1:27
	ds_read2_b64 v[126:129], v104 offset0:28 offset1:29
	ds_read2_b64 v[130:133], v104 offset0:30 offset1:31
	s_waitcnt lgkmcnt(7)
	v_pk_add_f32 v[102:103], v[66:67], v[98:99]
	v_pk_add_f32 v[66:67], v[66:67], v[98:99] neg_lo:[0,1] neg_hi:[0,1]
	v_pk_add_f32 v[98:99], v[68:69], v[100:101]
	v_pk_add_f32 v[68:69], v[68:69], v[100:101] neg_lo:[0,1] neg_hi:[0,1]
	s_nop 0
	v_pk_mul_f32 v[100:101], v[68:69], s[18:19]
	s_nop 0
	v_pk_fma_f32 v[68:69], v[68:69], s[20:21], v[100:101] op_sel:[0,0,1] op_sel_hi:[1,0,0]
	s_waitcnt lgkmcnt(6)
	v_pk_add_f32 v[100:101], v[70:71], v[106:107]
	v_pk_add_f32 v[70:71], v[70:71], v[106:107] neg_lo:[0,1] neg_hi:[0,1]
	s_nop 0
	v_pk_mul_f32 v[106:107], v[70:71], s[4:5]
	s_nop 0
	v_pk_fma_f32 v[70:71], v[70:71], s[6:7], v[106:107] op_sel:[0,0,1] op_sel_hi:[1,0,0]
	v_pk_add_f32 v[106:107], v[72:73], v[108:109]
	v_pk_add_f32 v[72:73], v[72:73], v[108:109] neg_lo:[0,1] neg_hi:[0,1]
	s_nop 0
	v_pk_mul_f32 v[108:109], v[72:73], s[22:23]
	s_nop 0
	v_pk_fma_f32 v[72:73], v[72:73], s[24:25], v[108:109] op_sel:[0,0,1] op_sel_hi:[1,0,0]
	s_waitcnt lgkmcnt(5)
	v_pk_add_f32 v[108:109], v[74:75], v[110:111]
	v_pk_add_f32 v[74:75], v[74:75], v[110:111] neg_lo:[0,1] neg_hi:[0,1]
	s_nop 0
	v_pk_mul_f32 v[110:111], v[74:75], s[8:9]
	s_nop 0
	v_pk_fma_f32 v[74:75], v[74:75], s[10:11], v[110:111] op_sel:[0,0,1] op_sel_hi:[1,0,0]
	v_pk_add_f32 v[110:111], v[76:77], v[112:113]
	v_pk_add_f32 v[76:77], v[76:77], v[112:113] neg_lo:[0,1] neg_hi:[0,1]
	s_nop 0
	v_pk_mul_f32 v[112:113], v[76:77], s[26:27]
	s_nop 0
	v_pk_fma_f32 v[76:77], v[76:77], s[0:1], v[112:113] op_sel:[0,0,1] op_sel_hi:[1,0,0]
	s_waitcnt lgkmcnt(4)
	v_pk_add_f32 v[112:113], v[78:79], v[114:115]
	v_pk_add_f32 v[78:79], v[78:79], v[114:115] neg_lo:[0,1] neg_hi:[0,1]
	s_mov_b64 s[0:1], 0
	v_pk_mul_f32 v[114:115], v[78:79], s[12:13]
	s_nop 0
	v_pk_fma_f32 v[78:79], v[78:79], s[14:15], v[114:115] op_sel:[0,0,1] op_sel_hi:[1,0,0]
	v_pk_add_f32 v[114:115], v[80:81], v[116:117]
	v_pk_add_f32 v[80:81], v[80:81], v[116:117] neg_lo:[0,1] neg_hi:[0,1]
	s_nop 0
	v_pk_mul_f32 v[116:117], v[80:81], s[34:35]
	s_nop 0
	v_pk_fma_f32 v[80:81], v[80:81], s[44:45], v[116:117] op_sel:[0,0,1] op_sel_hi:[1,0,0]
	s_waitcnt lgkmcnt(3)
	v_pk_add_f32 v[116:117], v[82:83], v[118:119]
	v_pk_add_f32 v[118:119], v[82:83], v[118:119] op_sel:[1,1] op_sel_hi:[0,0] neg_lo:[0,1] neg_hi:[1,0]
	s_mov_b64 s[44:45], -1
	v_pk_add_f32 v[82:83], v[84:85], v[120:121]
	v_pk_add_f32 v[84:85], v[84:85], v[120:121] neg_lo:[0,1] neg_hi:[0,1]
	s_nop 0
	v_pk_mul_f32 v[120:121], v[84:85], s[34:35]
	s_nop 0
	v_pk_fma_f32 v[84:85], v[84:85], s[18:19], v[120:121] op_sel:[0,0,1] op_sel_hi:[1,0,0]
	s_waitcnt lgkmcnt(2)
	v_pk_add_f32 v[120:121], v[86:87], v[122:123]
	v_pk_add_f32 v[86:87], v[86:87], v[122:123] neg_lo:[0,1] neg_hi:[0,1]
	s_nop 0
	v_pk_mul_f32 v[122:123], v[86:87], s[12:13]
	s_nop 0
	v_pk_fma_f32 v[86:87], v[86:87], s[4:5], v[122:123] op_sel:[0,0,1] op_sel_hi:[1,0,0]
	v_pk_add_f32 v[122:123], v[88:89], v[124:125]
	v_pk_add_f32 v[88:89], v[88:89], v[124:125] neg_lo:[0,1] neg_hi:[0,1]
	s_nop 0
	v_pk_mul_f32 v[124:125], v[88:89], s[26:27]
	s_nop 0
	v_pk_fma_f32 v[88:89], v[88:89], s[22:23], v[124:125] op_sel:[0,0,1] op_sel_hi:[1,0,0]
	s_waitcnt lgkmcnt(1)
	v_pk_add_f32 v[124:125], v[90:91], v[126:127]
	v_pk_add_f32 v[90:91], v[90:91], v[126:127] neg_lo:[0,1] neg_hi:[0,1]
	s_nop 0
	v_pk_mul_f32 v[126:127], v[90:91], s[8:9]
	s_nop 0
	v_pk_fma_f32 v[90:91], v[90:91], s[8:9], v[126:127] op_sel:[0,0,1] op_sel_hi:[1,0,0]
	v_pk_add_f32 v[126:127], v[92:93], v[128:129]
	v_pk_add_f32 v[92:93], v[92:93], v[128:129] neg_lo:[0,1] neg_hi:[0,1]
	s_nop 0
	v_pk_mul_f32 v[128:129], v[92:93], s[22:23]
	s_nop 0
	v_pk_fma_f32 v[92:93], v[92:93], s[26:27], v[128:129] op_sel:[0,0,1] op_sel_hi:[1,0,0]
	s_waitcnt lgkmcnt(0)
	v_pk_add_f32 v[128:129], v[94:95], v[130:131]
	v_pk_add_f32 v[94:95], v[94:95], v[130:131] neg_lo:[0,1] neg_hi:[0,1]
	s_nop 0
	v_pk_mul_f32 v[130:131], v[94:95], s[4:5]
	s_nop 0
	v_pk_fma_f32 v[94:95], v[94:95], s[12:13], v[130:131] op_sel:[0,0,1] op_sel_hi:[1,0,0]
	v_pk_add_f32 v[130:131], v[96:97], v[132:133]
	v_pk_add_f32 v[96:97], v[96:97], v[132:133] neg_lo:[0,1] neg_hi:[0,1]
	s_nop 0
	v_pk_mul_f32 v[132:133], v[96:97], s[18:19]
	s_nop 0
	v_pk_fma_f32 v[96:97], v[96:97], s[34:35], v[132:133] op_sel:[0,0,1] op_sel_hi:[1,0,0]
	v_pk_add_f32 v[132:133], v[102:103], v[116:117]
	v_pk_add_f32 v[102:103], v[102:103], v[116:117] neg_lo:[0,1] neg_hi:[0,1]
	v_pk_add_f32 v[116:117], v[98:99], v[82:83]
	v_pk_add_f32 v[82:83], v[98:99], v[82:83] neg_lo:[0,1] neg_hi:[0,1]
	s_nop 0
	v_pk_mul_f32 v[98:99], v[82:83], s[4:5]
	s_nop 0
	v_pk_fma_f32 v[82:83], v[82:83], s[6:7], v[98:99] op_sel:[0,0,1] op_sel_hi:[1,0,0]
	v_pk_add_f32 v[98:99], v[100:101], v[120:121]
	v_pk_add_f32 v[100:101], v[100:101], v[120:121] neg_lo:[0,1] neg_hi:[0,1]
	s_nop 0
	v_pk_mul_f32 v[120:121], v[100:101], s[8:9]
	s_nop 0
	v_pk_fma_f32 v[100:101], v[100:101], s[10:11], v[120:121] op_sel:[0,0,1] op_sel_hi:[1,0,0]
	v_pk_add_f32 v[120:121], v[106:107], v[122:123]
	v_pk_add_f32 v[106:107], v[106:107], v[122:123] neg_lo:[0,1] neg_hi:[0,1]
	s_nop 0
	v_pk_mul_f32 v[122:123], v[106:107], s[12:13]
	s_nop 0
	v_pk_fma_f32 v[106:107], v[106:107], s[14:15], v[122:123] op_sel:[0,0,1] op_sel_hi:[1,0,0]
	v_pk_add_f32 v[122:123], v[108:109], v[124:125]
	v_pk_add_f32 v[124:125], v[108:109], v[124:125] op_sel:[1,1] op_sel_hi:[0,0] neg_lo:[0,1] neg_hi:[1,0]
	s_nop 0
	v_pk_add_f32 v[108:109], v[110:111], v[126:127]
	v_pk_add_f32 v[110:111], v[110:111], v[126:127] neg_lo:[0,1] neg_hi:[0,1]
	s_nop 0
	v_pk_mul_f32 v[126:127], v[110:111], s[12:13]
	s_nop 0
	v_pk_fma_f32 v[110:111], v[110:111], s[4:5], v[126:127] op_sel:[0,0,1] op_sel_hi:[1,0,0]
	v_pk_add_f32 v[126:127], v[112:113], v[128:129]
	v_pk_add_f32 v[112:113], v[112:113], v[128:129] neg_lo:[0,1] neg_hi:[0,1]
	s_nop 0
	v_pk_mul_f32 v[128:129], v[112:113], s[8:9]
	s_nop 0
	v_pk_fma_f32 v[112:113], v[112:113], s[8:9], v[128:129] op_sel:[0,0,1] op_sel_hi:[1,0,0]
	v_pk_add_f32 v[128:129], v[114:115], v[130:131]
	v_pk_add_f32 v[114:115], v[114:115], v[130:131] neg_lo:[0,1] neg_hi:[0,1]
	s_nop 0
	v_pk_mul_f32 v[130:131], v[114:115], s[4:5]
	s_nop 0
	v_pk_fma_f32 v[114:115], v[114:115], s[12:13], v[130:131] op_sel:[0,0,1] op_sel_hi:[1,0,0]
	v_pk_add_f32 v[130:131], v[66:67], v[118:119]
	v_pk_add_f32 v[66:67], v[66:67], v[118:119] neg_lo:[0,1] neg_hi:[0,1]
	v_pk_add_f32 v[118:119], v[68:69], v[84:85]
	v_pk_add_f32 v[68:69], v[68:69], v[84:85] neg_lo:[0,1] neg_hi:[0,1]
	s_nop 0
	v_pk_mul_f32 v[84:85], v[68:69], s[4:5]
	s_nop 0
	v_pk_fma_f32 v[68:69], v[68:69], s[6:7], v[84:85] op_sel:[0,0,1] op_sel_hi:[1,0,0]
	v_pk_add_f32 v[84:85], v[70:71], v[86:87]
	v_pk_add_f32 v[70:71], v[70:71], v[86:87] neg_lo:[0,1] neg_hi:[0,1]
	s_nop 0
	v_pk_mul_f32 v[86:87], v[70:71], s[8:9]
	s_nop 0
	v_pk_fma_f32 v[70:71], v[70:71], s[10:11], v[86:87] op_sel:[0,0,1] op_sel_hi:[1,0,0]
	v_pk_add_f32 v[86:87], v[72:73], v[88:89]
	v_pk_add_f32 v[72:73], v[72:73], v[88:89] neg_lo:[0,1] neg_hi:[0,1]
	s_nop 0
	v_pk_mul_f32 v[88:89], v[72:73], s[12:13]
	s_nop 0
	v_pk_fma_f32 v[72:73], v[72:73], s[14:15], v[88:89] op_sel:[0,0,1] op_sel_hi:[1,0,0]
	v_pk_add_f32 v[88:89], v[74:75], v[90:91]
	v_pk_add_f32 v[90:91], v[74:75], v[90:91] op_sel:[1,1] op_sel_hi:[0,0] neg_lo:[0,1] neg_hi:[1,0]
	s_nop 0
	v_pk_add_f32 v[74:75], v[76:77], v[92:93]
	v_pk_add_f32 v[76:77], v[76:77], v[92:93] neg_lo:[0,1] neg_hi:[0,1]
	s_nop 0
	v_pk_mul_f32 v[92:93], v[76:77], s[12:13]
	s_nop 0
	v_pk_fma_f32 v[76:77], v[76:77], s[4:5], v[92:93] op_sel:[0,0,1] op_sel_hi:[1,0,0]
	v_pk_add_f32 v[92:93], v[78:79], v[94:95]
	v_pk_add_f32 v[78:79], v[78:79], v[94:95] neg_lo:[0,1] neg_hi:[0,1]
	s_nop 0
	v_pk_mul_f32 v[94:95], v[78:79], s[8:9]
	s_nop 0
	v_pk_fma_f32 v[78:79], v[78:79], s[8:9], v[94:95] op_sel:[0,0,1] op_sel_hi:[1,0,0]
	v_pk_add_f32 v[94:95], v[80:81], v[96:97]
	v_pk_add_f32 v[80:81], v[80:81], v[96:97] neg_lo:[0,1] neg_hi:[0,1]
	s_nop 0
	v_pk_mul_f32 v[96:97], v[80:81], s[4:5]
	s_nop 0
	v_pk_fma_f32 v[80:81], v[80:81], s[12:13], v[96:97] op_sel:[0,0,1] op_sel_hi:[1,0,0]
	v_pk_add_f32 v[96:97], v[132:133], v[122:123]
	v_pk_add_f32 v[122:123], v[132:133], v[122:123] neg_lo:[0,1] neg_hi:[0,1]
	v_pk_add_f32 v[132:133], v[116:117], v[108:109]
	v_pk_add_f32 v[108:109], v[116:117], v[108:109] neg_lo:[0,1] neg_hi:[0,1]
	s_nop 0
	v_pk_mul_f32 v[116:117], v[108:109], s[8:9]
	s_nop 0
	v_pk_fma_f32 v[108:109], v[108:109], s[10:11], v[116:117] op_sel:[0,0,1] op_sel_hi:[1,0,0]
	v_pk_add_f32 v[116:117], v[98:99], v[126:127]
	v_pk_add_f32 v[126:127], v[98:99], v[126:127] op_sel:[1,1] op_sel_hi:[0,0] neg_lo:[0,1] neg_hi:[1,0]
	s_nop 0
	v_pk_add_f32 v[98:99], v[120:121], v[128:129]
	v_pk_add_f32 v[120:121], v[120:121], v[128:129] neg_lo:[0,1] neg_hi:[0,1]
	s_nop 0
	v_pk_mul_f32 v[128:129], v[120:121], s[8:9]
	s_nop 0
	v_pk_fma_f32 v[120:121], v[120:121], s[8:9], v[128:129] op_sel:[0,0,1] op_sel_hi:[1,0,0]
	v_pk_add_f32 v[128:129], v[102:103], v[124:125]
	v_pk_add_f32 v[102:103], v[102:103], v[124:125] neg_lo:[0,1] neg_hi:[0,1]
	v_pk_add_f32 v[124:125], v[82:83], v[110:111]
	v_pk_add_f32 v[82:83], v[82:83], v[110:111] neg_lo:[0,1] neg_hi:[0,1]
	s_nop 0
	v_pk_mul_f32 v[110:111], v[82:83], s[8:9]
	s_nop 0
	v_pk_fma_f32 v[82:83], v[82:83], s[10:11], v[110:111] op_sel:[0,0,1] op_sel_hi:[1,0,0]
	v_pk_add_f32 v[110:111], v[100:101], v[112:113]
	v_pk_add_f32 v[112:113], v[100:101], v[112:113] op_sel:[1,1] op_sel_hi:[0,0] neg_lo:[0,1] neg_hi:[1,0]
	s_nop 0
	v_pk_add_f32 v[100:101], v[106:107], v[114:115]
	v_pk_add_f32 v[106:107], v[106:107], v[114:115] neg_lo:[0,1] neg_hi:[0,1]
	s_nop 0
	v_pk_mul_f32 v[114:115], v[106:107], s[8:9]
	s_nop 0
	v_pk_fma_f32 v[106:107], v[106:107], s[8:9], v[114:115] op_sel:[0,0,1] op_sel_hi:[1,0,0]
	v_pk_add_f32 v[114:115], v[130:131], v[88:89]
	v_pk_add_f32 v[88:89], v[130:131], v[88:89] neg_lo:[0,1] neg_hi:[0,1]
	v_pk_add_f32 v[130:131], v[118:119], v[74:75]
	v_pk_add_f32 v[74:75], v[118:119], v[74:75] neg_lo:[0,1] neg_hi:[0,1]
	s_nop 0
	v_pk_mul_f32 v[118:119], v[74:75], s[8:9]
	s_nop 0
	v_pk_fma_f32 v[74:75], v[74:75], s[10:11], v[118:119] op_sel:[0,0,1] op_sel_hi:[1,0,0]
	v_pk_add_f32 v[118:119], v[84:85], v[92:93]
	v_pk_add_f32 v[92:93], v[84:85], v[92:93] op_sel:[1,1] op_sel_hi:[0,0] neg_lo:[0,1] neg_hi:[1,0]
	s_nop 0
	v_pk_add_f32 v[84:85], v[86:87], v[94:95]
	v_pk_add_f32 v[86:87], v[86:87], v[94:95] neg_lo:[0,1] neg_hi:[0,1]
	s_nop 0
	v_pk_mul_f32 v[94:95], v[86:87], s[8:9]
	s_nop 0
	v_pk_fma_f32 v[86:87], v[86:87], s[8:9], v[94:95] op_sel:[0,0,1] op_sel_hi:[1,0,0]
	v_pk_add_f32 v[94:95], v[66:67], v[90:91]
	v_pk_add_f32 v[66:67], v[66:67], v[90:91] neg_lo:[0,1] neg_hi:[0,1]
	v_pk_add_f32 v[90:91], v[68:69], v[76:77]
	v_pk_add_f32 v[68:69], v[68:69], v[76:77] neg_lo:[0,1] neg_hi:[0,1]
	s_nop 0
	v_pk_mul_f32 v[76:77], v[68:69], s[8:9]
	s_nop 0
	v_pk_fma_f32 v[68:69], v[68:69], s[10:11], v[76:77] op_sel:[0,0,1] op_sel_hi:[1,0,0]
	v_pk_add_f32 v[76:77], v[70:71], v[78:79]
	v_pk_add_f32 v[78:79], v[70:71], v[78:79] op_sel:[1,1] op_sel_hi:[0,0] neg_lo:[0,1] neg_hi:[1,0]
	s_nop 0
	v_pk_add_f32 v[70:71], v[72:73], v[80:81]
	v_pk_add_f32 v[72:73], v[72:73], v[80:81] neg_lo:[0,1] neg_hi:[0,1]
	s_nop 0
	v_pk_mul_f32 v[80:81], v[72:73], s[8:9]
	s_nop 0
	v_pk_fma_f32 v[72:73], v[72:73], s[8:9], v[80:81] op_sel:[0,0,1] op_sel_hi:[1,0,0]
	v_pk_add_f32 v[80:81], v[96:97], v[116:117]
	v_pk_add_f32 v[96:97], v[96:97], v[116:117] neg_lo:[0,1] neg_hi:[0,1]
	v_pk_add_f32 v[116:117], v[132:133], v[98:99]
	v_pk_add_f32 v[132:133], v[132:133], v[98:99] op_sel:[1,1] op_sel_hi:[0,0] neg_lo:[0,1] neg_hi:[1,0]
	s_nop 0
	v_pk_add_f32 v[98:99], v[122:123], v[126:127]
	v_pk_add_f32 v[122:123], v[122:123], v[126:127] neg_lo:[0,1] neg_hi:[0,1]
	v_pk_add_f32 v[126:127], v[108:109], v[120:121]
	v_pk_add_f32 v[120:121], v[108:109], v[120:121] op_sel:[1,1] op_sel_hi:[0,0] neg_lo:[0,1] neg_hi:[1,0]
	s_nop 0
	v_pk_add_f32 v[108:109], v[128:129], v[110:111]
	v_pk_add_f32 v[110:111], v[128:129], v[110:111] neg_lo:[0,1] neg_hi:[0,1]
	v_pk_add_f32 v[128:129], v[124:125], v[100:101]
	v_pk_add_f32 v[124:125], v[124:125], v[100:101] op_sel:[1,1] op_sel_hi:[0,0] neg_lo:[0,1] neg_hi:[1,0]
	s_nop 0
	v_pk_add_f32 v[100:101], v[102:103], v[112:113]
	v_pk_add_f32 v[102:103], v[102:103], v[112:113] neg_lo:[0,1] neg_hi:[0,1]
	v_pk_add_f32 v[112:113], v[82:83], v[106:107]
	v_pk_add_f32 v[106:107], v[82:83], v[106:107] op_sel:[1,1] op_sel_hi:[0,0] neg_lo:[0,1] neg_hi:[1,0]
	s_nop 0
	v_pk_add_f32 v[82:83], v[114:115], v[118:119]
	v_pk_add_f32 v[114:115], v[114:115], v[118:119] neg_lo:[0,1] neg_hi:[0,1]
	v_pk_add_f32 v[118:119], v[130:131], v[84:85]
	v_pk_add_f32 v[130:131], v[130:131], v[84:85] op_sel:[1,1] op_sel_hi:[0,0] neg_lo:[0,1] neg_hi:[1,0]
	s_nop 0
	v_pk_add_f32 v[84:85], v[88:89], v[92:93]
	v_pk_add_f32 v[88:89], v[88:89], v[92:93] neg_lo:[0,1] neg_hi:[0,1]
	v_pk_add_f32 v[92:93], v[74:75], v[86:87]
	v_pk_add_f32 v[86:87], v[74:75], v[86:87] op_sel:[1,1] op_sel_hi:[0,0] neg_lo:[0,1] neg_hi:[1,0]
	s_nop 0
	v_pk_add_f32 v[74:75], v[94:95], v[76:77]
	v_pk_add_f32 v[76:77], v[94:95], v[76:77] neg_lo:[0,1] neg_hi:[0,1]
	v_pk_add_f32 v[94:95], v[90:91], v[70:71]
	v_pk_add_f32 v[90:91], v[90:91], v[70:71] op_sel:[1,1] op_sel_hi:[0,0] neg_lo:[0,1] neg_hi:[1,0]
	s_nop 0
	v_pk_add_f32 v[70:71], v[66:67], v[78:79]
	v_pk_add_f32 v[66:67], v[66:67], v[78:79] neg_lo:[0,1] neg_hi:[0,1]
	v_pk_add_f32 v[78:79], v[68:69], v[72:73]
	v_pk_add_f32 v[72:73], v[68:69], v[72:73] op_sel:[1,1] op_sel_hi:[0,0] neg_lo:[0,1] neg_hi:[1,0]
	s_nop 0
	v_pk_add_f32 v[68:69], v[80:81], v[116:117]
	v_pk_add_f32 v[80:81], v[80:81], v[116:117] neg_lo:[0,1] neg_hi:[0,1]
	v_pk_add_f32 v[116:117], v[96:97], v[132:133]
	v_pk_add_f32 v[96:97], v[96:97], v[132:133] neg_lo:[0,1] neg_hi:[0,1]
	v_pk_add_f32 v[132:133], v[98:99], v[126:127]
	v_pk_add_f32 v[98:99], v[98:99], v[126:127] neg_lo:[0,1] neg_hi:[0,1]
	v_pk_add_f32 v[126:127], v[122:123], v[120:121]
	v_pk_add_f32 v[120:121], v[122:123], v[120:121] neg_lo:[0,1] neg_hi:[0,1]
	v_pk_add_f32 v[122:123], v[108:109], v[128:129]
	v_pk_add_f32 v[108:109], v[108:109], v[128:129] neg_lo:[0,1] neg_hi:[0,1]
	v_pk_add_f32 v[128:129], v[110:111], v[124:125]
	v_pk_add_f32 v[110:111], v[110:111], v[124:125] neg_lo:[0,1] neg_hi:[0,1]
	v_pk_add_f32 v[124:125], v[100:101], v[112:113]
	v_pk_add_f32 v[100:101], v[100:101], v[112:113] neg_lo:[0,1] neg_hi:[0,1]
	v_pk_add_f32 v[112:113], v[102:103], v[106:107]
	v_pk_add_f32 v[102:103], v[102:103], v[106:107] neg_lo:[0,1] neg_hi:[0,1]
	v_pk_add_f32 v[106:107], v[82:83], v[118:119]
	v_pk_mul_f32 v[68:69], v[68:69], s[2:3] op_sel_hi:[1,0]
	global_store_dwordx2 v[2:3], v[68:69], off
	v_pk_mul_f32 v[68:69], v[106:107], s[2:3] op_sel_hi:[1,0]
	v_pk_add_f32 v[82:83], v[82:83], v[118:119] neg_lo:[0,1] neg_hi:[0,1]
	v_pk_add_f32 v[118:119], v[114:115], v[130:131]
	v_pk_add_f32 v[114:115], v[114:115], v[130:131] neg_lo:[0,1] neg_hi:[0,1]
	v_pk_add_f32 v[130:131], v[84:85], v[92:93]
	v_pk_add_f32 v[84:85], v[84:85], v[92:93] neg_lo:[0,1] neg_hi:[0,1]
	v_pk_add_f32 v[92:93], v[88:89], v[86:87]
	v_pk_add_f32 v[86:87], v[88:89], v[86:87] neg_lo:[0,1] neg_hi:[0,1]
	v_pk_add_f32 v[88:89], v[74:75], v[94:95]
	global_store_dwordx2 v[4:5], v[68:69], off
	v_pk_mul_f32 v[68:69], v[122:123], s[2:3] op_sel_hi:[1,0]
	global_store_dwordx2 v[6:7], v[68:69], off
	v_pk_mul_f32 v[68:69], v[88:89], s[2:3] op_sel_hi:[1,0]
	global_store_dwordx2 v[8:9], v[68:69], off
	v_pk_mul_f32 v[68:69], v[132:133], s[2:3] op_sel_hi:[1,0]
	global_store_dwordx2 v[10:11], v[68:69], off
	v_pk_mul_f32 v[68:69], v[130:131], s[2:3] op_sel_hi:[1,0]
	v_pk_add_f32 v[74:75], v[74:75], v[94:95] neg_lo:[0,1] neg_hi:[0,1]
	v_pk_add_f32 v[94:95], v[76:77], v[90:91]
	v_pk_add_f32 v[76:77], v[76:77], v[90:91] neg_lo:[0,1] neg_hi:[0,1]
	v_pk_add_f32 v[90:91], v[70:71], v[78:79]
	global_store_dwordx2 v[12:13], v[68:69], off
	v_pk_mul_f32 v[68:69], v[124:125], s[2:3] op_sel_hi:[1,0]
	global_store_dwordx2 v[14:15], v[68:69], off
	v_pk_mul_f32 v[68:69], v[90:91], s[2:3] op_sel_hi:[1,0]
	global_store_dwordx2 v[16:17], v[68:69], off
	v_pk_mul_f32 v[68:69], v[116:117], s[2:3] op_sel_hi:[1,0]
	global_store_dwordx2 v[18:19], v[68:69], off
	v_pk_mul_f32 v[68:69], v[118:119], s[2:3] op_sel_hi:[1,0]
	global_store_dwordx2 v[20:21], v[68:69], off
	v_pk_mul_f32 v[68:69], v[128:129], s[2:3] op_sel_hi:[1,0]
	global_store_dwordx2 v[22:23], v[68:69], off
	v_pk_mul_f32 v[68:69], v[94:95], s[2:3] op_sel_hi:[1,0]
	global_store_dwordx2 v[24:25], v[68:69], off
	v_pk_mul_f32 v[68:69], v[126:127], s[2:3] op_sel_hi:[1,0]
	global_store_dwordx2 v[26:27], v[68:69], off
	v_pk_mul_f32 v[68:69], v[92:93], s[2:3] op_sel_hi:[1,0]
	v_pk_add_f32 v[70:71], v[70:71], v[78:79] neg_lo:[0,1] neg_hi:[0,1]
	v_pk_add_f32 v[78:79], v[66:67], v[72:73]
	global_store_dwordx2 v[28:29], v[68:69], off
	v_pk_mul_f32 v[68:69], v[112:113], s[2:3] op_sel_hi:[1,0]
	global_store_dwordx2 v[30:31], v[68:69], off
	v_pk_mul_f32 v[68:69], v[78:79], s[2:3] op_sel_hi:[1,0]
	global_store_dwordx2 v[32:33], v[68:69], off
	v_pk_mul_f32 v[68:69], v[80:81], s[2:3] op_sel_hi:[1,0]
	global_store_dwordx2 v[34:35], v[68:69], off
	v_pk_mul_f32 v[68:69], v[82:83], s[2:3] op_sel_hi:[1,0]
	global_store_dwordx2 v[36:37], v[68:69], off
	v_pk_mul_f32 v[68:69], v[108:109], s[2:3] op_sel_hi:[1,0]
	global_store_dwordx2 v[38:39], v[68:69], off
	v_pk_mul_f32 v[68:69], v[74:75], s[2:3] op_sel_hi:[1,0]
	global_store_dwordx2 v[40:41], v[68:69], off
	v_pk_mul_f32 v[68:69], v[98:99], s[2:3] op_sel_hi:[1,0]
	global_store_dwordx2 v[42:43], v[68:69], off
	v_pk_mul_f32 v[68:69], v[84:85], s[2:3] op_sel_hi:[1,0]
	global_store_dwordx2 v[44:45], v[68:69], off
	v_pk_mul_f32 v[68:69], v[100:101], s[2:3] op_sel_hi:[1,0]
	global_store_dwordx2 v[46:47], v[68:69], off
	v_pk_mul_f32 v[68:69], v[70:71], s[2:3] op_sel_hi:[1,0]
	global_store_dwordx2 v[48:49], v[68:69], off
	v_pk_mul_f32 v[68:69], v[96:97], s[2:3] op_sel_hi:[1,0]
	global_store_dwordx2 v[50:51], v[68:69], off
	v_pk_mul_f32 v[68:69], v[114:115], s[2:3] op_sel_hi:[1,0]
	global_store_dwordx2 v[52:53], v[68:69], off
	v_pk_mul_f32 v[68:69], v[110:111], s[2:3] op_sel_hi:[1,0]
	global_store_dwordx2 v[54:55], v[68:69], off
	v_pk_mul_f32 v[68:69], v[76:77], s[2:3] op_sel_hi:[1,0]
	global_store_dwordx2 v[56:57], v[68:69], off
	v_pk_mul_f32 v[68:69], v[120:121], s[2:3] op_sel_hi:[1,0]
	v_pk_add_f32 v[66:67], v[66:67], v[72:73] neg_lo:[0,1] neg_hi:[0,1]
	global_store_dwordx2 v[58:59], v[68:69], off
	v_pk_mul_f32 v[68:69], v[86:87], s[2:3] op_sel_hi:[1,0]
	global_store_dwordx2 v[60:61], v[68:69], off
	v_pk_mul_f32 v[68:69], v[102:103], s[2:3] op_sel_hi:[1,0]
	v_pk_mul_f32 v[66:67], v[66:67], s[2:3] op_sel_hi:[1,0]
	global_store_dwordx2 v[62:63], v[68:69], off
	global_store_dwordx2 v[64:65], v[66:67], off
	s_barrier

.Lmy_fft_hj:
	v_mov_b32 v66, 0
	s_movk_i32 s5, 0x200
	v_add_u32_e32 v0, v66, v0
	v_cvt_f32_i32_e32 v68, v0
	v_ashrrev_i32_e32 v66, 5, v0
	v_lshlrev_b32_e32 v67, 3, v0
	v_add_u32_e32 v69, 0x400, v0
	v_add_u32_e32 v70, 0x800, v0
	v_add_u32_e32 v71, 0xc00, v0
	v_add_u32_e32 v72, 0x1000, v0
	v_add_u32_e32 v73, 0x1400, v0
	v_add_u32_e32 v74, 0x1800, v0
	v_add_u32_e32 v75, 0x1c00, v0
	v_add_u32_e32 v76, 0x2000, v0
	v_add_u32_e32 v77, 0x2400, v0
	v_add_u32_e32 v78, 0x2800, v0
	v_add_u32_e32 v79, 0x2c00, v0
	v_add_u32_e32 v80, 0x3000, v0
	v_add_u32_e32 v81, 0x3400, v0
	v_add_u32_e32 v82, 0x3800, v0
	v_add_u32_e32 v0, 0x3c00, v0
	v_lshlrev_b32_e32 v66, 3, v66
	v_ashrrev_i32_e32 v69, 5, v69
	v_ashrrev_i32_e32 v70, 5, v70
	v_ashrrev_i32_e32 v71, 5, v71
	v_ashrrev_i32_e32 v72, 5, v72
	v_ashrrev_i32_e32 v73, 5, v73
	v_ashrrev_i32_e32 v74, 5, v74
	v_ashrrev_i32_e32 v75, 5, v75
	v_ashrrev_i32_e32 v83, 5, v76
	v_ashrrev_i32_e32 v84, 5, v77
	v_ashrrev_i32_e32 v85, 5, v78
	v_ashrrev_i32_e32 v86, 5, v79
	v_ashrrev_i32_e32 v87, 5, v80
	v_ashrrev_i32_e32 v88, 5, v81
	v_ashrrev_i32_e32 v89, 5, v82
	v_ashrrev_i32_e32 v90, 5, v0
	v_lshlrev_b32_e32 v0, 3, v0
	v_add3_u32 v171, 0, v66, v67
	v_lshlrev_b32_e32 v66, 3, v69
	v_lshlrev_b32_e32 v69, 3, v70
	v_lshlrev_b32_e32 v70, 3, v71
	v_lshlrev_b32_e32 v71, 3, v72
	v_lshlrev_b32_e32 v72, 3, v73
	v_lshlrev_b32_e32 v73, 3, v74
	v_lshlrev_b32_e32 v74, 3, v75
	v_lshlrev_b32_e32 v75, 3, v83
	v_lshlrev_b32_e32 v83, 3, v84
	v_lshlrev_b32_e32 v84, 3, v85
	v_lshlrev_b32_e32 v85, 3, v86
	v_lshlrev_b32_e32 v86, 3, v87
	v_lshlrev_b32_e32 v87, 3, v88
	v_lshlrev_b32_e32 v88, 3, v89
	v_lshlrev_b32_e32 v89, 3, v90
	v_add3_u32 v186, 0, v89, v0
	v_mul_f32_e32 v0, 0x38800000, v68
	v_add3_u32 v172, 0, v66, v67
	v_add3_u32 v173, 0, v69, v67
	v_add3_u32 v174, 0, v70, v67
	v_add3_u32 v175, 0, v71, v67
	v_add3_u32 v176, 0, v72, v67
	v_add3_u32 v177, 0, v73, v67
	v_add3_u32 v178, 0, v74, v67
	v_sin_f32_e32 v67, v0
	v_cos_f32_e32 v66, v0
	v_lshlrev_b32_e32 v76, 3, v76
	v_add3_u32 v179, 0, v75, v76
	v_xor_b32_e32 v68, 0x80000000, v67
	v_mov_b32_e32 v69, v67
	v_pk_mul_f32 v[70:71], v[68:69], v[66:67] op_sel:[0,1] op_sel_hi:[1,0]
	v_lshlrev_b32_e32 v78, 3, v78
	v_pk_fma_f32 v[70:71], v[66:67], v[66:67], v[70:71] op_sel_hi:[1,0,1]
	v_lshlrev_b32_e32 v79, 3, v79
	v_pk_mul_f32 v[74:75], v[68:69], v[70:71] op_sel:[0,1] op_sel_hi:[1,0]
	v_add3_u32 v181, 0, v84, v78
	v_pk_fma_f32 v[74:75], v[70:71], v[66:67], v[74:75] op_sel_hi:[1,0,1]
	v_add3_u32 v182, 0, v85, v79
	v_pk_mul_f32 v[78:79], v[68:69], v[74:75] op_sel:[0,1] op_sel_hi:[1,0]
	v_lshlrev_b32_e32 v77, 3, v77
	v_lshlrev_b32_e32 v82, 3, v82
	v_pk_fma_f32 v[78:79], v[74:75], v[66:67], v[78:79] op_sel_hi:[1,0,1]
	v_add3_u32 v180, 0, v83, v77
	v_add3_u32 v185, 0, v88, v82
	v_pk_mul_f32 v[82:83], v[68:69], v[78:79] op_sel:[0,1] op_sel_hi:[1,0]
	v_lshlrev_b32_e32 v80, 3, v80
	v_lshlrev_b32_e32 v81, 3, v81
	v_pk_fma_f32 v[82:83], v[78:79], v[66:67], v[82:83] op_sel_hi:[1,0,1]
	v_add3_u32 v183, 0, v86, v80
	v_add3_u32 v184, 0, v87, v81
	v_pk_mul_f32 v[86:87], v[68:69], v[82:83] op_sel:[0,1] op_sel_hi:[1,0]
	s_waitcnt vmcnt(31)
	v_lshlrev_b32_e32 v126, 16, v105
	v_pk_fma_f32 v[86:87], v[82:83], v[66:67], v[86:87] op_sel_hi:[1,0,1]
	s_waitcnt vmcnt(30)
	v_lshlrev_b32_e32 v127, 16, v127
	v_pk_mul_f32 v[90:91], v[68:69], v[86:87] op_sel:[0,1] op_sel_hi:[1,0]
	s_waitcnt vmcnt(29)
	v_lshlrev_b32_e32 v129, 16, v128
	v_pk_fma_f32 v[90:91], v[86:87], v[66:67], v[90:91] op_sel_hi:[1,0,1]
	s_waitcnt vmcnt(24)
	v_lshlrev_b32_e32 v128, 16, v134
	v_pk_mul_f32 v[94:95], v[68:69], v[90:91] op_sel:[0,1] op_sel_hi:[1,0]
	v_lshlrev_b32_e32 v130, 16, v130
	v_pk_fma_f32 v[94:95], v[90:91], v[66:67], v[94:95] op_sel_hi:[1,0,1]
	v_lshlrev_b32_e32 v131, 16, v131
	v_pk_mul_f32 v[98:99], v[68:69], v[94:95] op_sel:[0,1] op_sel_hi:[1,0]
	v_lshlrev_b32_e32 v132, 16, v132
	v_pk_fma_f32 v[98:99], v[94:95], v[66:67], v[98:99] op_sel_hi:[1,0,1]
	v_lshlrev_b32_e32 v133, 16, v133
	v_pk_mul_f32 v[102:103], v[68:69], v[98:99] op_sel:[0,1] op_sel_hi:[1,0]
	s_waitcnt vmcnt(22)
	v_lshlrev_b32_e32 v135, 16, v135
	v_pk_fma_f32 v[102:103], v[98:99], v[66:67], v[102:103] op_sel_hi:[1,0,1]
	v_lshlrev_b32_e32 v134, 16, v136
	v_pk_mul_f32 v[108:109], v[68:69], v[102:103] op_sel:[0,1] op_sel_hi:[1,0]
	s_waitcnt vmcnt(21)
	v_lshlrev_b32_e32 v136, 16, v137
	v_pk_fma_f32 v[108:109], v[102:103], v[66:67], v[108:109] op_sel_hi:[1,0,1]
	s_waitcnt vmcnt(20)
	v_lshlrev_b32_e32 v137, 16, v138
	v_pk_mul_f32 v[112:113], v[68:69], v[108:109] op_sel:[0,1] op_sel_hi:[1,0]
	s_waitcnt vmcnt(19)
	v_lshlrev_b32_e32 v138, 16, v139
	s_waitcnt vmcnt(18)
	v_lshlrev_b32_e32 v139, 16, v140
	s_waitcnt vmcnt(17)
	v_lshlrev_b32_e32 v140, 16, v141
	s_waitcnt vmcnt(16)
	v_lshlrev_b32_e32 v141, 16, v142
	v_pk_fma_f32 v[112:113], v[108:109], v[66:67], v[112:113] op_sel_hi:[1,0,1]
	v_pk_add_f32 v[142:143], v[126:127], 0 op_sel_hi:[1,0]
	v_pk_add_f32 v[144:145], v[128:129], 0 op_sel_hi:[1,0]
	v_pk_mul_f32 v[146:147], v[128:129], s[36:37]
	v_pk_add_f32 v[148:149], v[130:131], 0 op_sel_hi:[1,0]
	v_pk_mul_f32 v[150:151], v[130:131], s[16:17]
	v_pk_add_f32 v[152:153], v[132:133], 0 op_sel_hi:[1,0]
	v_pk_mul_f32 v[154:155], v[132:133], s[38:39]
	v_pk_add_f32 v[156:157], v[134:135], 0 op_sel_hi:[1,0]
	v_xor_b32_e32 v159, 0x80000000, v134
	v_mov_b32_e32 v158, v135
	v_pk_add_f32 v[134:135], v[136:137], 0 op_sel_hi:[1,0]
	v_pk_mul_f32 v[160:161], v[136:137], s[38:39]
	v_pk_add_f32 v[162:163], v[138:139], 0 op_sel_hi:[1,0]
	v_pk_mul_f32 v[164:165], v[138:139], s[16:17]
	v_pk_add_f32 v[166:167], v[140:141], 0 op_sel_hi:[1,0]
	v_pk_mul_f32 v[168:169], v[140:141], s[36:37]
	v_pk_mul_f32 v[116:117], v[68:69], v[112:113] op_sel:[0,1] op_sel_hi:[1,0]
	v_pk_fma_f32 v[128:129], v[128:129], s[6:7], v[146:147] op_sel:[0,0,1] op_sel_hi:[1,0,0]
	v_pk_fma_f32 v[130:131], v[130:131], s[10:11], v[150:151] op_sel:[0,0,1] op_sel_hi:[1,0,0]
	v_pk_fma_f32 v[132:133], v[132:133], s[14:15], v[154:155] op_sel:[0,0,1] op_sel_hi:[1,0,0]
	v_pk_fma_f32 v[136:137], v[136:137], s[4:5], v[160:161] op_sel:[0,0,1] op_sel_hi:[1,0,0]
	v_pk_fma_f32 v[138:139], v[138:139], s[8:9], v[164:165] op_sel:[0,0,1] op_sel_hi:[1,0,0]
	v_pk_fma_f32 v[140:141], v[140:141], s[12:13], v[168:169] op_sel:[0,0,1] op_sel_hi:[1,0,0]
	v_pk_add_f32 v[146:147], v[142:143], v[156:157]
	v_pk_add_f32 v[150:151], v[144:145], v[134:135]
	v_pk_add_f32 v[134:135], v[144:145], v[134:135] neg_lo:[0,1] neg_hi:[0,1]
	v_pk_add_f32 v[144:145], v[148:149], v[162:163]
	v_pk_add_f32 v[160:161], v[148:149], v[162:163] op_sel:[1,1] op_sel_hi:[0,0] neg_lo:[0,1] neg_hi:[1,0]
	v_pk_add_f32 v[154:155], v[152:153], v[166:167]
	v_pk_add_f32 v[152:153], v[152:153], v[166:167] neg_lo:[0,1] neg_hi:[0,1]
	v_pk_fma_f32 v[116:117], v[112:113], v[66:67], v[116:117] op_sel_hi:[1,0,1]
	v_pk_add_f32 v[142:143], v[142:143], v[156:157] neg_lo:[0,1] neg_hi:[0,1]
	v_pk_add_f32 v[156:157], v[158:159], v[126:127]
	v_pk_add_f32 v[126:127], v[126:127], v[158:159] neg_lo:[0,1] neg_hi:[0,1]
	v_pk_mul_f32 v[158:159], v[134:135], s[16:17]
	v_pk_mul_f32 v[148:149], v[152:153], s[16:17]
	v_pk_add_f32 v[162:163], v[128:129], v[136:137]
	v_pk_add_f32 v[128:129], v[128:129], v[136:137] neg_lo:[0,1] neg_hi:[0,1]
	v_pk_add_f32 v[136:137], v[130:131], v[138:139]
	v_pk_add_f32 v[130:131], v[130:131], v[138:139] neg_lo:[0,1] neg_hi:[0,1]
	v_pk_add_f32 v[138:139], v[132:133], v[140:141]
	v_pk_add_f32 v[132:133], v[132:133], v[140:141] neg_lo:[0,1] neg_hi:[0,1]
	v_pk_add_f32 v[140:141], v[146:147], v[144:145]
	v_pk_add_f32 v[144:145], v[146:147], v[144:145] neg_lo:[0,1] neg_hi:[0,1]
	v_pk_add_f32 v[146:147], v[150:151], v[154:155]
	v_pk_add_f32 v[150:151], v[150:151], v[154:155] neg_lo:[0,1] neg_hi:[0,1]
	v_pk_add_f32 v[96:97], v[94:95], 0 neg_lo:[1,1] neg_hi:[1,1]
	v_pk_mul_f32 v[120:121], v[68:69], v[116:117] op_sel:[0,1] op_sel_hi:[1,0]
	v_pk_fma_f32 v[134:135], v[134:135], s[10:11], v[158:159] op_sel:[0,0,1] op_sel_hi:[1,0,0]
	v_pk_fma_f32 v[148:149], v[152:153], s[8:9], v[148:149] op_sel:[0,0,1] op_sel_hi:[1,0,0]
	v_pk_mul_f32 v[152:153], v[128:129], s[16:17]
	v_xor_b32_e32 v155, 0x80000000, v130
	v_mov_b32_e32 v154, v131
	v_pk_mul_f32 v[130:131], v[132:133], s[16:17]
	v_xor_b32_e32 v159, 0x80000000, v150
	v_mov_b32_e32 v158, v151
	v_pk_add_f32 v[150:151], v[142:143], v[160:161]
	v_pk_add_f32 v[142:143], v[142:143], v[160:161] neg_lo:[0,1] neg_hi:[0,1]
	v_pk_add_f32 v[160:161], v[156:157], v[136:137]
	v_pk_add_f32 v[136:137], v[156:157], v[136:137] neg_lo:[0,1] neg_hi:[0,1]
	v_pk_add_f32 v[156:157], v[162:163], v[138:139]
	v_pk_add_f32 v[138:139], v[162:163], v[138:139] neg_lo:[0,1] neg_hi:[0,1]
	v_mov_b32_e32 v0, v67
	v_pk_add_f32 v[72:73], v[70:71], 0 neg_lo:[1,1] neg_hi:[1,1]
	v_pk_add_f32 v[80:81], v[78:79], 0 neg_lo:[1,1] neg_hi:[1,1]
	v_mov_b32_e32 v96, v95
	v_pk_add_f32 v[100:101], v[98:99], 0 neg_lo:[1,1] neg_hi:[1,1]
	v_pk_add_f32 v[114:115], v[112:113], 0 neg_lo:[1,1] neg_hi:[1,1]
	v_pk_fma_f32 v[120:121], v[116:117], v[66:67], v[120:121] op_sel_hi:[1,0,1]
	v_pk_add_f32 v[162:163], v[140:141], v[146:147]
	v_pk_add_f32 v[140:141], v[140:141], v[146:147] neg_lo:[0,1] neg_hi:[0,1]
	v_pk_fma_f32 v[128:129], v[128:129], s[10:11], v[152:153] op_sel:[0,0,1] op_sel_hi:[1,0,0]
	v_pk_fma_f32 v[130:131], v[132:133], s[8:9], v[130:131] op_sel:[0,0,1] op_sel_hi:[1,0,0]
	v_pk_add_f32 v[132:133], v[134:135], v[148:149]
	v_pk_add_f32 v[134:135], v[134:135], v[148:149] neg_lo:[0,1] neg_hi:[0,1]
	v_xor_b32_e32 v147, 0x80000000, v138
	v_mov_b32_e32 v146, v139
	v_pk_add_f32 v[152:153], v[160:161], v[156:157]
	v_mov_b32_e32 v72, v71
	v_pk_add_f32 v[76:77], v[74:75], 0 neg_lo:[1,1] neg_hi:[1,1]
	v_mov_b32_e32 v80, v79
	v_pk_add_f32 v[84:85], v[82:83], 0 neg_lo:[1,1] neg_hi:[1,1]
	v_mov_b32_e32 v100, v99
	v_pk_add_f32 v[106:107], v[102:103], 0 neg_lo:[1,1] neg_hi:[1,1]
	v_mov_b32_e32 v114, v113
	v_pk_mul_f32 v[68:69], v[68:69], v[120:121] op_sel:[0,1] op_sel_hi:[1,0]
	v_pk_add_f32 v[138:139], v[126:127], v[154:155]
	v_pk_add_f32 v[126:127], v[126:127], v[154:155] neg_lo:[0,1] neg_hi:[0,1]
	v_pk_add_f32 v[148:149], v[144:145], v[158:159]
	v_pk_add_f32 v[144:145], v[144:145], v[158:159] neg_lo:[0,1] neg_hi:[0,1]
	v_pk_add_f32 v[154:155], v[160:161], v[156:157] neg_lo:[0,1] neg_hi:[0,1]
	v_pk_mul_f32 v[96:97], v[140:141], v[96:97] op_sel:[1,0] op_sel_hi:[0,1]
	v_xor_b32_e32 v157, 0x80000000, v134
	v_mov_b32_e32 v156, v135
	v_pk_add_f32 v[134:135], v[128:129], v[130:131]
	v_pk_add_f32 v[128:129], v[128:129], v[130:131] neg_lo:[0,1] neg_hi:[0,1]
	v_pk_add_f32 v[130:131], v[150:151], v[132:133]
	v_pk_add_f32 v[132:133], v[150:151], v[132:133] neg_lo:[0,1] neg_hi:[0,1]
	v_pk_add_f32 v[150:151], v[136:137], v[146:147]
	v_pk_add_f32 v[136:137], v[136:137], v[146:147] neg_lo:[0,1] neg_hi:[0,1]
	v_pk_mul_f32 v[146:147], v[0:1], v[152:153] op_sel:[0,1] op_sel_hi:[0,0] neg_hi:[1,0]
	v_mov_b32_e32 v76, v75
	v_mov_b32_e32 v84, v83
	v_pk_add_f32 v[88:89], v[86:87], 0 neg_lo:[1,1] neg_hi:[1,1]
	v_pk_add_f32 v[92:93], v[90:91], 0 neg_lo:[1,1] neg_hi:[1,1]
	v_mov_b32_e32 v106, v103
	v_pk_fma_f32 v[68:69], v[120:121], v[66:67], v[68:69] op_sel_hi:[1,0,1]
	v_pk_mul_f32 v[80:81], v[148:149], v[80:81] op_sel:[1,0] op_sel_hi:[0,1]
	v_pk_fma_f32 v[94:95], v[140:141], v[94:95], v[96:97] op_sel_hi:[1,0,1]
	v_pk_mul_f32 v[96:97], v[154:155], v[100:101] op_sel:[1,0] op_sel_hi:[0,1]
	v_pk_mul_f32 v[100:101], v[144:145], v[114:115] op_sel:[1,0] op_sel_hi:[0,1]
	v_xor_b32_e32 v115, 0x80000000, v128
	v_mov_b32_e32 v114, v129
	v_pk_add_f32 v[128:129], v[142:143], v[156:157]
	v_pk_add_f32 v[140:141], v[142:143], v[156:157] neg_lo:[0,1] neg_hi:[0,1]
	v_pk_add_f32 v[142:143], v[138:139], v[134:135]
	v_pk_fma_f32 v[66:67], v[152:153], v[66:67], v[146:147] op_sel_hi:[1,0,1]
	v_pk_mul_f32 v[72:73], v[130:131], v[72:73] op_sel:[1,0] op_sel_hi:[0,1]
	v_mov_b32_e32 v88, v87
	v_mov_b32_e32 v92, v91
	v_pk_add_f32 v[110:111], v[108:109], 0 neg_lo:[1,1] neg_hi:[1,1]
	v_pk_add_f32 v[118:119], v[116:117], 0 neg_lo:[1,1] neg_hi:[1,1]
	v_pk_add_f32 v[122:123], v[120:121], 0 neg_lo:[1,1] neg_hi:[1,1]
	v_pk_add_f32 v[124:125], v[68:69], 0 neg_lo:[1,1] neg_hi:[1,1]
	ds_write_b64 v171, v[162:163]
	v_pk_fma_f32 v[78:79], v[148:149], v[78:79], v[80:81] op_sel_hi:[1,0,1]
	v_pk_mul_f32 v[80:81], v[150:151], v[84:85] op_sel:[1,0] op_sel_hi:[0,1]
	v_pk_fma_f32 v[84:85], v[154:155], v[98:99], v[96:97] op_sel_hi:[1,0,1]
	v_pk_mul_f32 v[96:97], v[132:133], v[106:107] op_sel:[1,0] op_sel_hi:[0,1]
	v_pk_add_f32 v[106:107], v[126:127], v[114:115]
	ds_write_b64 v172, v[66:67] offset:8192
	v_pk_fma_f32 v[66:67], v[130:131], v[70:71], v[72:73] op_sel_hi:[1,0,1]
	v_pk_mul_f32 v[70:71], v[142:143], v[76:77] op_sel:[1,0] op_sel_hi:[0,1]
	v_mov_b32_e32 v110, v109
	v_mov_b32_e32 v118, v117
	v_mov_b32_e32 v122, v121
	v_mov_b32_e32 v124, v69
	v_pk_add_f32 v[134:135], v[138:139], v[134:135] neg_lo:[0,1] neg_hi:[0,1]
	v_pk_fma_f32 v[98:99], v[144:145], v[112:113], v[100:101] op_sel_hi:[1,0,1]
	v_pk_add_f32 v[112:113], v[126:127], v[114:115] neg_lo:[0,1] neg_hi:[0,1]
	v_pk_mul_f32 v[76:77], v[128:129], v[88:89] op_sel:[1,0] op_sel_hi:[0,1]
	ds_write_b64 v173, v[66:67] offset:16384
	v_pk_fma_f32 v[66:67], v[142:143], v[74:75], v[70:71] op_sel_hi:[1,0,1]
	v_pk_mul_f32 v[74:75], v[106:107], v[92:93] op_sel:[1,0] op_sel_hi:[0,1]
	s_mov_b64 s[48:49], 0
	s_and_b64 vcc, exec, vcc
	v_pk_mul_f32 v[100:101], v[136:137], v[118:119] op_sel:[1,0] op_sel_hi:[0,1]
	v_pk_fma_f32 v[72:73], v[150:151], v[82:83], v[80:81] op_sel_hi:[1,0,1]
	v_pk_fma_f32 v[80:81], v[132:133], v[102:103], v[96:97] op_sel_hi:[1,0,1]
	v_pk_mul_f32 v[82:83], v[134:135], v[110:111] op_sel:[1,0] op_sel_hi:[0,1]
	v_pk_mul_f32 v[96:97], v[140:141], v[122:123] op_sel:[1,0] op_sel_hi:[0,1]
	v_pk_fma_f32 v[70:71], v[128:129], v[86:87], v[76:77] op_sel_hi:[1,0,1]
	v_pk_mul_f32 v[86:87], v[112:113], v[124:125] op_sel:[1,0] op_sel_hi:[0,1]
	ds_write_b64 v174, v[66:67] offset:24576
	ds_write_b64 v175, v[78:79] offset:32768
	ds_write_b64 v176, v[72:73] offset:40960
	ds_write_b64 v177, v[70:71] offset:49152
	v_pk_fma_f32 v[66:67], v[106:107], v[90:91], v[74:75] op_sel_hi:[1,0,1]
	v_pk_fma_f32 v[88:89], v[136:137], v[116:117], v[100:101] op_sel_hi:[1,0,1]
	v_pk_fma_f32 v[76:77], v[134:135], v[108:109], v[82:83] op_sel_hi:[1,0,1]
	v_pk_fma_f32 v[82:83], v[140:141], v[120:121], v[96:97] op_sel_hi:[1,0,1]
	v_pk_fma_f32 v[68:69], v[112:113], v[68:69], v[86:87] op_sel_hi:[1,0,1]
	ds_write_b64 v178, v[66:67] offset:57344
	ds_write_b64 v179, v[94:95]
	ds_write_b64 v180, v[84:85]
	ds_write_b64 v181, v[80:81]
	ds_write_b64 v182, v[76:77]
	ds_write_b64 v183, v[98:99]
	ds_write_b64 v184, v[88:89]
	ds_write_b64 v185, v[82:83]
	ds_write_b64 v186, v[68:69]
	s_cbranch_vccz .LBB0_362
	s_waitcnt lgkmcnt(0)
	s_barrier
	v_mov_b32 v0, 0
	s_mov_b32 s5, s14
	v_add_u32_e32 v74, v0, v170
	v_lshlrev_b32_e32 v0, 5, v74
	v_and_b32_e32 v71, 0xfffffc00, v0
	v_or_b32_e32 v75, 0x80, v71
	v_and_b32_e32 v70, 31, v74
	v_ashrrev_i32_e32 v75, 2, v75
	v_lshlrev_b32_e32 v78, 3, v71
	v_lshlrev_b32_e32 v79, 3, v70
	v_add_u32_e32 v75, 0, v75
	v_add3_u32 v111, v75, v78, v79
	v_or_b32_e32 v75, 0xa0, v71
	v_ashrrev_i32_e32 v75, 2, v75
	v_add_u32_e32 v75, 0, v75
	v_add3_u32 v110, v75, v78, v79
	v_or_b32_e32 v75, 0xc0, v71
	v_ashrrev_i32_e32 v75, 2, v75
	v_add_u32_e32 v75, 0, v75
	v_add3_u32 v109, v75, v78, v79
	v_or_b32_e32 v75, 0xe0, v71
	v_ashrrev_i32_e32 v75, 2, v75
	v_add_u32_e32 v75, 0, v75
	v_add3_u32 v108, v75, v78, v79
	v_or_b32_e32 v75, 0x100, v71
	v_ashrrev_i32_e32 v75, 2, v75
	v_add_u32_e32 v75, 0, v75
	v_add3_u32 v107, v75, v78, v79
	v_or_b32_e32 v75, 0x120, v71
	v_ashrrev_i32_e32 v75, 2, v75
	v_add_u32_e32 v75, 0, v75
	v_add3_u32 v106, v75, v78, v79
	v_or_b32_e32 v75, 0x140, v71
	v_ashrrev_i32_e32 v75, 2, v75
	v_add_u32_e32 v75, 0, v75
	v_add3_u32 v105, v75, v78, v79
	v_or_b32_e32 v75, 0x160, v71
	v_ashrrev_i32_e32 v75, 2, v75
	v_add_u32_e32 v75, 0, v75
	v_add3_u32 v103, v75, v78, v79
	v_or_b32_e32 v75, 0x180, v71
	v_ashrrev_i32_e32 v75, 2, v75
	v_add_u32_e32 v75, 0, v75
	v_add3_u32 v102, v75, v78, v79
	v_or_b32_e32 v75, 0x1a0, v71
	v_ashrrev_i32_e32 v75, 2, v75
	v_add_u32_e32 v75, 0, v75
	v_add3_u32 v101, v75, v78, v79
	v_or_b32_e32 v75, 0x1c0, v71
	v_ashrrev_i32_e32 v75, 2, v75
	v_add_u32_e32 v75, 0, v75
	v_add3_u32 v100, v75, v78, v79
	v_or_b32_e32 v75, 0x1e0, v71
	v_ashrrev_i32_e32 v75, 2, v75
	v_add_u32_e32 v75, 0, v75
	v_add3_u32 v99, v75, v78, v79
	v_or_b32_e32 v75, 0x200, v71
	v_ashrrev_i32_e32 v75, 2, v75
	v_add_u32_e32 v75, 0, v75
	v_add3_u32 v98, v75, v78, v79
	v_or_b32_e32 v75, 0x220, v71
	v_ashrrev_i32_e32 v75, 2, v75
	v_add_u32_e32 v75, 0, v75
	v_add3_u32 v97, v75, v78, v79
	v_or_b32_e32 v75, 0x240, v71
	v_ashrrev_i32_e32 v75, 2, v75
	v_add_u32_e32 v75, 0, v75
	v_add3_u32 v96, v75, v78, v79
	v_or_b32_e32 v75, 0x260, v71
	v_ashrrev_i32_e32 v75, 2, v75
	v_add_u32_e32 v75, 0, v75
	v_add3_u32 v95, v75, v78, v79
	v_or_b32_e32 v75, 0x280, v71
	v_or_b32_e32 v67, 32, v71
	v_ashrrev_i32_e32 v75, 2, v75
	v_ashrrev_i32_e32 v67, 2, v67
	v_add_u32_e32 v75, 0, v75
	v_add_u32_e32 v67, 0, v67
	v_add3_u32 v94, v75, v78, v79
	v_or_b32_e32 v75, 0x2a0, v71
	v_add3_u32 v114, v67, v78, v79
	v_or_b32_e32 v67, 64, v71
	v_ashrrev_i32_e32 v75, 2, v75
	v_ashrrev_i32_e32 v67, 2, v67
	v_add_u32_e32 v75, 0, v75
	v_add_u32_e32 v67, 0, v67
	v_add3_u32 v93, v75, v78, v79
	v_or_b32_e32 v75, 0x2c0, v71
	v_ashrrev_i32_e32 v66, 2, v71
	v_add3_u32 v113, v67, v78, v79
	v_or_b32_e32 v67, 0x60, v71
	v_ashrrev_i32_e32 v75, 2, v75
	v_add_u32_e32 v66, 0, v66
	v_ashrrev_i32_e32 v67, 2, v67
	v_add_u32_e32 v75, 0, v75
	v_add3_u32 v66, v66, v78, v79
	v_add_u32_e32 v67, 0, v67
	v_add3_u32 v92, v75, v78, v79
	v_or_b32_e32 v75, 0x2e0, v71
	v_add3_u32 v112, v67, v78, v79
	ds_read_b64 v[66:67], v66
	ds_read_b64 v[68:69], v114 offset:256
	ds_read_b64 v[72:73], v113 offset:512
	ds_read_b64 v[76:77], v112 offset:768
	ds_read_b64 v[80:81], v111 offset:1024
	ds_read_b64 v[82:83], v110 offset:1280
	ds_read_b64 v[116:117], v109 offset:1536
	ds_read_b64 v[118:119], v108 offset:1792
	ds_read_b64 v[120:121], v107 offset:2048
	ds_read_b64 v[122:123], v106 offset:2304
	ds_read_b64 v[124:125], v105 offset:2560
	ds_read_b64 v[126:127], v103 offset:2816
	ds_read_b64 v[128:129], v102 offset:3072
	ds_read_b64 v[130:131], v101 offset:3328
	ds_read_b64 v[132:133], v100 offset:3584
	ds_read_b64 v[134:135], v99 offset:3840
	ds_read_b64 v[136:137], v98 offset:4096
	ds_read_b64 v[138:139], v97 offset:4352
	ds_read_b64 v[140:141], v96 offset:4608
	ds_read_b64 v[142:143], v95 offset:4864
	v_ashrrev_i32_e32 v75, 2, v75
	v_add_u32_e32 v75, 0, v75
	v_add3_u32 v91, v75, v78, v79
	v_or_b32_e32 v75, 0x300, v71
	v_ashrrev_i32_e32 v75, 2, v75
	s_waitcnt lgkmcnt(3)
	v_pk_add_f32 v[168:169], v[66:67], v[136:137]
	v_pk_add_f32 v[66:67], v[66:67], v[136:137] neg_lo:[0,1] neg_hi:[0,1]
	s_waitcnt lgkmcnt(2)
	v_pk_add_f32 v[136:137], v[68:69], v[138:139]
	v_pk_add_f32 v[68:69], v[68:69], v[138:139] neg_lo:[0,1] neg_hi:[0,1]
	v_add_u32_e32 v75, 0, v75
	v_pk_mul_f32 v[138:139], v[68:69], s[18:19]
	v_add3_u32 v90, v75, v78, v79
	v_or_b32_e32 v75, 0x320, v71
	v_pk_fma_f32 v[68:69], v[68:69], s[20:21], v[138:139] op_sel:[0,0,1] op_sel_hi:[1,0,0]
	s_waitcnt lgkmcnt(1)
	v_pk_add_f32 v[138:139], v[72:73], v[140:141]
	v_pk_add_f32 v[72:73], v[72:73], v[140:141] neg_lo:[0,1] neg_hi:[0,1]
	v_ashrrev_i32_e32 v75, 2, v75
	v_pk_mul_f32 v[140:141], v[72:73], s[4:5]
	ds_read_b64 v[144:145], v94 offset:5120
	ds_read_b64 v[146:147], v93 offset:5376
	ds_read_b64 v[148:149], v92 offset:5632
	ds_read_b64 v[150:151], v91 offset:5888
	v_add_u32_e32 v75, 0, v75
	v_pk_fma_f32 v[72:73], v[72:73], s[6:7], v[140:141] op_sel:[0,0,1] op_sel_hi:[1,0,0]
	s_waitcnt lgkmcnt(4)
	v_pk_add_f32 v[140:141], v[76:77], v[142:143]
	v_pk_add_f32 v[76:77], v[76:77], v[142:143] neg_lo:[0,1] neg_hi:[0,1]
	v_add3_u32 v89, v75, v78, v79
	v_or_b32_e32 v75, 0x340, v71
	v_pk_mul_f32 v[142:143], v[76:77], s[22:23]
	v_ashrrev_i32_e32 v75, 2, v75
	v_pk_fma_f32 v[76:77], v[76:77], s[24:25], v[142:143] op_sel:[0,0,1] op_sel_hi:[1,0,0]
	s_waitcnt lgkmcnt(3)
	v_pk_add_f32 v[142:143], v[80:81], v[144:145]
	v_pk_add_f32 v[80:81], v[80:81], v[144:145] neg_lo:[0,1] neg_hi:[0,1]
	s_mov_b32 s9, s10
	v_add_u32_e32 v75, 0, v75
	v_pk_mul_f32 v[144:145], v[80:81], s[8:9]
	v_add3_u32 v88, v75, v78, v79
	v_or_b32_e32 v75, 0x360, v71
	v_pk_fma_f32 v[80:81], v[80:81], s[10:11], v[144:145] op_sel:[0,0,1] op_sel_hi:[1,0,0]
	s_waitcnt lgkmcnt(2)
	v_pk_add_f32 v[144:145], v[82:83], v[146:147]
	v_pk_add_f32 v[82:83], v[82:83], v[146:147] neg_lo:[0,1] neg_hi:[0,1]
	s_mov_b32 s27, s24
	v_ashrrev_i32_e32 v75, 2, v75
	v_pk_mul_f32 v[146:147], v[82:83], s[26:27]
	s_mov_b32 s0, s23
	v_add_u32_e32 v75, 0, v75
	v_pk_fma_f32 v[82:83], v[82:83], s[0:1], v[146:147] op_sel:[0,0,1] op_sel_hi:[1,0,0]
	s_waitcnt lgkmcnt(1)
	v_pk_add_f32 v[146:147], v[116:117], v[148:149]
	v_pk_add_f32 v[116:117], v[116:117], v[148:149] neg_lo:[0,1] neg_hi:[0,1]
	s_mov_b32 s13, s6
	v_add3_u32 v87, v75, v78, v79
	v_or_b32_e32 v75, 0x380, v71
	v_pk_mul_f32 v[148:149], v[116:117], s[12:13]
	ds_read_b64 v[152:153], v90 offset:6144
	ds_read_b64 v[154:155], v89 offset:6400
	ds_read_b64 v[156:157], v88 offset:6656
	ds_read_b64 v[158:159], v87 offset:6912
	v_ashrrev_i32_e32 v75, 2, v75
	v_pk_fma_f32 v[116:117], v[116:117], s[14:15], v[148:149] op_sel:[0,0,1] op_sel_hi:[1,0,0]
	s_waitcnt lgkmcnt(4)
	v_pk_add_f32 v[148:149], v[118:119], v[150:151]
	v_pk_add_f32 v[118:119], v[118:119], v[150:151] neg_lo:[0,1] neg_hi:[0,1]
	s_mov_b32 s35, s20
	v_add_u32_e32 v75, 0, v75
	v_pk_mul_f32 v[150:151], v[118:119], s[34:35]
	s_mov_b32 s48, s19
	v_add3_u32 v86, v75, v78, v79
	v_or_b32_e32 v75, 0x3a0, v71
	v_or_b32_e32 v71, 0x3c0, v71
	v_pk_fma_f32 v[118:119], v[118:119], s[48:49], v[150:151] op_sel:[0,0,1] op_sel_hi:[1,0,0]
	s_waitcnt lgkmcnt(3)
	v_pk_add_f32 v[150:151], v[120:121], v[152:153]
	v_pk_add_f32 v[152:153], v[120:121], v[152:153] op_sel:[1,1] op_sel_hi:[0,0] neg_lo:[0,1] neg_hi:[1,0]
	v_ashrrev_i32_e32 v71, 2, v71
	s_waitcnt lgkmcnt(2)
	v_pk_add_f32 v[120:121], v[122:123], v[154:155]
	v_pk_add_f32 v[122:123], v[122:123], v[154:155] neg_lo:[0,1] neg_hi:[0,1]
	v_add_u32_e32 v71, 0, v71
	v_or_b32_e32 v0, 0x3e0, v0
	v_pk_mul_f32 v[154:155], v[122:123], s[34:35]
	v_ashrrev_i32_e32 v75, 2, v75
	v_add3_u32 v84, v71, v78, v79
	v_ashrrev_i32_e32 v71, 2, v0
	v_pk_fma_f32 v[122:123], v[122:123], s[18:19], v[154:155] op_sel:[0,0,1] op_sel_hi:[1,0,0]
	s_waitcnt lgkmcnt(1)
	v_pk_add_f32 v[154:155], v[124:125], v[156:157]
	v_pk_add_f32 v[124:125], v[124:125], v[156:157] neg_lo:[0,1] neg_hi:[0,1]
	v_add_u32_e32 v75, 0, v75
	v_add_u32_e32 v71, 0, v71
	v_lshlrev_b32_e32 v0, 3, v0
	v_pk_mul_f32 v[156:157], v[124:125], s[12:13]
	v_add3_u32 v85, v75, v78, v79
	v_add3_u32 v0, v71, v0, v79
	ds_read_b64 v[160:161], v86 offset:7168
	ds_read_b64 v[162:163], v85 offset:7424
	ds_read_b64 v[164:165], v84 offset:7680
	ds_read_b64 v[166:167], v0
	v_pk_fma_f32 v[124:125], v[124:125], s[4:5], v[156:157] op_sel:[0,0,1] op_sel_hi:[1,0,0]
	s_waitcnt lgkmcnt(4)
	v_pk_add_f32 v[156:157], v[126:127], v[158:159]
	v_pk_add_f32 v[126:127], v[126:127], v[158:159] neg_lo:[0,1] neg_hi:[0,1]
	v_lshlrev_b32_e32 v70, 4, v70
	v_pk_mul_f32 v[158:159], v[126:127], s[26:27]
	v_cvt_f32_u32_e32 v75, v70
	v_pk_fma_f32 v[126:127], v[126:127], s[22:23], v[158:159] op_sel:[0,0,1] op_sel_hi:[1,0,0]
	s_waitcnt lgkmcnt(3)
	v_pk_add_f32 v[158:159], v[128:129], v[160:161]
	v_pk_add_f32 v[128:129], v[128:129], v[160:161] neg_lo:[0,1] neg_hi:[0,1]
	v_and_b32_e32 v74, 0x1fffffe0, v74
	v_pk_mul_f32 v[160:161], v[128:129], s[8:9]
	v_mul_f32_e32 v115, 0x38800000, v75
	v_pk_fma_f32 v[128:129], v[128:129], s[8:9], v[160:161] op_sel:[0,0,1] op_sel_hi:[1,0,0]
	s_waitcnt lgkmcnt(2)
	v_pk_add_f32 v[160:161], v[130:131], v[162:163]
	v_pk_add_f32 v[130:131], v[130:131], v[162:163] neg_lo:[0,1] neg_hi:[0,1]
	v_lshl_add_u32 v74, v74, 3, 0
	v_pk_mul_f32 v[162:163], v[130:131], s[22:23]
	v_sin_f32_e32 v75, v115
	v_pk_fma_f32 v[130:131], v[130:131], s[26:27], v[162:163] op_sel:[0,0,1] op_sel_hi:[1,0,0]
	s_waitcnt lgkmcnt(1)
	v_pk_add_f32 v[162:163], v[132:133], v[164:165]
	v_pk_add_f32 v[132:133], v[132:133], v[164:165] neg_lo:[0,1] neg_hi:[0,1]
	v_add3_u32 v74, v74, v78, v79
	v_pk_mul_f32 v[164:165], v[132:133], s[4:5]
	v_xor_b32_e32 v78, 0x80000000, v75
	v_pk_fma_f32 v[132:133], v[132:133], s[12:13], v[164:165] op_sel:[0,0,1] op_sel_hi:[1,0,0]
	s_waitcnt lgkmcnt(0)
	v_pk_add_f32 v[164:165], v[134:135], v[166:167]
	v_pk_add_f32 v[134:135], v[134:135], v[166:167] neg_lo:[0,1] neg_hi:[0,1]
	v_mov_b32_e32 v79, v75
	v_pk_mul_f32 v[166:167], v[134:135], s[18:19]
	s_mov_b32 s50, s19
	v_pk_fma_f32 v[134:135], v[134:135], s[34:35], v[166:167] op_sel:[0,0,1] op_sel_hi:[1,0,0]
	v_pk_add_f32 v[166:167], v[168:169], v[150:151]
	v_pk_add_f32 v[150:151], v[168:169], v[150:151] neg_lo:[0,1] neg_hi:[0,1]
	v_pk_add_f32 v[168:169], v[136:137], v[120:121]
	v_pk_add_f32 v[120:121], v[136:137], v[120:121] neg_lo:[0,1] neg_hi:[0,1]
	s_mov_b32 s51, s18
	v_pk_mul_f32 v[136:137], v[120:121], s[4:5]
	s_mov_b32 s52, s23
	v_pk_fma_f32 v[120:121], v[120:121], s[6:7], v[136:137] op_sel:[0,0,1] op_sel_hi:[1,0,0]
	v_pk_add_f32 v[136:137], v[138:139], v[154:155]
	v_pk_add_f32 v[138:139], v[138:139], v[154:155] neg_lo:[0,1] neg_hi:[0,1]
	s_mov_b32 s53, s22
	v_pk_mul_f32 v[154:155], v[138:139], s[8:9]
	s_nop 0
	v_pk_fma_f32 v[138:139], v[138:139], s[10:11], v[154:155] op_sel:[0,0,1] op_sel_hi:[1,0,0]
	v_pk_add_f32 v[154:155], v[140:141], v[156:157]
	v_pk_add_f32 v[140:141], v[140:141], v[156:157] neg_lo:[0,1] neg_hi:[0,1]
	s_nop 0
	v_pk_mul_f32 v[156:157], v[140:141], s[12:13]
	s_nop 0
	v_pk_fma_f32 v[140:141], v[140:141], s[14:15], v[156:157] op_sel:[0,0,1] op_sel_hi:[1,0,0]
	v_pk_add_f32 v[156:157], v[142:143], v[158:159]
	v_pk_add_f32 v[158:159], v[142:143], v[158:159] op_sel:[1,1] op_sel_hi:[0,0] neg_lo:[0,1] neg_hi:[1,0]
	s_nop 0
	v_pk_add_f32 v[142:143], v[144:145], v[160:161]
	v_pk_add_f32 v[144:145], v[144:145], v[160:161] neg_lo:[0,1] neg_hi:[0,1]
	s_nop 0
	v_pk_mul_f32 v[160:161], v[144:145], s[12:13]
	s_nop 0
	v_pk_fma_f32 v[144:145], v[144:145], s[4:5], v[160:161] op_sel:[0,0,1] op_sel_hi:[1,0,0]
	v_pk_add_f32 v[160:161], v[146:147], v[162:163]
	v_pk_add_f32 v[146:147], v[146:147], v[162:163] neg_lo:[0,1] neg_hi:[0,1]
	s_nop 0
	v_pk_mul_f32 v[162:163], v[146:147], s[8:9]
	s_nop 0
	v_pk_fma_f32 v[146:147], v[146:147], s[8:9], v[162:163] op_sel:[0,0,1] op_sel_hi:[1,0,0]
	v_pk_add_f32 v[162:163], v[148:149], v[164:165]
	v_pk_add_f32 v[148:149], v[148:149], v[164:165] neg_lo:[0,1] neg_hi:[0,1]
	s_nop 0
	v_pk_mul_f32 v[164:165], v[148:149], s[4:5]
	s_nop 0
	v_pk_fma_f32 v[148:149], v[148:149], s[12:13], v[164:165] op_sel:[0,0,1] op_sel_hi:[1,0,0]
	v_pk_add_f32 v[164:165], v[66:67], v[152:153]
	v_pk_add_f32 v[66:67], v[66:67], v[152:153] neg_lo:[0,1] neg_hi:[0,1]
	v_pk_add_f32 v[152:153], v[68:69], v[122:123]
	v_pk_add_f32 v[68:69], v[68:69], v[122:123] neg_lo:[0,1] neg_hi:[0,1]
	s_nop 0
	v_pk_mul_f32 v[122:123], v[68:69], s[4:5]
	s_nop 0
	v_pk_fma_f32 v[68:69], v[68:69], s[6:7], v[122:123] op_sel:[0,0,1] op_sel_hi:[1,0,0]
	v_pk_add_f32 v[122:123], v[72:73], v[124:125]
	v_pk_add_f32 v[72:73], v[72:73], v[124:125] neg_lo:[0,1] neg_hi:[0,1]
	s_nop 0
	v_pk_mul_f32 v[124:125], v[72:73], s[8:9]
	s_nop 0
	v_pk_fma_f32 v[72:73], v[72:73], s[10:11], v[124:125] op_sel:[0,0,1] op_sel_hi:[1,0,0]
	v_pk_add_f32 v[124:125], v[76:77], v[126:127]
	v_pk_add_f32 v[76:77], v[76:77], v[126:127] neg_lo:[0,1] neg_hi:[0,1]
	s_nop 0
	v_pk_mul_f32 v[126:127], v[76:77], s[12:13]
	s_nop 0
	v_pk_fma_f32 v[76:77], v[76:77], s[14:15], v[126:127] op_sel:[0,0,1] op_sel_hi:[1,0,0]
	v_pk_add_f32 v[126:127], v[80:81], v[128:129]
	v_pk_add_f32 v[128:129], v[80:81], v[128:129] op_sel:[1,1] op_sel_hi:[0,0] neg_lo:[0,1] neg_hi:[1,0]
	s_nop 0
	v_pk_add_f32 v[80:81], v[82:83], v[130:131]
	v_pk_add_f32 v[82:83], v[82:83], v[130:131] neg_lo:[0,1] neg_hi:[0,1]
	s_nop 0
	v_pk_mul_f32 v[130:131], v[82:83], s[12:13]
	s_nop 0
	v_pk_fma_f32 v[82:83], v[82:83], s[4:5], v[130:131] op_sel:[0,0,1] op_sel_hi:[1,0,0]
	v_pk_add_f32 v[130:131], v[116:117], v[132:133]
	v_pk_add_f32 v[116:117], v[116:117], v[132:133] neg_lo:[0,1] neg_hi:[0,1]
	s_nop 0
	v_pk_mul_f32 v[132:133], v[116:117], s[8:9]
	s_nop 0
	v_pk_fma_f32 v[116:117], v[116:117], s[8:9], v[132:133] op_sel:[0,0,1] op_sel_hi:[1,0,0]
	v_pk_add_f32 v[132:133], v[118:119], v[134:135]
	v_pk_add_f32 v[118:119], v[118:119], v[134:135] neg_lo:[0,1] neg_hi:[0,1]
	s_nop 0
	v_pk_mul_f32 v[134:135], v[118:119], s[4:5]
	s_nop 0
	v_pk_fma_f32 v[118:119], v[118:119], s[12:13], v[134:135] op_sel:[0,0,1] op_sel_hi:[1,0,0]
	v_pk_add_f32 v[134:135], v[166:167], v[156:157]
	v_pk_add_f32 v[156:157], v[166:167], v[156:157] neg_lo:[0,1] neg_hi:[0,1]
	v_pk_add_f32 v[166:167], v[168:169], v[142:143]
	v_pk_add_f32 v[142:143], v[168:169], v[142:143] neg_lo:[0,1] neg_hi:[0,1]
	s_nop 0
	v_pk_mul_f32 v[168:169], v[142:143], s[8:9]
	s_nop 0
	v_pk_fma_f32 v[142:143], v[142:143], s[10:11], v[168:169] op_sel:[0,0,1] op_sel_hi:[1,0,0]
	v_pk_add_f32 v[168:169], v[136:137], v[160:161]
	v_pk_add_f32 v[160:161], v[136:137], v[160:161] op_sel:[1,1] op_sel_hi:[0,0] neg_lo:[0,1] neg_hi:[1,0]
	s_nop 0
	v_pk_add_f32 v[136:137], v[154:155], v[162:163]
	v_pk_add_f32 v[154:155], v[154:155], v[162:163] neg_lo:[0,1] neg_hi:[0,1]
	s_nop 0
	v_pk_mul_f32 v[162:163], v[154:155], s[8:9]
	s_nop 0
	v_pk_fma_f32 v[154:155], v[154:155], s[8:9], v[162:163] op_sel:[0,0,1] op_sel_hi:[1,0,0]
	v_pk_add_f32 v[162:163], v[150:151], v[158:159]
	v_pk_add_f32 v[150:151], v[150:151], v[158:159] neg_lo:[0,1] neg_hi:[0,1]
	v_pk_add_f32 v[158:159], v[120:121], v[144:145]
	v_pk_add_f32 v[120:121], v[120:121], v[144:145] neg_lo:[0,1] neg_hi:[0,1]
	s_nop 0
	v_pk_mul_f32 v[144:145], v[120:121], s[8:9]
	s_nop 0
	v_pk_fma_f32 v[120:121], v[120:121], s[10:11], v[144:145] op_sel:[0,0,1] op_sel_hi:[1,0,0]
	v_pk_add_f32 v[144:145], v[138:139], v[146:147]
	v_pk_add_f32 v[146:147], v[138:139], v[146:147] op_sel:[1,1] op_sel_hi:[0,0] neg_lo:[0,1] neg_hi:[1,0]
	s_nop 0
	v_pk_add_f32 v[138:139], v[140:141], v[148:149]
	v_pk_add_f32 v[140:141], v[140:141], v[148:149] neg_lo:[0,1] neg_hi:[0,1]
	s_nop 0
	v_pk_mul_f32 v[148:149], v[140:141], s[8:9]
	s_nop 0
	v_pk_fma_f32 v[140:141], v[140:141], s[8:9], v[148:149] op_sel:[0,0,1] op_sel_hi:[1,0,0]
	v_pk_add_f32 v[148:149], v[164:165], v[126:127]
	v_pk_add_f32 v[126:127], v[164:165], v[126:127] neg_lo:[0,1] neg_hi:[0,1]
	v_pk_add_f32 v[164:165], v[152:153], v[80:81]
	v_pk_add_f32 v[80:81], v[152:153], v[80:81] neg_lo:[0,1] neg_hi:[0,1]
	s_nop 0
	v_pk_mul_f32 v[152:153], v[80:81], s[8:9]
	s_nop 0
	v_pk_fma_f32 v[80:81], v[80:81], s[10:11], v[152:153] op_sel:[0,0,1] op_sel_hi:[1,0,0]
	v_pk_add_f32 v[152:153], v[122:123], v[130:131]
	v_pk_add_f32 v[130:131], v[122:123], v[130:131] op_sel:[1,1] op_sel_hi:[0,0] neg_lo:[0,1] neg_hi:[1,0]
	s_nop 0
	v_pk_add_f32 v[122:123], v[124:125], v[132:133]
	v_pk_add_f32 v[124:125], v[124:125], v[132:133] neg_lo:[0,1] neg_hi:[0,1]
	s_nop 0
	v_pk_mul_f32 v[132:133], v[124:125], s[8:9]
	s_nop 0
	v_pk_fma_f32 v[124:125], v[124:125], s[8:9], v[132:133] op_sel:[0,0,1] op_sel_hi:[1,0,0]
	v_pk_add_f32 v[132:133], v[66:67], v[128:129]
	v_pk_add_f32 v[66:67], v[66:67], v[128:129] neg_lo:[0,1] neg_hi:[0,1]
	v_pk_add_f32 v[128:129], v[68:69], v[82:83]
	v_pk_add_f32 v[68:69], v[68:69], v[82:83] neg_lo:[0,1] neg_hi:[0,1]
	s_nop 0
	v_pk_mul_f32 v[82:83], v[68:69], s[8:9]
	s_nop 0
	v_pk_fma_f32 v[68:69], v[68:69], s[10:11], v[82:83] op_sel:[0,0,1] op_sel_hi:[1,0,0]
	v_pk_add_f32 v[82:83], v[72:73], v[116:117]
	v_pk_add_f32 v[116:117], v[72:73], v[116:117] op_sel:[1,1] op_sel_hi:[0,0] neg_lo:[0,1] neg_hi:[1,0]
	s_nop 0
	v_pk_add_f32 v[72:73], v[76:77], v[118:119]
	v_pk_add_f32 v[76:77], v[76:77], v[118:119] neg_lo:[0,1] neg_hi:[0,1]
	v_pk_add_f32 v[174:175], v[66:67], v[116:117]
	v_pk_mul_f32 v[118:119], v[76:77], s[8:9]
	v_pk_add_f32 v[116:117], v[66:67], v[116:117] neg_lo:[0,1] neg_hi:[0,1]
	v_pk_fma_f32 v[76:77], v[76:77], s[8:9], v[118:119] op_sel:[0,0,1] op_sel_hi:[1,0,0]
	v_pk_add_f32 v[118:119], v[134:135], v[168:169]
	v_pk_add_f32 v[134:135], v[134:135], v[168:169] neg_lo:[0,1] neg_hi:[0,1]
	v_pk_add_f32 v[168:169], v[166:167], v[136:137]
	v_pk_add_f32 v[166:167], v[166:167], v[136:137] op_sel:[1,1] op_sel_hi:[0,0] neg_lo:[0,1] neg_hi:[1,0]
	v_pk_add_f32 v[180:181], v[118:119], v[168:169]
	v_pk_add_f32 v[136:137], v[156:157], v[160:161]
	v_pk_add_f32 v[156:157], v[156:157], v[160:161] neg_lo:[0,1] neg_hi:[0,1]
	v_pk_add_f32 v[160:161], v[142:143], v[154:155]
	v_pk_add_f32 v[154:155], v[142:143], v[154:155] op_sel:[1,1] op_sel_hi:[0,0] neg_lo:[0,1] neg_hi:[1,0]
	v_pk_add_f32 v[66:67], v[68:69], v[76:77] neg_lo:[0,1] neg_hi:[0,1]
	v_pk_add_f32 v[142:143], v[162:163], v[144:145]
	v_pk_add_f32 v[144:145], v[162:163], v[144:145] neg_lo:[0,1] neg_hi:[0,1]
	v_pk_add_f32 v[162:163], v[158:159], v[138:139]
	v_pk_add_f32 v[158:159], v[158:159], v[138:139] op_sel:[1,1] op_sel_hi:[0,0] neg_lo:[0,1] neg_hi:[1,0]
	ds_write_b64 v74, v[180:181]
	v_pk_add_f32 v[138:139], v[150:151], v[146:147]
	v_pk_add_f32 v[146:147], v[150:151], v[146:147] neg_lo:[0,1] neg_hi:[0,1]
	v_pk_add_f32 v[150:151], v[120:121], v[140:141]
	v_pk_add_f32 v[140:141], v[120:121], v[140:141] op_sel:[1,1] op_sel_hi:[0,0] neg_lo:[0,1] neg_hi:[1,0]
	v_cos_f32_e32 v74, v115
	v_pk_add_f32 v[120:121], v[148:149], v[152:153]
	v_pk_add_f32 v[148:149], v[148:149], v[152:153] neg_lo:[0,1] neg_hi:[0,1]
	v_pk_add_f32 v[152:153], v[164:165], v[122:123]
	v_pk_add_f32 v[164:165], v[164:165], v[122:123] op_sel:[1,1] op_sel_hi:[0,0] neg_lo:[0,1] neg_hi:[1,0]
	v_xor_b32_e32 v179, 0x80000000, v66
	v_pk_add_f32 v[122:123], v[126:127], v[130:131]
	v_pk_add_f32 v[126:127], v[126:127], v[130:131] neg_lo:[0,1] neg_hi:[0,1]
	v_pk_add_f32 v[130:131], v[80:81], v[124:125]
	v_pk_add_f32 v[124:125], v[80:81], v[124:125] op_sel:[1,1] op_sel_hi:[0,0] neg_lo:[0,1] neg_hi:[1,0]
	v_mov_b32_e32 v178, v67
	v_pk_add_f32 v[80:81], v[132:133], v[82:83]
	v_pk_add_f32 v[132:133], v[132:133], v[82:83] neg_lo:[0,1] neg_hi:[0,1]
	v_pk_add_f32 v[176:177], v[68:69], v[76:77]
	v_pk_add_f32 v[118:119], v[118:119], v[168:169] neg_lo:[0,1] neg_hi:[0,1]
	v_pk_add_f32 v[168:169], v[134:135], v[166:167]
	v_pk_add_f32 v[82:83], v[134:135], v[166:167] neg_lo:[0,1] neg_hi:[0,1]
	v_pk_add_f32 v[134:135], v[136:137], v[160:161]
	v_pk_add_f32 v[136:137], v[136:137], v[160:161] neg_lo:[0,1] neg_hi:[0,1]
	v_pk_add_f32 v[160:161], v[156:157], v[154:155]
	v_pk_add_f32 v[68:69], v[156:157], v[154:155] neg_lo:[0,1] neg_hi:[0,1]
	v_pk_add_f32 v[154:155], v[142:143], v[162:163]
	v_pk_add_f32 v[142:143], v[142:143], v[162:163] neg_lo:[0,1] neg_hi:[0,1]
	v_pk_add_f32 v[156:157], v[144:145], v[158:159]
	v_pk_add_f32 v[76:77], v[144:145], v[158:159] neg_lo:[0,1] neg_hi:[0,1]
	v_pk_add_f32 v[144:145], v[138:139], v[150:151]
	v_pk_add_f32 v[138:139], v[138:139], v[150:151] neg_lo:[0,1] neg_hi:[0,1]
	v_pk_add_f32 v[150:151], v[146:147], v[140:141]
	v_pk_add_f32 v[66:67], v[146:147], v[140:141] neg_lo:[0,1] neg_hi:[0,1]
	v_pk_add_f32 v[140:141], v[120:121], v[152:153]
	v_pk_add_f32 v[162:163], v[116:117], v[178:179]
	v_pk_add_f32 v[70:71], v[116:117], v[178:179] neg_lo:[0,1] neg_hi:[0,1]
	v_mov_b32_e32 v116, v75
	v_pk_mul_f32 v[116:117], v[116:117], v[140:141] op_sel:[0,1] op_sel_hi:[0,0] neg_hi:[1,0]
	v_pk_fma_f32 v[116:117], v[140:141], v[74:75], v[116:117] op_sel_hi:[1,0,1]
	ds_write_b64 v114, v[116:117] offset:256
	v_pk_mul_f32 v[114:115], v[78:79], v[74:75] op_sel:[0,1] op_sel_hi:[1,0]
	v_pk_add_f32 v[172:173], v[128:129], v[72:73]
	v_pk_fma_f32 v[114:115], v[74:75], v[74:75], v[114:115] op_sel_hi:[1,0,1]
	v_pk_add_f32 v[128:129], v[128:129], v[72:73] op_sel:[1,1] op_sel_hi:[0,0] neg_lo:[0,1] neg_hi:[1,0]
	v_pk_mul_f32 v[116:117], v[154:155], v[114:115] op_sel:[1,1] op_sel_hi:[0,1] neg_hi:[0,1]
	v_pk_fma_f32 v[116:117], v[154:155], v[114:115], v[116:117] op_sel_hi:[1,0,1]
	ds_write_b64 v113, v[116:117] offset:512
	v_pk_mul_f32 v[116:117], v[78:79], v[114:115] op_sel:[0,1] op_sel_hi:[1,0]
	v_pk_add_f32 v[120:121], v[120:121], v[152:153] neg_lo:[0,1] neg_hi:[0,1]
	v_pk_fma_f32 v[114:115], v[114:115], v[74:75], v[116:117] op_sel_hi:[1,0,1]
	v_pk_add_f32 v[152:153], v[122:123], v[130:131]
	v_pk_add_f32 v[122:123], v[122:123], v[130:131] neg_lo:[0,1] neg_hi:[0,1]
	v_pk_add_f32 v[130:131], v[126:127], v[124:125]
	v_pk_add_f32 v[72:73], v[126:127], v[124:125] neg_lo:[0,1] neg_hi:[0,1]
	v_pk_add_f32 v[124:125], v[80:81], v[172:173]
	v_pk_mul_f32 v[116:117], v[124:125], v[114:115] op_sel:[1,1] op_sel_hi:[0,1] neg_hi:[0,1]
	v_pk_add_f32 v[126:127], v[80:81], v[172:173] neg_lo:[0,1] neg_hi:[0,1]
	v_pk_fma_f32 v[116:117], v[124:125], v[114:115], v[116:117] op_sel_hi:[1,0,1]
	ds_write_b64 v112, v[116:117] offset:768
	v_pk_mul_f32 v[112:113], v[78:79], v[114:115] op_sel:[0,1] op_sel_hi:[1,0]
	v_pk_add_f32 v[158:159], v[132:133], v[128:129]
	v_pk_fma_f32 v[112:113], v[114:115], v[74:75], v[112:113] op_sel_hi:[1,0,1]
	v_pk_add_f32 v[80:81], v[132:133], v[128:129] neg_lo:[0,1] neg_hi:[0,1]
	v_pk_add_f32 v[128:129], v[174:175], v[176:177]
	v_pk_mul_f32 v[114:115], v[134:135], v[112:113] op_sel:[1,1] op_sel_hi:[0,1] neg_hi:[0,1]
	v_pk_add_f32 v[146:147], v[148:149], v[164:165]
	v_pk_fma_f32 v[114:115], v[134:135], v[112:113], v[114:115] op_sel_hi:[1,0,1]
	ds_write_b64 v111, v[114:115] offset:1024
	v_pk_mul_f32 v[114:115], v[78:79], v[112:113] op_sel:[0,1] op_sel_hi:[1,0]
	v_pk_add_f32 v[132:133], v[174:175], v[176:177] neg_lo:[0,1] neg_hi:[0,1]
	v_pk_fma_f32 v[112:113], v[112:113], v[74:75], v[114:115] op_sel_hi:[1,0,1]
	v_pk_add_f32 v[148:149], v[148:149], v[164:165] neg_lo:[0,1] neg_hi:[0,1]
	s_nop 0
	v_pk_mul_f32 v[114:115], v[152:153], v[112:113] op_sel:[1,1] op_sel_hi:[0,1] neg_hi:[0,1]
	s_nop 0
	v_pk_fma_f32 v[114:115], v[152:153], v[112:113], v[114:115] op_sel_hi:[1,0,1]
	ds_write_b64 v110, v[114:115] offset:1280
	v_pk_mul_f32 v[110:111], v[78:79], v[112:113] op_sel:[0,1] op_sel_hi:[1,0]
	s_nop 0
	v_pk_fma_f32 v[110:111], v[112:113], v[74:75], v[110:111] op_sel_hi:[1,0,1]
	s_nop 0
	s_nop 0
	v_pk_mul_f32 v[112:113], v[144:145], v[110:111] op_sel:[1,1] op_sel_hi:[0,1] neg_hi:[0,1]
	s_nop 0
	v_pk_fma_f32 v[112:113], v[144:145], v[110:111], v[112:113] op_sel_hi:[1,0,1]
	ds_write_b64 v109, v[112:113] offset:1536
	v_pk_mul_f32 v[112:113], v[78:79], v[110:111] op_sel:[0,1] op_sel_hi:[1,0]
	s_nop 0
	v_pk_fma_f32 v[110:111], v[110:111], v[74:75], v[112:113] op_sel_hi:[1,0,1]
	s_nop 0
	s_nop 0
	v_pk_mul_f32 v[112:113], v[128:129], v[110:111] op_sel:[1,1] op_sel_hi:[0,1] neg_hi:[0,1]
	s_nop 0
	v_pk_fma_f32 v[112:113], v[128:129], v[110:111], v[112:113] op_sel_hi:[1,0,1]
	ds_write_b64 v108, v[112:113] offset:1792
	v_pk_mul_f32 v[108:109], v[78:79], v[110:111] op_sel:[0,1] op_sel_hi:[1,0]
	s_nop 0
	v_pk_fma_f32 v[108:109], v[110:111], v[74:75], v[108:109] op_sel_hi:[1,0,1]
	s_nop 0
	s_nop 0
	v_pk_mul_f32 v[110:111], v[168:169], v[108:109] op_sel:[1,1] op_sel_hi:[0,1] neg_hi:[0,1]
	s_nop 0
	v_pk_fma_f32 v[110:111], v[168:169], v[108:109], v[110:111] op_sel_hi:[1,0,1]
	ds_write_b64 v107, v[110:111] offset:2048
	v_pk_mul_f32 v[110:111], v[78:79], v[108:109] op_sel:[0,1] op_sel_hi:[1,0]
	s_nop 0
	v_pk_fma_f32 v[108:109], v[108:109], v[74:75], v[110:111] op_sel_hi:[1,0,1]
	s_nop 0
	s_nop 0
	v_pk_mul_f32 v[110:111], v[146:147], v[108:109] op_sel:[1,1] op_sel_hi:[0,1] neg_hi:[0,1]
	s_nop 0
	v_pk_fma_f32 v[110:111], v[146:147], v[108:109], v[110:111] op_sel_hi:[1,0,1]
	ds_write_b64 v106, v[110:111] offset:2304
	v_pk_mul_f32 v[106:107], v[78:79], v[108:109] op_sel:[0,1] op_sel_hi:[1,0]
	s_nop 0
	v_pk_fma_f32 v[106:107], v[108:109], v[74:75], v[106:107] op_sel_hi:[1,0,1]
	s_nop 0
	s_nop 0
	v_pk_mul_f32 v[108:109], v[156:157], v[106:107] op_sel:[1,1] op_sel_hi:[0,1] neg_hi:[0,1]
	s_nop 0
	v_pk_fma_f32 v[108:109], v[156:157], v[106:107], v[108:109] op_sel_hi:[1,0,1]
	ds_write_b64 v105, v[108:109] offset:2560
	v_pk_mul_f32 v[108:109], v[78:79], v[106:107] op_sel:[0,1] op_sel_hi:[1,0]
	s_nop 0
	v_pk_fma_f32 v[106:107], v[106:107], v[74:75], v[108:109] op_sel_hi:[1,0,1]
	s_nop 0
	s_nop 0
	v_pk_mul_f32 v[108:109], v[158:159], v[106:107] op_sel:[1,1] op_sel_hi:[0,1] neg_hi:[0,1]
	s_nop 0
	v_pk_fma_f32 v[108:109], v[158:159], v[106:107], v[108:109] op_sel_hi:[1,0,1]
	ds_write_b64 v103, v[108:109] offset:2816
	v_pk_mul_f32 v[108:109], v[78:79], v[106:107] op_sel:[0,1] op_sel_hi:[1,0]
	s_nop 0
	v_pk_fma_f32 v[106:107], v[106:107], v[74:75], v[108:109] op_sel_hi:[1,0,1]
	s_nop 0
	s_nop 0
	v_pk_mul_f32 v[108:109], v[160:161], v[106:107] op_sel:[1,1] op_sel_hi:[0,1] neg_hi:[0,1]
	s_nop 0
	v_pk_fma_f32 v[108:109], v[160:161], v[106:107], v[108:109] op_sel_hi:[1,0,1]
	ds_write_b64 v102, v[108:109] offset:3072
	v_pk_mul_f32 v[102:103], v[78:79], v[106:107] op_sel:[0,1] op_sel_hi:[1,0]
	s_nop 0
	v_pk_fma_f32 v[102:103], v[106:107], v[74:75], v[102:103] op_sel_hi:[1,0,1]
	s_nop 0
	s_nop 0
	v_pk_mul_f32 v[106:107], v[130:131], v[102:103] op_sel:[1,1] op_sel_hi:[0,1] neg_hi:[0,1]
	s_nop 0
	v_pk_fma_f32 v[106:107], v[130:131], v[102:103], v[106:107] op_sel_hi:[1,0,1]
	ds_write_b64 v101, v[106:107] offset:3328
	v_pk_mul_f32 v[106:107], v[78:79], v[102:103] op_sel:[0,1] op_sel_hi:[1,0]
	s_nop 0
	v_pk_fma_f32 v[102:103], v[102:103], v[74:75], v[106:107] op_sel_hi:[1,0,1]
	s_nop 0
	s_nop 0
	v_pk_mul_f32 v[106:107], v[150:151], v[102:103] op_sel:[1,1] op_sel_hi:[0,1] neg_hi:[0,1]
	v_pk_fma_f32 v[106:107], v[150:151], v[102:103], v[106:107] op_sel_hi:[1,0,1]
	ds_write_b64 v100, v[106:107] offset:3584
	v_pk_mul_f32 v[100:101], v[78:79], v[102:103] op_sel:[0,1] op_sel_hi:[1,0]
	s_nop 0
	v_pk_fma_f32 v[100:101], v[102:103], v[74:75], v[100:101] op_sel_hi:[1,0,1]
	s_nop 0
	s_nop 0
	v_pk_mul_f32 v[102:103], v[162:163], v[100:101] op_sel:[1,1] op_sel_hi:[0,1] neg_hi:[0,1]
	v_pk_fma_f32 v[102:103], v[162:163], v[100:101], v[102:103] op_sel_hi:[1,0,1]
	ds_write_b64 v99, v[102:103] offset:3840
	v_pk_mul_f32 v[102:103], v[78:79], v[100:101] op_sel:[0,1] op_sel_hi:[1,0]
	s_nop 0
	v_pk_fma_f32 v[100:101], v[100:101], v[74:75], v[102:103] op_sel_hi:[1,0,1]
	s_nop 0
	s_nop 0
	v_pk_mul_f32 v[102:103], v[118:119], v[100:101] op_sel:[1,1] op_sel_hi:[0,1] neg_hi:[0,1]
	v_pk_fma_f32 v[102:103], v[118:119], v[100:101], v[102:103] op_sel_hi:[1,0,1]
	ds_write_b64 v98, v[102:103] offset:4096
	v_pk_mul_f32 v[98:99], v[78:79], v[100:101] op_sel:[0,1] op_sel_hi:[1,0]
	s_nop 0
	v_pk_fma_f32 v[98:99], v[100:101], v[74:75], v[98:99] op_sel_hi:[1,0,1]
	s_nop 0
	s_nop 0
	v_pk_mul_f32 v[100:101], v[120:121], v[98:99] op_sel:[1,1] op_sel_hi:[0,1] neg_hi:[0,1]
	v_pk_fma_f32 v[100:101], v[120:121], v[98:99], v[100:101] op_sel_hi:[1,0,1]
	ds_write_b64 v97, v[100:101] offset:4352
	v_pk_mul_f32 v[100:101], v[78:79], v[98:99] op_sel:[0,1] op_sel_hi:[1,0]
	s_nop 0
	v_pk_fma_f32 v[98:99], v[98:99], v[74:75], v[100:101] op_sel_hi:[1,0,1]
	s_nop 0
	s_nop 0
	v_pk_mul_f32 v[100:101], v[142:143], v[98:99] op_sel:[1,1] op_sel_hi:[0,1] neg_hi:[0,1]
	v_pk_fma_f32 v[100:101], v[142:143], v[98:99], v[100:101] op_sel_hi:[1,0,1]
	ds_write_b64 v96, v[100:101] offset:4608
	v_pk_mul_f32 v[96:97], v[78:79], v[98:99] op_sel:[0,1] op_sel_hi:[1,0]
	s_nop 0
	v_pk_fma_f32 v[96:97], v[98:99], v[74:75], v[96:97] op_sel_hi:[1,0,1]
	s_nop 0
	s_nop 0
	v_pk_mul_f32 v[98:99], v[126:127], v[96:97] op_sel:[1,1] op_sel_hi:[0,1] neg_hi:[0,1]
	v_pk_fma_f32 v[98:99], v[126:127], v[96:97], v[98:99] op_sel_hi:[1,0,1]
	ds_write_b64 v95, v[98:99] offset:4864
	v_pk_mul_f32 v[98:99], v[78:79], v[96:97] op_sel:[0,1] op_sel_hi:[1,0]
	s_nop 0
	v_pk_fma_f32 v[96:97], v[96:97], v[74:75], v[98:99] op_sel_hi:[1,0,1]
	s_nop 0
	s_nop 0
	v_pk_mul_f32 v[98:99], v[136:137], v[96:97] op_sel:[1,1] op_sel_hi:[0,1] neg_hi:[0,1]
	v_pk_fma_f32 v[98:99], v[136:137], v[96:97], v[98:99] op_sel_hi:[1,0,1]
	ds_write_b64 v94, v[98:99] offset:5120
	v_pk_mul_f32 v[94:95], v[78:79], v[96:97] op_sel:[0,1] op_sel_hi:[1,0]
	s_nop 0
	v_pk_fma_f32 v[94:95], v[96:97], v[74:75], v[94:95] op_sel_hi:[1,0,1]
	s_nop 0
	s_nop 0
	v_pk_mul_f32 v[96:97], v[122:123], v[94:95] op_sel:[1,1] op_sel_hi:[0,1] neg_hi:[0,1]
	v_pk_fma_f32 v[96:97], v[122:123], v[94:95], v[96:97] op_sel_hi:[1,0,1]
	ds_write_b64 v93, v[96:97] offset:5376
	v_pk_mul_f32 v[96:97], v[78:79], v[94:95] op_sel:[0,1] op_sel_hi:[1,0]
	s_nop 0
	v_pk_fma_f32 v[94:95], v[94:95], v[74:75], v[96:97] op_sel_hi:[1,0,1]
	s_nop 0
	s_nop 0
	v_pk_mul_f32 v[96:97], v[138:139], v[94:95] op_sel:[1,1] op_sel_hi:[0,1] neg_hi:[0,1]
	v_pk_fma_f32 v[96:97], v[138:139], v[94:95], v[96:97] op_sel_hi:[1,0,1]
	ds_write_b64 v92, v[96:97] offset:5632
	v_pk_mul_f32 v[92:93], v[78:79], v[94:95] op_sel:[0,1] op_sel_hi:[1,0]
	s_nop 0
	v_pk_fma_f32 v[92:93], v[94:95], v[74:75], v[92:93] op_sel_hi:[1,0,1]
	s_nop 0
	s_nop 0
	v_pk_mul_f32 v[94:95], v[132:133], v[92:93] op_sel:[1,1] op_sel_hi:[0,1] neg_hi:[0,1]
	v_pk_fma_f32 v[94:95], v[132:133], v[92:93], v[94:95] op_sel_hi:[1,0,1]
	ds_write_b64 v91, v[94:95] offset:5888
	v_pk_mul_f32 v[94:95], v[78:79], v[92:93] op_sel:[0,1] op_sel_hi:[1,0]
	s_nop 0
	v_pk_fma_f32 v[92:93], v[92:93], v[74:75], v[94:95] op_sel_hi:[1,0,1]
	s_nop 0
	s_nop 0
	v_pk_mul_f32 v[94:95], v[82:83], v[92:93] op_sel:[1,1] op_sel_hi:[0,1] neg_hi:[0,1]
	v_pk_fma_f32 v[82:83], v[82:83], v[92:93], v[94:95] op_sel_hi:[1,0,1]
	ds_write_b64 v90, v[82:83] offset:6144
	v_pk_mul_f32 v[82:83], v[78:79], v[92:93] op_sel:[0,1] op_sel_hi:[1,0]
	s_nop 0
	v_pk_fma_f32 v[82:83], v[92:93], v[74:75], v[82:83] op_sel_hi:[1,0,1]
	s_nop 0
	s_nop 0
	v_pk_mul_f32 v[90:91], v[148:149], v[82:83] op_sel:[1,1] op_sel_hi:[0,1] neg_hi:[0,1]
	v_pk_fma_f32 v[90:91], v[148:149], v[82:83], v[90:91] op_sel_hi:[1,0,1]
	ds_write_b64 v89, v[90:91] offset:6400
	v_pk_mul_f32 v[90:91], v[78:79], v[82:83] op_sel:[0,1] op_sel_hi:[1,0]
	s_nop 0
	v_pk_fma_f32 v[82:83], v[82:83], v[74:75], v[90:91] op_sel_hi:[1,0,1]
	s_nop 0
	s_nop 0
	v_pk_mul_f32 v[90:91], v[76:77], v[82:83] op_sel:[1,1] op_sel_hi:[0,1] neg_hi:[0,1]
	v_pk_fma_f32 v[76:77], v[76:77], v[82:83], v[90:91] op_sel_hi:[1,0,1]
	ds_write_b64 v88, v[76:77] offset:6656
	v_pk_mul_f32 v[76:77], v[78:79], v[82:83] op_sel:[0,1] op_sel_hi:[1,0]
	s_nop 0
	v_pk_fma_f32 v[76:77], v[82:83], v[74:75], v[76:77] op_sel_hi:[1,0,1]
	s_nop 0
	s_nop 0
	v_pk_mul_f32 v[82:83], v[80:81], v[76:77] op_sel:[1,1] op_sel_hi:[0,1] neg_hi:[0,1]
	v_pk_fma_f32 v[80:81], v[80:81], v[76:77], v[82:83] op_sel_hi:[1,0,1]
	ds_write_b64 v87, v[80:81] offset:6912
	v_pk_mul_f32 v[80:81], v[78:79], v[76:77] op_sel:[0,1] op_sel_hi:[1,0]
	s_nop 0
	v_pk_fma_f32 v[76:77], v[76:77], v[74:75], v[80:81] op_sel_hi:[1,0,1]
	s_nop 0
	s_nop 0
	v_pk_mul_f32 v[80:81], v[68:69], v[76:77] op_sel:[1,1] op_sel_hi:[0,1] neg_hi:[0,1]
	v_pk_fma_f32 v[68:69], v[68:69], v[76:77], v[80:81] op_sel_hi:[1,0,1]
	ds_write_b64 v86, v[68:69] offset:7168
	v_pk_mul_f32 v[68:69], v[78:79], v[76:77] op_sel:[0,1] op_sel_hi:[1,0]
	s_nop 0
	v_pk_fma_f32 v[68:69], v[76:77], v[74:75], v[68:69] op_sel_hi:[1,0,1]
	s_nop 0
	s_nop 0
	v_pk_mul_f32 v[76:77], v[72:73], v[68:69] op_sel:[1,1] op_sel_hi:[0,1] neg_hi:[0,1]
	v_pk_fma_f32 v[72:73], v[72:73], v[68:69], v[76:77] op_sel_hi:[1,0,1]
	ds_write_b64 v85, v[72:73] offset:7424
	v_pk_mul_f32 v[72:73], v[78:79], v[68:69] op_sel:[0,1] op_sel_hi:[1,0]
	s_nop 0
	v_pk_fma_f32 v[68:69], v[68:69], v[74:75], v[72:73] op_sel_hi:[1,0,1]
	s_nop 0
	s_nop 0
	v_pk_mul_f32 v[72:73], v[66:67], v[68:69] op_sel:[1,1] op_sel_hi:[0,1] neg_hi:[0,1]
	v_pk_fma_f32 v[66:67], v[66:67], v[68:69], v[72:73] op_sel_hi:[1,0,1]
	ds_write_b64 v84, v[66:67] offset:7680
	v_pk_mul_f32 v[66:67], v[78:79], v[68:69] op_sel:[0,1] op_sel_hi:[1,0]
	s_nop 0
	v_pk_fma_f32 v[66:67], v[68:69], v[74:75], v[66:67] op_sel_hi:[1,0,1]
	s_nop 0
	s_nop 0
	v_pk_mul_f32 v[68:69], v[70:71], v[66:67] op_sel:[1,1] op_sel_hi:[0,1] neg_hi:[0,1]
	v_pk_fma_f32 v[66:67], v[70:71], v[66:67], v[68:69] op_sel_hi:[1,0,1]
	ds_write_b64 v0, v[66:67]
	s_waitcnt lgkmcnt(0)
	s_barrier
	ds_read2_b64 v[66:69], v104 offset1:1
	ds_read2_b64 v[70:73], v104 offset0:2 offset1:3
	ds_read2_b64 v[74:77], v104 offset0:4 offset1:5
	ds_read2_b64 v[78:81], v104 offset0:6 offset1:7
	ds_read2_b64 v[82:85], v104 offset0:8 offset1:9
	ds_read2_b64 v[86:89], v104 offset0:10 offset1:11
	ds_read2_b64 v[90:93], v104 offset0:12 offset1:13
	ds_read2_b64 v[94:97], v104 offset0:14 offset1:15
	ds_read2_b64 v[98:101], v104 offset0:16 offset1:17
	ds_read2_b64 v[106:109], v104 offset0:18 offset1:19
	ds_read2_b64 v[110:113], v104 offset0:20 offset1:21
	ds_read2_b64 v[114:117], v104 offset0:22 offset1:23
	ds_read2_b64 v[118:121], v104 offset0:24 offset1:25
	ds_read2_b64 v[122:125], v104 offset0:26 offset1:27
	ds_read2_b64 v[126:129], v104 offset0:28 offset1:29
	ds_read2_b64 v[130:133], v104 offset0:30 offset1:31
	s_waitcnt lgkmcnt(7)
	v_pk_add_f32 v[102:103], v[66:67], v[98:99]
	v_pk_add_f32 v[66:67], v[66:67], v[98:99] neg_lo:[0,1] neg_hi:[0,1]
	v_pk_add_f32 v[98:99], v[68:69], v[100:101]
	v_pk_add_f32 v[68:69], v[68:69], v[100:101] neg_lo:[0,1] neg_hi:[0,1]
	global_load_dwordx2 v[134:135], v[2:3], off
	global_load_dwordx2 v[136:137], v[4:5], off
	global_load_dwordx2 v[138:139], v[6:7], off
	v_pk_mul_f32 v[100:101], v[68:69], s[18:19]
	global_load_dwordx2 v[148:149], v[14:15], off
	global_load_dwordx2 v[154:155], v[16:17], off
	v_pk_fma_f32 v[68:69], v[68:69], s[20:21], v[100:101] op_sel:[0,0,1] op_sel_hi:[1,0,0]
	s_waitcnt lgkmcnt(6)
	v_pk_add_f32 v[100:101], v[70:71], v[106:107]
	v_pk_add_f32 v[70:71], v[70:71], v[106:107] neg_lo:[0,1] neg_hi:[0,1]
	global_load_dwordx2 v[158:159], v[18:19], off
	v_pk_mul_f32 v[106:107], v[70:71], s[4:5]
	global_load_dwordx2 v[160:161], v[28:29], off
	global_load_dwordx2 v[164:165], v[32:33], off
	v_pk_fma_f32 v[70:71], v[70:71], s[6:7], v[106:107] op_sel:[0,0,1] op_sel_hi:[1,0,0]
	v_pk_add_f32 v[106:107], v[72:73], v[108:109]
	v_pk_add_f32 v[72:73], v[72:73], v[108:109] neg_lo:[0,1] neg_hi:[0,1]
	global_load_dwordx2 v[168:169], v[36:37], off
	v_pk_mul_f32 v[108:109], v[72:73], s[22:23]
	global_load_dwordx2 v[172:173], v[44:45], off
	v_pk_fma_f32 v[72:73], v[72:73], s[24:25], v[108:109] op_sel:[0,0,1] op_sel_hi:[1,0,0]
	s_waitcnt lgkmcnt(5)
	v_pk_add_f32 v[108:109], v[74:75], v[110:111]
	v_pk_add_f32 v[74:75], v[74:75], v[110:111] neg_lo:[0,1] neg_hi:[0,1]
	global_load_dwordx2 v[174:175], v[52:53], off
	v_pk_mul_f32 v[110:111], v[74:75], s[8:9]
	global_load_dwordx2 v[176:177], v[60:61], off
	v_pk_fma_f32 v[74:75], v[74:75], s[10:11], v[110:111] op_sel:[0,0,1] op_sel_hi:[1,0,0]
	v_pk_add_f32 v[110:111], v[76:77], v[112:113]
	v_pk_add_f32 v[76:77], v[76:77], v[112:113] neg_lo:[0,1] neg_hi:[0,1]
	s_nop 0
	v_pk_mul_f32 v[112:113], v[76:77], s[26:27]
	s_nop 0
	v_pk_fma_f32 v[76:77], v[76:77], s[0:1], v[112:113] op_sel:[0,0,1] op_sel_hi:[1,0,0]
	s_waitcnt lgkmcnt(4)
	v_pk_add_f32 v[112:113], v[78:79], v[114:115]
	v_pk_add_f32 v[78:79], v[78:79], v[114:115] neg_lo:[0,1] neg_hi:[0,1]
	s_nop 0
	v_pk_mul_f32 v[114:115], v[78:79], s[12:13]
	s_nop 0
	v_pk_fma_f32 v[78:79], v[78:79], s[14:15], v[114:115] op_sel:[0,0,1] op_sel_hi:[1,0,0]
	v_pk_add_f32 v[114:115], v[80:81], v[116:117]
	v_pk_add_f32 v[80:81], v[80:81], v[116:117] neg_lo:[0,1] neg_hi:[0,1]
	s_nop 0
	v_pk_mul_f32 v[116:117], v[80:81], s[34:35]
	s_nop 0
	v_pk_fma_f32 v[80:81], v[80:81], s[48:49], v[116:117] op_sel:[0,0,1] op_sel_hi:[1,0,0]
	s_waitcnt lgkmcnt(3)
	v_pk_add_f32 v[116:117], v[82:83], v[118:119]
	v_pk_add_f32 v[118:119], v[82:83], v[118:119] op_sel:[1,1] op_sel_hi:[0,0] neg_lo:[0,1] neg_hi:[1,0]
	s_nop 0
	v_pk_add_f32 v[82:83], v[84:85], v[120:121]
	v_pk_add_f32 v[84:85], v[84:85], v[120:121] neg_lo:[0,1] neg_hi:[0,1]
	s_nop 0
	v_pk_mul_f32 v[120:121], v[84:85], s[34:35]
	s_nop 0
	v_pk_fma_f32 v[84:85], v[84:85], s[18:19], v[120:121] op_sel:[0,0,1] op_sel_hi:[1,0,0]
	s_waitcnt lgkmcnt(2)
	v_pk_add_f32 v[120:121], v[86:87], v[122:123]
	v_pk_add_f32 v[86:87], v[86:87], v[122:123] neg_lo:[0,1] neg_hi:[0,1]
	s_nop 0
	v_pk_mul_f32 v[122:123], v[86:87], s[12:13]
	s_nop 0
	v_pk_fma_f32 v[86:87], v[86:87], s[4:5], v[122:123] op_sel:[0,0,1] op_sel_hi:[1,0,0]
	v_pk_add_f32 v[122:123], v[88:89], v[124:125]
	v_pk_add_f32 v[88:89], v[88:89], v[124:125] neg_lo:[0,1] neg_hi:[0,1]
	s_nop 0
	v_pk_mul_f32 v[124:125], v[88:89], s[26:27]
	s_nop 0
	v_pk_fma_f32 v[88:89], v[88:89], s[22:23], v[124:125] op_sel:[0,0,1] op_sel_hi:[1,0,0]
	s_waitcnt lgkmcnt(1)
	v_pk_add_f32 v[124:125], v[90:91], v[126:127]
	v_pk_add_f32 v[90:91], v[90:91], v[126:127] neg_lo:[0,1] neg_hi:[0,1]
	s_nop 0
	v_pk_mul_f32 v[126:127], v[90:91], s[8:9]
	s_nop 0
	v_pk_fma_f32 v[90:91], v[90:91], s[8:9], v[126:127] op_sel:[0,0,1] op_sel_hi:[1,0,0]
	v_pk_add_f32 v[126:127], v[92:93], v[128:129]
	v_pk_add_f32 v[92:93], v[92:93], v[128:129] neg_lo:[0,1] neg_hi:[0,1]
	s_nop 0
	v_pk_mul_f32 v[128:129], v[92:93], s[22:23]
	s_nop 0
	v_pk_fma_f32 v[92:93], v[92:93], s[26:27], v[128:129] op_sel:[0,0,1] op_sel_hi:[1,0,0]
	s_waitcnt lgkmcnt(0)
	v_pk_add_f32 v[128:129], v[94:95], v[130:131]
	v_pk_add_f32 v[94:95], v[94:95], v[130:131] neg_lo:[0,1] neg_hi:[0,1]
	s_nop 0
	v_pk_mul_f32 v[130:131], v[94:95], s[4:5]
	s_nop 0
	v_pk_fma_f32 v[94:95], v[94:95], s[12:13], v[130:131] op_sel:[0,0,1] op_sel_hi:[1,0,0]
	v_pk_add_f32 v[130:131], v[96:97], v[132:133]
	v_pk_add_f32 v[96:97], v[96:97], v[132:133] neg_lo:[0,1] neg_hi:[0,1]
	s_nop 0
	v_pk_mul_f32 v[132:133], v[96:97], s[18:19]
	s_nop 0
	v_pk_fma_f32 v[96:97], v[96:97], s[34:35], v[132:133] op_sel:[0,0,1] op_sel_hi:[1,0,0]
	v_pk_add_f32 v[132:133], v[102:103], v[116:117]
	v_pk_add_f32 v[102:103], v[102:103], v[116:117] neg_lo:[0,1] neg_hi:[0,1]
	v_pk_add_f32 v[116:117], v[98:99], v[82:83]
	v_pk_add_f32 v[82:83], v[98:99], v[82:83] neg_lo:[0,1] neg_hi:[0,1]
	s_nop 0
	v_pk_mul_f32 v[98:99], v[82:83], s[4:5]
	s_nop 0
	v_pk_fma_f32 v[82:83], v[82:83], s[6:7], v[98:99] op_sel:[0,0,1] op_sel_hi:[1,0,0]
	v_pk_add_f32 v[98:99], v[100:101], v[120:121]
	v_pk_add_f32 v[100:101], v[100:101], v[120:121] neg_lo:[0,1] neg_hi:[0,1]
	s_nop 0
	v_pk_mul_f32 v[120:121], v[100:101], s[8:9]
	s_nop 0
	v_pk_fma_f32 v[100:101], v[100:101], s[10:11], v[120:121] op_sel:[0,0,1] op_sel_hi:[1,0,0]
	v_pk_add_f32 v[120:121], v[106:107], v[122:123]
	v_pk_add_f32 v[106:107], v[106:107], v[122:123] neg_lo:[0,1] neg_hi:[0,1]
	s_nop 0
	v_pk_mul_f32 v[122:123], v[106:107], s[12:13]
	s_nop 0
	v_pk_fma_f32 v[106:107], v[106:107], s[14:15], v[122:123] op_sel:[0,0,1] op_sel_hi:[1,0,0]
	v_pk_add_f32 v[122:123], v[108:109], v[124:125]
	v_pk_add_f32 v[124:125], v[108:109], v[124:125] op_sel:[1,1] op_sel_hi:[0,0] neg_lo:[0,1] neg_hi:[1,0]
	s_nop 0
	v_pk_add_f32 v[108:109], v[110:111], v[126:127]
	v_pk_add_f32 v[110:111], v[110:111], v[126:127] neg_lo:[0,1] neg_hi:[0,1]
	s_nop 0
	v_pk_mul_f32 v[126:127], v[110:111], s[12:13]
	s_nop 0
	v_pk_fma_f32 v[110:111], v[110:111], s[4:5], v[126:127] op_sel:[0,0,1] op_sel_hi:[1,0,0]
	v_pk_add_f32 v[126:127], v[112:113], v[128:129]
	v_pk_add_f32 v[112:113], v[112:113], v[128:129] neg_lo:[0,1] neg_hi:[0,1]
	s_nop 0
	v_pk_mul_f32 v[128:129], v[112:113], s[8:9]
	s_nop 0
	v_pk_fma_f32 v[112:113], v[112:113], s[8:9], v[128:129] op_sel:[0,0,1] op_sel_hi:[1,0,0]
	v_pk_add_f32 v[128:129], v[114:115], v[130:131]
	v_pk_add_f32 v[114:115], v[114:115], v[130:131] neg_lo:[0,1] neg_hi:[0,1]
	s_nop 0
	v_pk_mul_f32 v[130:131], v[114:115], s[4:5]
	s_nop 0
	v_pk_fma_f32 v[114:115], v[114:115], s[12:13], v[130:131] op_sel:[0,0,1] op_sel_hi:[1,0,0]
	v_pk_add_f32 v[130:131], v[66:67], v[118:119]
	v_pk_add_f32 v[66:67], v[66:67], v[118:119] neg_lo:[0,1] neg_hi:[0,1]
	v_pk_add_f32 v[118:119], v[68:69], v[84:85]
	v_pk_add_f32 v[68:69], v[68:69], v[84:85] neg_lo:[0,1] neg_hi:[0,1]
	s_nop 0
	v_pk_mul_f32 v[84:85], v[68:69], s[4:5]
	s_nop 0
	v_pk_fma_f32 v[68:69], v[68:69], s[6:7], v[84:85] op_sel:[0,0,1] op_sel_hi:[1,0,0]
	v_pk_add_f32 v[84:85], v[70:71], v[86:87]
	v_pk_add_f32 v[70:71], v[70:71], v[86:87] neg_lo:[0,1] neg_hi:[0,1]
	s_nop 0
	v_pk_mul_f32 v[86:87], v[70:71], s[8:9]
	s_nop 0
	v_pk_fma_f32 v[70:71], v[70:71], s[10:11], v[86:87] op_sel:[0,0,1] op_sel_hi:[1,0,0]
	v_pk_add_f32 v[86:87], v[72:73], v[88:89]
	v_pk_add_f32 v[72:73], v[72:73], v[88:89] neg_lo:[0,1] neg_hi:[0,1]
	s_nop 0
	v_pk_mul_f32 v[88:89], v[72:73], s[12:13]
	s_nop 0
	v_pk_fma_f32 v[72:73], v[72:73], s[14:15], v[88:89] op_sel:[0,0,1] op_sel_hi:[1,0,0]
	v_pk_add_f32 v[88:89], v[74:75], v[90:91]
	v_pk_add_f32 v[90:91], v[74:75], v[90:91] op_sel:[1,1] op_sel_hi:[0,0] neg_lo:[0,1] neg_hi:[1,0]
	s_mov_b32 s15, s4
	v_pk_add_f32 v[74:75], v[76:77], v[92:93]
	v_pk_add_f32 v[76:77], v[76:77], v[92:93] neg_lo:[0,1] neg_hi:[0,1]
	s_nop 0
	v_pk_mul_f32 v[92:93], v[76:77], s[12:13]
	s_nop 0
	v_pk_fma_f32 v[76:77], v[76:77], s[4:5], v[92:93] op_sel:[0,0,1] op_sel_hi:[1,0,0]
	v_pk_add_f32 v[92:93], v[78:79], v[94:95]
	v_pk_add_f32 v[78:79], v[78:79], v[94:95] neg_lo:[0,1] neg_hi:[0,1]
	s_nop 0
	v_pk_mul_f32 v[94:95], v[78:79], s[8:9]
	s_nop 0
	v_pk_fma_f32 v[78:79], v[78:79], s[8:9], v[94:95] op_sel:[0,0,1] op_sel_hi:[1,0,0]
	v_pk_add_f32 v[94:95], v[80:81], v[96:97]
	v_pk_add_f32 v[80:81], v[80:81], v[96:97] neg_lo:[0,1] neg_hi:[0,1]
	s_nop 0
	v_pk_mul_f32 v[96:97], v[80:81], s[4:5]
	s_nop 0
	v_pk_fma_f32 v[80:81], v[80:81], s[12:13], v[96:97] op_sel:[0,0,1] op_sel_hi:[1,0,0]
	v_pk_add_f32 v[96:97], v[132:133], v[122:123]
	v_pk_add_f32 v[122:123], v[132:133], v[122:123] neg_lo:[0,1] neg_hi:[0,1]
	v_pk_add_f32 v[132:133], v[116:117], v[108:109]
	v_pk_add_f32 v[108:109], v[116:117], v[108:109] neg_lo:[0,1] neg_hi:[0,1]
	s_nop 0
	v_pk_mul_f32 v[116:117], v[108:109], s[8:9]
	s_nop 0
	v_pk_fma_f32 v[108:109], v[108:109], s[10:11], v[116:117] op_sel:[0,0,1] op_sel_hi:[1,0,0]
	v_pk_add_f32 v[116:117], v[98:99], v[126:127]
	v_pk_add_f32 v[126:127], v[98:99], v[126:127] op_sel:[1,1] op_sel_hi:[0,0] neg_lo:[0,1] neg_hi:[1,0]
	s_nop 0
	v_pk_add_f32 v[98:99], v[120:121], v[128:129]
	v_pk_add_f32 v[120:121], v[120:121], v[128:129] neg_lo:[0,1] neg_hi:[0,1]
	s_nop 0
	v_pk_mul_f32 v[128:129], v[120:121], s[8:9]
	s_nop 0
	v_pk_fma_f32 v[120:121], v[120:121], s[8:9], v[128:129] op_sel:[0,0,1] op_sel_hi:[1,0,0]
	v_pk_add_f32 v[128:129], v[102:103], v[124:125]
	v_pk_add_f32 v[102:103], v[102:103], v[124:125] neg_lo:[0,1] neg_hi:[0,1]
	v_pk_add_f32 v[124:125], v[82:83], v[110:111]
	v_pk_add_f32 v[82:83], v[82:83], v[110:111] neg_lo:[0,1] neg_hi:[0,1]
	s_nop 0
	v_pk_mul_f32 v[110:111], v[82:83], s[8:9]
	s_nop 0
	v_pk_fma_f32 v[82:83], v[82:83], s[10:11], v[110:111] op_sel:[0,0,1] op_sel_hi:[1,0,0]
	v_pk_add_f32 v[110:111], v[100:101], v[112:113]
	v_pk_add_f32 v[112:113], v[100:101], v[112:113] op_sel:[1,1] op_sel_hi:[0,0] neg_lo:[0,1] neg_hi:[1,0]
	s_nop 0
	v_pk_add_f32 v[100:101], v[106:107], v[114:115]
	v_pk_add_f32 v[106:107], v[106:107], v[114:115] neg_lo:[0,1] neg_hi:[0,1]
	s_nop 0
	v_pk_mul_f32 v[114:115], v[106:107], s[8:9]
	s_nop 0
	v_pk_fma_f32 v[106:107], v[106:107], s[8:9], v[114:115] op_sel:[0,0,1] op_sel_hi:[1,0,0]
	v_pk_add_f32 v[114:115], v[130:131], v[88:89]
	v_pk_add_f32 v[88:89], v[130:131], v[88:89] neg_lo:[0,1] neg_hi:[0,1]
	v_pk_add_f32 v[130:131], v[118:119], v[74:75]
	v_pk_add_f32 v[74:75], v[118:119], v[74:75] neg_lo:[0,1] neg_hi:[0,1]
	s_nop 0
	v_pk_mul_f32 v[118:119], v[74:75], s[8:9]
	s_nop 0
	v_pk_fma_f32 v[74:75], v[74:75], s[10:11], v[118:119] op_sel:[0,0,1] op_sel_hi:[1,0,0]
	v_pk_add_f32 v[118:119], v[84:85], v[92:93]
	v_pk_add_f32 v[92:93], v[84:85], v[92:93] op_sel:[1,1] op_sel_hi:[0,0] neg_lo:[0,1] neg_hi:[1,0]
	s_nop 0
	v_pk_add_f32 v[84:85], v[86:87], v[94:95]
	v_pk_add_f32 v[86:87], v[86:87], v[94:95] neg_lo:[0,1] neg_hi:[0,1]
	v_pk_add_f32 v[140:141], v[88:89], v[92:93]
	v_pk_mul_f32 v[94:95], v[86:87], s[8:9]
	v_pk_add_f32 v[88:89], v[88:89], v[92:93] neg_lo:[0,1] neg_hi:[0,1]
	v_pk_fma_f32 v[86:87], v[86:87], s[8:9], v[94:95] op_sel:[0,0,1] op_sel_hi:[1,0,0]
	v_pk_add_f32 v[94:95], v[66:67], v[90:91]
	v_pk_add_f32 v[66:67], v[66:67], v[90:91] neg_lo:[0,1] neg_hi:[0,1]
	v_pk_add_f32 v[90:91], v[68:69], v[76:77]
	v_pk_add_f32 v[68:69], v[68:69], v[76:77] neg_lo:[0,1] neg_hi:[0,1]
	v_pk_add_f32 v[92:93], v[74:75], v[86:87]
	v_pk_mul_f32 v[76:77], v[68:69], s[8:9]
	v_pk_add_f32 v[142:143], v[74:75], v[86:87] op_sel:[1,1] op_sel_hi:[0,0] neg_lo:[0,1] neg_hi:[1,0]
	v_pk_fma_f32 v[68:69], v[68:69], s[10:11], v[76:77] op_sel:[0,0,1] op_sel_hi:[1,0,0]
	v_pk_add_f32 v[76:77], v[70:71], v[78:79]
	v_pk_add_f32 v[78:79], v[70:71], v[78:79] op_sel:[1,1] op_sel_hi:[0,0] neg_lo:[0,1] neg_hi:[1,0]
	global_load_dwordx2 v[86:87], v[10:11], off
	v_pk_add_f32 v[70:71], v[72:73], v[80:81]
	v_pk_add_f32 v[72:73], v[72:73], v[80:81] neg_lo:[0,1] neg_hi:[0,1]
	v_pk_mul_f32 v[80:81], v[72:73], s[8:9]
	v_pk_fma_f32 v[72:73], v[72:73], s[8:9], v[80:81] op_sel:[0,0,1] op_sel_hi:[1,0,0]
	v_pk_add_f32 v[80:81], v[96:97], v[116:117]
	v_pk_add_f32 v[96:97], v[96:97], v[116:117] neg_lo:[0,1] neg_hi:[0,1]
	v_pk_add_f32 v[116:117], v[132:133], v[98:99]
	v_pk_add_f32 v[132:133], v[132:133], v[98:99] op_sel:[1,1] op_sel_hi:[0,0] neg_lo:[0,1] neg_hi:[1,0]
	v_pk_add_f32 v[74:75], v[94:95], v[76:77]
	v_pk_add_f32 v[98:99], v[122:123], v[126:127]
	v_pk_add_f32 v[122:123], v[122:123], v[126:127] neg_lo:[0,1] neg_hi:[0,1]
	v_pk_add_f32 v[126:127], v[108:109], v[120:121]
	v_pk_add_f32 v[120:121], v[108:109], v[120:121] op_sel:[1,1] op_sel_hi:[0,0] neg_lo:[0,1] neg_hi:[1,0]
	v_pk_add_f32 v[76:77], v[94:95], v[76:77] neg_lo:[0,1] neg_hi:[0,1]
	v_pk_add_f32 v[108:109], v[128:129], v[110:111]
	v_pk_add_f32 v[110:111], v[128:129], v[110:111] neg_lo:[0,1] neg_hi:[0,1]
	v_pk_add_f32 v[128:129], v[124:125], v[100:101]
	v_pk_add_f32 v[124:125], v[124:125], v[100:101] op_sel:[1,1] op_sel_hi:[0,0] neg_lo:[0,1] neg_hi:[1,0]
	global_load_dwordx2 v[94:95], v[12:13], off
	v_pk_add_f32 v[100:101], v[102:103], v[112:113]
	v_pk_add_f32 v[102:103], v[102:103], v[112:113] neg_lo:[0,1] neg_hi:[0,1]
	v_pk_add_f32 v[112:113], v[82:83], v[106:107]
	v_pk_add_f32 v[106:107], v[82:83], v[106:107] op_sel:[1,1] op_sel_hi:[0,0] neg_lo:[0,1] neg_hi:[1,0]
	v_pk_add_f32 v[146:147], v[66:67], v[78:79]
	v_pk_add_f32 v[82:83], v[114:115], v[118:119]
	v_pk_add_f32 v[114:115], v[114:115], v[118:119] neg_lo:[0,1] neg_hi:[0,1]
	v_pk_add_f32 v[118:119], v[130:131], v[84:85]
	v_pk_add_f32 v[130:131], v[130:131], v[84:85] op_sel:[1,1] op_sel_hi:[0,0] neg_lo:[0,1] neg_hi:[1,0]
	v_pk_add_f32 v[78:79], v[66:67], v[78:79] neg_lo:[0,1] neg_hi:[0,1]
	global_load_dwordx2 v[84:85], v[8:9], off
	v_pk_add_f32 v[152:153], v[68:69], v[72:73] op_sel:[1,1] op_sel_hi:[0,0] neg_lo:[0,1] neg_hi:[1,0]
	v_pk_add_f32 v[150:151], v[68:69], v[72:73]
	v_pk_add_f32 v[156:157], v[80:81], v[116:117]
	v_pk_add_f32 v[80:81], v[80:81], v[116:117] neg_lo:[0,1] neg_hi:[0,1]
	v_pk_add_f32 v[116:117], v[96:97], v[132:133]
	v_pk_add_f32 v[68:69], v[96:97], v[132:133] neg_lo:[0,1] neg_hi:[0,1]
	v_pk_add_f32 v[96:97], v[98:99], v[126:127]
	v_pk_add_f32 v[98:99], v[98:99], v[126:127] neg_lo:[0,1] neg_hi:[0,1]
	v_pk_add_f32 v[126:127], v[122:123], v[120:121]
	v_pk_add_f32 v[66:67], v[122:123], v[120:121] neg_lo:[0,1] neg_hi:[0,1]
	global_load_dwordx2 v[120:121], v[20:21], off
	v_pk_add_f32 v[122:123], v[108:109], v[128:129]
	v_pk_add_f32 v[108:109], v[108:109], v[128:129] neg_lo:[0,1] neg_hi:[0,1]
	v_pk_add_f32 v[128:129], v[110:111], v[124:125]
	v_pk_add_f32 v[72:73], v[110:111], v[124:125] neg_lo:[0,1] neg_hi:[0,1]
	global_load_dwordx2 v[110:111], v[22:23], off
	v_pk_add_f32 v[144:145], v[90:91], v[70:71]
	v_pk_add_f32 v[90:91], v[90:91], v[70:71] op_sel:[1,1] op_sel_hi:[0,0] neg_lo:[0,1] neg_hi:[1,0]
	v_pk_add_f32 v[124:125], v[100:101], v[112:113]
	v_pk_add_f32 v[100:101], v[100:101], v[112:113] neg_lo:[0,1] neg_hi:[0,1]
	v_pk_add_f32 v[112:113], v[102:103], v[106:107]
	v_pk_add_f32 v[70:71], v[102:103], v[106:107] neg_lo:[0,1] neg_hi:[0,1]
	global_load_dwordx2 v[102:103], v[24:25], off
	v_pk_add_f32 v[106:107], v[82:83], v[118:119]
	v_pk_add_f32 v[82:83], v[82:83], v[118:119] neg_lo:[0,1] neg_hi:[0,1]
	v_pk_add_f32 v[118:119], v[114:115], v[130:131]
	v_pk_add_f32 v[114:115], v[114:115], v[130:131] neg_lo:[0,1] neg_hi:[0,1]
	global_load_dwordx2 v[130:131], v[26:27], off
	v_pk_add_f32 v[162:163], v[76:77], v[90:91]
	v_pk_add_f32 v[76:77], v[76:77], v[90:91] neg_lo:[0,1] neg_hi:[0,1]
	v_pk_add_f32 v[90:91], v[146:147], v[150:151]
	v_pk_add_f32 v[146:147], v[146:147], v[150:151] neg_lo:[0,1] neg_hi:[0,1]
	v_pk_add_f32 v[150:151], v[78:79], v[152:153]
	v_pk_add_f32 v[78:79], v[78:79], v[152:153] neg_lo:[0,1] neg_hi:[0,1]
	global_load_dwordx2 v[152:153], v[34:35], off
	s_waitcnt vmcnt(19)
	v_pk_mul_f32 v[166:167], v[156:157], v[134:135] op_sel:[1,1] op_sel_hi:[0,1] neg_lo:[0,1]
	v_pk_add_f32 v[132:133], v[140:141], v[92:93]
	v_pk_fma_f32 v[134:135], v[156:157], v[134:135], v[166:167] op_sel_hi:[1,0,1]
	s_waitcnt vmcnt(18)
	global_load_dwordx2 v[166:167], v[38:39], off
	v_pk_mul_f32 v[156:157], v[106:107], v[136:137] op_sel:[1,1] op_sel_hi:[0,1] neg_lo:[0,1]
	v_pk_add_f32 v[92:93], v[140:141], v[92:93] neg_lo:[0,1] neg_hi:[0,1]
	v_pk_fma_f32 v[106:107], v[106:107], v[136:137], v[156:157] op_sel_hi:[1,0,1]
	s_waitcnt vmcnt(18)
	global_load_dwordx2 v[156:157], v[40:41], off
	v_pk_mul_f32 v[136:137], v[122:123], v[138:139] op_sel:[1,1] op_sel_hi:[0,1] neg_lo:[0,1]
	v_pk_add_f32 v[140:141], v[88:89], v[142:143]
	v_pk_fma_f32 v[122:123], v[122:123], v[138:139], v[136:137] op_sel_hi:[1,0,1]
	global_load_dwordx2 v[136:137], v[42:43], off
	v_pk_add_f32 v[88:89], v[88:89], v[142:143] neg_lo:[0,1] neg_hi:[0,1]
	v_pk_add_f32 v[142:143], v[74:75], v[144:145]
	v_pk_add_f32 v[74:75], v[74:75], v[144:145] neg_lo:[0,1] neg_hi:[0,1]
	global_load_dwordx2 v[144:145], v[30:31], off
	s_mov_b32 s11, s8
	s_waitcnt vmcnt(9)
	v_pk_mul_f32 v[138:139], v[142:143], v[84:85] op_sel:[1,1] op_sel_hi:[0,1] neg_lo:[0,1]
	s_nop 0
	v_pk_fma_f32 v[84:85], v[142:143], v[84:85], v[138:139] op_sel_hi:[1,0,1]
	global_load_dwordx2 v[142:143], v[46:47], off
	v_pk_mul_f32 v[138:139], v[96:97], v[86:87] op_sel:[1,1] op_sel_hi:[0,1] neg_lo:[0,1]
	s_nop 0
	v_pk_fma_f32 v[86:87], v[96:97], v[86:87], v[138:139] op_sel_hi:[1,0,1]
	global_load_dwordx2 v[138:139], v[48:49], off
	v_pk_mul_f32 v[96:97], v[132:133], v[94:95] op_sel:[1,1] op_sel_hi:[0,1] neg_lo:[0,1]
	s_nop 0
	v_pk_fma_f32 v[94:95], v[132:133], v[94:95], v[96:97] op_sel_hi:[1,0,1]
	global_load_dwordx2 v[96:97], v[50:51], off
	v_pk_mul_f32 v[132:133], v[124:125], v[148:149] op_sel:[1,1] op_sel_hi:[0,1] neg_lo:[0,1]
	s_nop 0
	v_pk_fma_f32 v[124:125], v[124:125], v[148:149], v[132:133] op_sel_hi:[1,0,1]
	global_load_dwordx2 v[148:149], v[54:55], off
	v_pk_mul_f32 v[132:133], v[90:91], v[154:155] op_sel:[1,1] op_sel_hi:[0,1] neg_lo:[0,1]
	s_nop 0
	v_pk_fma_f32 v[90:91], v[90:91], v[154:155], v[132:133] op_sel_hi:[1,0,1]
	global_load_dwordx2 v[154:155], v[56:57], off
	v_pk_mul_f32 v[132:133], v[116:117], v[158:159] op_sel:[1,1] op_sel_hi:[0,1] neg_lo:[0,1]
	v_pk_fma_f32 v[116:117], v[116:117], v[158:159], v[132:133] op_sel_hi:[1,0,1]
	global_load_dwordx2 v[132:133], v[58:59], off
	s_waitcnt vmcnt(14)
	v_pk_mul_f32 v[158:159], v[118:119], v[120:121] op_sel:[1,1] op_sel_hi:[0,1] neg_lo:[0,1]
	v_pk_fma_f32 v[118:119], v[118:119], v[120:121], v[158:159] op_sel_hi:[1,0,1]
	s_waitcnt vmcnt(13)
	global_load_dwordx2 v[158:159], v[62:63], off
	v_pk_mul_f32 v[120:121], v[128:129], v[110:111] op_sel:[1,1] op_sel_hi:[0,1] neg_lo:[0,1]
	v_pk_fma_f32 v[110:111], v[128:129], v[110:111], v[120:121] op_sel_hi:[1,0,1]
	global_load_dwordx2 v[128:129], v[64:65], off
	s_waitcnt vmcnt(14)
	v_pk_mul_f32 v[120:121], v[162:163], v[102:103] op_sel:[1,1] op_sel_hi:[0,1] neg_lo:[0,1]
	v_mov_b32 v0, 0
	s_nop 0
	v_pk_fma_f32 v[102:103], v[162:163], v[102:103], v[120:121] op_sel_hi:[1,0,1]
	s_waitcnt vmcnt(13)
	v_pk_mul_f32 v[120:121], v[126:127], v[130:131] op_sel:[1,1] op_sel_hi:[0,1] neg_lo:[0,1]
	v_pk_fma_f32 v[120:121], v[126:127], v[130:131], v[120:121] op_sel_hi:[1,0,1]
	v_pk_mul_f32 v[126:127], v[140:141], v[160:161] op_sel:[1,1] op_sel_hi:[0,1] neg_lo:[0,1]
	v_pk_fma_f32 v[126:127], v[140:141], v[160:161], v[126:127] op_sel_hi:[1,0,1]
	s_waitcnt vmcnt(12)
	v_pk_mul_f32 v[140:141], v[80:81], v[152:153] op_sel:[1,1] op_sel_hi:[0,1] neg_lo:[0,1]
	v_pk_fma_f32 v[80:81], v[80:81], v[152:153], v[140:141] op_sel_hi:[1,0,1]
	v_pk_mul_f32 v[140:141], v[82:83], v[168:169] op_sel:[1,1] op_sel_hi:[0,1] neg_lo:[0,1]
	v_pk_fma_f32 v[82:83], v[82:83], v[168:169], v[140:141] op_sel_hi:[1,0,1]
	s_waitcnt vmcnt(11)
	v_pk_mul_f32 v[140:141], v[108:109], v[166:167] op_sel:[1,1] op_sel_hi:[0,1] neg_lo:[0,1]
	v_pk_fma_f32 v[108:109], v[108:109], v[166:167], v[140:141] op_sel_hi:[1,0,1]
	s_waitcnt vmcnt(10)
	v_pk_mul_f32 v[140:141], v[74:75], v[156:157] op_sel:[1,1] op_sel_hi:[0,1] neg_lo:[0,1]
	v_pk_fma_f32 v[74:75], v[74:75], v[156:157], v[140:141] op_sel_hi:[1,0,1]
	s_waitcnt vmcnt(9)
	v_pk_mul_f32 v[140:141], v[98:99], v[136:137] op_sel:[1,1] op_sel_hi:[0,1] neg_lo:[0,1]
	v_pk_fma_f32 v[98:99], v[98:99], v[136:137], v[140:141] op_sel_hi:[1,0,1]
	v_pk_mul_f32 v[136:137], v[92:93], v[172:173] op_sel:[1,1] op_sel_hi:[0,1] neg_lo:[0,1]
	v_pk_fma_f32 v[92:93], v[92:93], v[172:173], v[136:137] op_sel_hi:[1,0,1]
	s_waitcnt vmcnt(8)
	v_pk_mul_f32 v[130:131], v[112:113], v[144:145] op_sel:[1,1] op_sel_hi:[0,1] neg_lo:[0,1]
	v_pk_fma_f32 v[112:113], v[112:113], v[144:145], v[130:131] op_sel_hi:[1,0,1]
	s_waitcnt vmcnt(7)
	v_pk_mul_f32 v[136:137], v[100:101], v[142:143] op_sel:[1,1] op_sel_hi:[0,1] neg_lo:[0,1]
	v_pk_fma_f32 v[100:101], v[100:101], v[142:143], v[136:137] op_sel_hi:[1,0,1]
	v_xor_b32_e32 v130, 0x80000000, v165
	s_waitcnt vmcnt(6)
	v_pk_mul_f32 v[136:137], v[146:147], v[138:139] op_sel:[1,1] op_sel_hi:[0,1] neg_lo:[0,1]
	v_pk_fma_f32 v[136:137], v[146:147], v[138:139], v[136:137] op_sel_hi:[1,0,1]
	v_mov_b32_e32 v131, v165
	s_waitcnt vmcnt(5)
	v_pk_mul_f32 v[138:139], v[68:69], v[96:97] op_sel:[1,1] op_sel_hi:[0,1] neg_lo:[0,1]
	v_pk_fma_f32 v[68:69], v[68:69], v[96:97], v[138:139] op_sel_hi:[1,0,1]
	v_pk_mul_f32 v[96:97], v[114:115], v[174:175] op_sel:[1,1] op_sel_hi:[0,1] neg_lo:[0,1]
	v_pk_fma_f32 v[96:97], v[114:115], v[174:175], v[96:97] op_sel_hi:[1,0,1]
	s_waitcnt vmcnt(4)
	v_pk_mul_f32 v[114:115], v[72:73], v[148:149] op_sel:[1,1] op_sel_hi:[0,1] neg_lo:[0,1]
	v_pk_fma_f32 v[72:73], v[72:73], v[148:149], v[114:115] op_sel_hi:[1,0,1]
	v_pk_mul_f32 v[130:131], v[150:151], v[130:131] op_sel:[1,0] op_sel_hi:[0,1]
	s_waitcnt vmcnt(3)
	v_pk_mul_f32 v[114:115], v[76:77], v[154:155] op_sel:[1,1] op_sel_hi:[0,1] neg_lo:[0,1]
	v_pk_fma_f32 v[76:77], v[76:77], v[154:155], v[114:115] op_sel_hi:[1,0,1]
	s_waitcnt vmcnt(2)
	v_pk_mul_f32 v[114:115], v[66:67], v[132:133] op_sel:[1,1] op_sel_hi:[0,1] neg_lo:[0,1]
	v_pk_fma_f32 v[66:67], v[66:67], v[132:133], v[114:115] op_sel_hi:[1,0,1]
	v_pk_mul_f32 v[114:115], v[88:89], v[176:177] op_sel:[1,1] op_sel_hi:[0,1] neg_lo:[0,1]
	v_pk_fma_f32 v[88:89], v[88:89], v[176:177], v[114:115] op_sel_hi:[1,0,1]
	s_waitcnt vmcnt(1)
	v_pk_mul_f32 v[114:115], v[70:71], v[158:159] op_sel:[1,1] op_sel_hi:[0,1] neg_lo:[0,1]
	v_pk_fma_f32 v[70:71], v[70:71], v[158:159], v[114:115] op_sel_hi:[1,0,1]
	s_waitcnt vmcnt(0)
	v_pk_mul_f32 v[114:115], v[78:79], v[128:129] op_sel:[1,1] op_sel_hi:[0,1] neg_lo:[0,1]
	v_pk_fma_f32 v[78:79], v[78:79], v[128:129], v[114:115] op_sel_hi:[1,0,1]
	v_pk_add_f32 v[128:129], v[106:107], v[82:83]
	v_pk_add_f32 v[82:83], v[106:107], v[82:83] neg_lo:[0,1] neg_hi:[0,1]
	v_pk_fma_f32 v[130:131], v[150:151], v[164:165], v[130:131] op_sel_hi:[1,0,1]
	v_pk_mul_f32 v[106:107], v[82:83], s[50:51]
	v_pk_add_f32 v[114:115], v[134:135], v[80:81]
	v_pk_fma_f32 v[82:83], v[82:83], s[20:21], v[106:107] op_sel:[0,0,1] op_sel_hi:[1,0,0]
	v_pk_add_f32 v[106:107], v[122:123], v[108:109]
	v_pk_add_f32 v[108:109], v[122:123], v[108:109] neg_lo:[0,1] neg_hi:[0,1]
	s_mov_b32 s21, s34
	v_pk_mul_f32 v[122:123], v[108:109], s[14:15]
	v_pk_add_f32 v[80:81], v[134:135], v[80:81] neg_lo:[0,1] neg_hi:[0,1]
	v_pk_fma_f32 v[108:109], v[108:109], s[6:7], v[122:123] op_sel:[0,0,1] op_sel_hi:[1,0,0]
	v_pk_add_f32 v[122:123], v[84:85], v[74:75]
	v_pk_add_f32 v[74:75], v[84:85], v[74:75] neg_lo:[0,1] neg_hi:[0,1]
	s_mov_b32 s7, s12
	v_pk_mul_f32 v[84:85], v[74:75], s[52:53]
	v_add_u32_e32 v0, v0, v170
	v_pk_fma_f32 v[74:75], v[74:75], s[24:25], v[84:85] op_sel:[0,0,1] op_sel_hi:[1,0,0]
	v_pk_add_f32 v[84:85], v[86:87], v[98:99]
	v_pk_add_f32 v[86:87], v[86:87], v[98:99] neg_lo:[0,1] neg_hi:[0,1]
	s_mov_b32 s25, s26
	v_pk_mul_f32 v[98:99], v[86:87], s[10:11]
	v_lshlrev_b32_e32 v105, 5, v0
	v_pk_fma_f32 v[86:87], v[86:87], s[10:11], v[98:99] op_sel:[0,0,1] op_sel_hi:[1,0,0]
	v_pk_add_f32 v[98:99], v[94:95], v[92:93]
	v_pk_add_f32 v[92:93], v[94:95], v[92:93] neg_lo:[0,1] neg_hi:[0,1]
	s_nop 0
	v_pk_mul_f32 v[94:95], v[92:93], s[24:25]
	s_nop 0
	v_pk_fma_f32 v[92:93], v[92:93], s[0:1], v[94:95] op_sel:[0,0,1] op_sel_hi:[1,0,0]
	v_pk_add_f32 v[94:95], v[124:125], v[100:101]
	v_pk_add_f32 v[100:101], v[124:125], v[100:101] neg_lo:[0,1] neg_hi:[0,1]
	s_nop 0
	v_pk_mul_f32 v[124:125], v[100:101], s[6:7]
	s_nop 0
	v_pk_fma_f32 v[100:101], v[100:101], s[14:15], v[124:125] op_sel:[0,0,1] op_sel_hi:[1,0,0]
	v_pk_add_f32 v[124:125], v[90:91], v[136:137]
	v_pk_add_f32 v[90:91], v[90:91], v[136:137] neg_lo:[0,1] neg_hi:[0,1]
	s_nop 0
	v_pk_mul_f32 v[132:133], v[90:91], s[20:21]
	s_nop 0
	v_pk_fma_f32 v[90:91], v[90:91], s[48:49], v[132:133] op_sel:[0,0,1] op_sel_hi:[1,0,0]
	v_pk_add_f32 v[132:133], v[116:117], v[68:69]
	v_pk_add_f32 v[116:117], v[116:117], v[68:69] op_sel:[1,1] op_sel_hi:[0,0] neg_lo:[1,0] neg_hi:[0,1]
	s_nop 0
	v_pk_add_f32 v[68:69], v[118:119], v[96:97]
	v_pk_add_f32 v[96:97], v[118:119], v[96:97] neg_lo:[0,1] neg_hi:[0,1]
	s_nop 0
	v_pk_mul_f32 v[118:119], v[96:97], s[20:21]
	s_nop 0
	v_pk_fma_f32 v[96:97], v[96:97], s[18:19], v[118:119] op_sel:[0,0,1] op_sel_hi:[1,0,0]
	v_pk_add_f32 v[118:119], v[110:111], v[72:73]
	v_pk_add_f32 v[72:73], v[110:111], v[72:73] neg_lo:[0,1] neg_hi:[0,1]
	s_nop 0
	v_pk_mul_f32 v[110:111], v[72:73], s[6:7]
	s_nop 0
	v_pk_fma_f32 v[72:73], v[72:73], s[4:5], v[110:111] op_sel:[0,0,1] op_sel_hi:[1,0,0]
	v_pk_add_f32 v[110:111], v[102:103], v[76:77]
	v_pk_add_f32 v[76:77], v[102:103], v[76:77] neg_lo:[0,1] neg_hi:[0,1]
	s_nop 0
	v_pk_mul_f32 v[102:103], v[76:77], s[24:25]
	s_nop 0
	v_pk_fma_f32 v[76:77], v[76:77], s[22:23], v[102:103] op_sel:[0,0,1] op_sel_hi:[1,0,0]
	v_pk_add_f32 v[102:103], v[120:121], v[66:67]
	v_pk_add_f32 v[66:67], v[120:121], v[66:67] neg_lo:[0,1] neg_hi:[0,1]
	s_nop 0
	v_pk_mul_f32 v[120:121], v[66:67], s[10:11]
	s_nop 0
	v_pk_fma_f32 v[66:67], v[66:67], s[8:9], v[120:121] op_sel:[0,0,1] op_sel_hi:[1,0,0]
	v_pk_add_f32 v[120:121], v[126:127], v[88:89]
	v_pk_add_f32 v[88:89], v[126:127], v[88:89] neg_lo:[0,1] neg_hi:[0,1]
	s_nop 0
	v_pk_mul_f32 v[126:127], v[88:89], s[52:53]
	s_nop 0
	v_pk_fma_f32 v[88:89], v[88:89], s[26:27], v[126:127] op_sel:[0,0,1] op_sel_hi:[1,0,0]
	v_pk_add_f32 v[126:127], v[112:113], v[70:71]
	v_pk_add_f32 v[70:71], v[112:113], v[70:71] neg_lo:[0,1] neg_hi:[0,1]
	s_nop 0
	v_pk_mul_f32 v[112:113], v[70:71], s[14:15]
	s_nop 0
	v_pk_fma_f32 v[70:71], v[70:71], s[12:13], v[112:113] op_sel:[0,0,1] op_sel_hi:[1,0,0]
	v_pk_add_f32 v[112:113], v[130:131], v[78:79]
	v_pk_add_f32 v[78:79], v[130:131], v[78:79] neg_lo:[0,1] neg_hi:[0,1]
	s_nop 0
	v_pk_mul_f32 v[130:131], v[78:79], s[50:51]
	s_nop 0
	v_pk_fma_f32 v[78:79], v[78:79], s[34:35], v[130:131] op_sel:[0,0,1] op_sel_hi:[1,0,0]
	v_pk_add_f32 v[130:131], v[114:115], v[132:133]
	v_pk_add_f32 v[114:115], v[114:115], v[132:133] neg_lo:[0,1] neg_hi:[0,1]
	v_pk_add_f32 v[132:133], v[128:129], v[68:69]
	v_pk_add_f32 v[68:69], v[128:129], v[68:69] neg_lo:[0,1] neg_hi:[0,1]
	s_nop 0
	v_pk_mul_f32 v[128:129], v[68:69], s[14:15]
	s_nop 0
	v_pk_fma_f32 v[68:69], v[68:69], s[6:7], v[128:129] op_sel:[0,0,1] op_sel_hi:[1,0,0]
	v_pk_add_f32 v[128:129], v[106:107], v[118:119]
	v_pk_add_f32 v[106:107], v[106:107], v[118:119] neg_lo:[0,1] neg_hi:[0,1]
	s_nop 0
	v_pk_mul_f32 v[118:119], v[106:107], s[10:11]
	s_nop 0
	v_pk_fma_f32 v[106:107], v[106:107], s[10:11], v[118:119] op_sel:[0,0,1] op_sel_hi:[1,0,0]
	v_pk_add_f32 v[118:119], v[122:123], v[110:111]
	v_pk_add_f32 v[110:111], v[122:123], v[110:111] neg_lo:[0,1] neg_hi:[0,1]
	s_nop 0
	v_pk_mul_f32 v[122:123], v[110:111], s[6:7]
	s_nop 0
	v_pk_fma_f32 v[110:111], v[110:111], s[14:15], v[122:123] op_sel:[0,0,1] op_sel_hi:[1,0,0]
	v_pk_add_f32 v[122:123], v[84:85], v[102:103]
	v_pk_add_f32 v[102:103], v[84:85], v[102:103] op_sel:[1,1] op_sel_hi:[0,0] neg_lo:[1,0] neg_hi:[0,1]
	s_nop 0
	v_pk_add_f32 v[84:85], v[98:99], v[120:121]
	v_pk_add_f32 v[98:99], v[98:99], v[120:121] neg_lo:[0,1] neg_hi:[0,1]
	s_nop 0
	v_pk_mul_f32 v[120:121], v[98:99], s[6:7]
	s_nop 0
	v_pk_fma_f32 v[98:99], v[98:99], s[4:5], v[120:121] op_sel:[0,0,1] op_sel_hi:[1,0,0]
	v_pk_add_f32 v[120:121], v[94:95], v[126:127]
	v_pk_add_f32 v[94:95], v[94:95], v[126:127] neg_lo:[0,1] neg_hi:[0,1]
	s_nop 0
	v_pk_mul_f32 v[126:127], v[94:95], s[10:11]
	s_nop 0
	v_pk_fma_f32 v[94:95], v[94:95], s[8:9], v[126:127] op_sel:[0,0,1] op_sel_hi:[1,0,0]
	v_pk_add_f32 v[126:127], v[124:125], v[112:113]
	v_pk_add_f32 v[112:113], v[124:125], v[112:113] neg_lo:[0,1] neg_hi:[0,1]
	s_nop 0
	v_pk_mul_f32 v[124:125], v[112:113], s[14:15]
	s_nop 0
	v_pk_fma_f32 v[112:113], v[112:113], s[12:13], v[124:125] op_sel:[0,0,1] op_sel_hi:[1,0,0]
	v_pk_add_f32 v[124:125], v[80:81], v[116:117]
	v_pk_add_f32 v[80:81], v[80:81], v[116:117] neg_lo:[0,1] neg_hi:[0,1]
	v_pk_add_f32 v[116:117], v[82:83], v[96:97]
	v_pk_add_f32 v[82:83], v[82:83], v[96:97] neg_lo:[0,1] neg_hi:[0,1]
	s_nop 0
	v_pk_mul_f32 v[96:97], v[82:83], s[14:15]
	s_nop 0
	v_pk_fma_f32 v[82:83], v[82:83], s[6:7], v[96:97] op_sel:[0,0,1] op_sel_hi:[1,0,0]
	v_pk_add_f32 v[96:97], v[108:109], v[72:73]
	v_pk_add_f32 v[72:73], v[108:109], v[72:73] neg_lo:[0,1] neg_hi:[0,1]
	s_nop 0
	v_pk_mul_f32 v[108:109], v[72:73], s[10:11]
	s_nop 0
	v_pk_fma_f32 v[72:73], v[72:73], s[10:11], v[108:109] op_sel:[0,0,1] op_sel_hi:[1,0,0]
	v_pk_add_f32 v[108:109], v[74:75], v[76:77]
	v_pk_add_f32 v[74:75], v[74:75], v[76:77] neg_lo:[0,1] neg_hi:[0,1]
	s_nop 0
	v_pk_mul_f32 v[76:77], v[74:75], s[6:7]
	s_nop 0
	v_pk_fma_f32 v[74:75], v[74:75], s[14:15], v[76:77] op_sel:[0,0,1] op_sel_hi:[1,0,0]
	v_pk_add_f32 v[76:77], v[86:87], v[66:67]
	v_pk_add_f32 v[86:87], v[86:87], v[66:67] op_sel:[1,1] op_sel_hi:[0,0] neg_lo:[1,0] neg_hi:[0,1]
	s_nop 0
	v_pk_add_f32 v[66:67], v[92:93], v[88:89]
	v_pk_add_f32 v[88:89], v[92:93], v[88:89] neg_lo:[0,1] neg_hi:[0,1]
	s_nop 0
	v_pk_mul_f32 v[92:93], v[88:89], s[6:7]
	s_nop 0
	v_pk_fma_f32 v[88:89], v[88:89], s[4:5], v[92:93] op_sel:[0,0,1] op_sel_hi:[1,0,0]
	v_pk_add_f32 v[92:93], v[100:101], v[70:71]
	v_pk_add_f32 v[70:71], v[100:101], v[70:71] neg_lo:[0,1] neg_hi:[0,1]
	s_nop 0
	v_pk_mul_f32 v[100:101], v[70:71], s[10:11]
	s_nop 0
	v_pk_fma_f32 v[70:71], v[70:71], s[8:9], v[100:101] op_sel:[0,0,1] op_sel_hi:[1,0,0]
	v_pk_add_f32 v[100:101], v[90:91], v[78:79]
	v_pk_add_f32 v[78:79], v[90:91], v[78:79] neg_lo:[0,1] neg_hi:[0,1]
	s_nop 0
	v_pk_mul_f32 v[90:91], v[78:79], s[14:15]
	s_nop 0
	v_pk_fma_f32 v[78:79], v[78:79], s[12:13], v[90:91] op_sel:[0,0,1] op_sel_hi:[1,0,0]
	v_pk_add_f32 v[90:91], v[130:131], v[122:123]
	v_pk_add_f32 v[122:123], v[130:131], v[122:123] neg_lo:[0,1] neg_hi:[0,1]
	v_pk_add_f32 v[130:131], v[132:133], v[84:85]
	v_pk_add_f32 v[84:85], v[132:133], v[84:85] neg_lo:[0,1] neg_hi:[0,1]
	s_nop 0
	v_pk_mul_f32 v[132:133], v[84:85], s[10:11]
	s_nop 0
	v_pk_fma_f32 v[84:85], v[84:85], s[10:11], v[132:133] op_sel:[0,0,1] op_sel_hi:[1,0,0]
	v_pk_add_f32 v[132:133], v[128:129], v[120:121]
	v_pk_add_f32 v[128:129], v[128:129], v[120:121] op_sel:[1,1] op_sel_hi:[0,0] neg_lo:[1,0] neg_hi:[0,1]
	s_nop 0
	v_pk_add_f32 v[120:121], v[118:119], v[126:127]
	v_pk_add_f32 v[118:119], v[118:119], v[126:127] neg_lo:[0,1] neg_hi:[0,1]
	s_nop 0
	v_pk_mul_f32 v[126:127], v[118:119], s[10:11]
	s_nop 0
	v_pk_fma_f32 v[118:119], v[118:119], s[8:9], v[126:127] op_sel:[0,0,1] op_sel_hi:[1,0,0]
	v_pk_add_f32 v[126:127], v[114:115], v[102:103]
	v_pk_add_f32 v[102:103], v[114:115], v[102:103] neg_lo:[0,1] neg_hi:[0,1]
	v_pk_add_f32 v[114:115], v[68:69], v[98:99]
	v_pk_add_f32 v[68:69], v[68:69], v[98:99] neg_lo:[0,1] neg_hi:[0,1]
	s_nop 0
	v_pk_mul_f32 v[98:99], v[68:69], s[10:11]
	s_nop 0
	v_pk_fma_f32 v[68:69], v[68:69], s[10:11], v[98:99] op_sel:[0,0,1] op_sel_hi:[1,0,0]
	v_pk_add_f32 v[98:99], v[106:107], v[94:95]
	v_pk_add_f32 v[106:107], v[106:107], v[94:95] op_sel:[1,1] op_sel_hi:[0,0] neg_lo:[1,0] neg_hi:[0,1]
	s_nop 0
	v_pk_add_f32 v[94:95], v[110:111], v[112:113]
	v_pk_add_f32 v[110:111], v[110:111], v[112:113] neg_lo:[0,1] neg_hi:[0,1]
	s_nop 0
	v_pk_mul_f32 v[112:113], v[110:111], s[10:11]
	s_nop 0
	v_pk_fma_f32 v[110:111], v[110:111], s[8:9], v[112:113] op_sel:[0,0,1] op_sel_hi:[1,0,0]
	v_pk_add_f32 v[112:113], v[124:125], v[76:77]
	v_pk_add_f32 v[76:77], v[124:125], v[76:77] neg_lo:[0,1] neg_hi:[0,1]
	v_pk_add_f32 v[124:125], v[116:117], v[66:67]
	v_pk_add_f32 v[66:67], v[116:117], v[66:67] neg_lo:[0,1] neg_hi:[0,1]
	s_nop 0
	v_pk_mul_f32 v[116:117], v[66:67], s[10:11]
	s_nop 0
	v_pk_fma_f32 v[66:67], v[66:67], s[10:11], v[116:117] op_sel:[0,0,1] op_sel_hi:[1,0,0]
	v_pk_add_f32 v[116:117], v[96:97], v[92:93]
	v_pk_add_f32 v[96:97], v[96:97], v[92:93] op_sel:[1,1] op_sel_hi:[0,0] neg_lo:[1,0] neg_hi:[0,1]
	v_pk_add_f32 v[134:135], v[112:113], v[116:117]
	v_pk_add_f32 v[92:93], v[108:109], v[100:101]
	v_pk_add_f32 v[100:101], v[108:109], v[100:101] neg_lo:[0,1] neg_hi:[0,1]
	v_pk_add_f32 v[112:113], v[112:113], v[116:117] neg_lo:[0,1] neg_hi:[0,1]
	v_pk_mul_f32 v[108:109], v[100:101], s[10:11]
	v_pk_add_f32 v[116:117], v[124:125], v[92:93]
	v_pk_fma_f32 v[100:101], v[100:101], s[8:9], v[108:109] op_sel:[0,0,1] op_sel_hi:[1,0,0]
	v_pk_add_f32 v[108:109], v[80:81], v[86:87]
	v_pk_add_f32 v[80:81], v[80:81], v[86:87] neg_lo:[0,1] neg_hi:[0,1]
	v_pk_add_f32 v[86:87], v[82:83], v[88:89]
	v_pk_add_f32 v[82:83], v[82:83], v[88:89] neg_lo:[0,1] neg_hi:[0,1]
	s_nop 0
	v_pk_mul_f32 v[88:89], v[82:83], s[10:11]
	s_nop 0
	v_pk_fma_f32 v[82:83], v[82:83], s[10:11], v[88:89] op_sel:[0,0,1] op_sel_hi:[1,0,0]
	v_pk_add_f32 v[88:89], v[72:73], v[70:71]
	v_pk_add_f32 v[72:73], v[72:73], v[70:71] op_sel:[1,1] op_sel_hi:[0,0] neg_lo:[1,0] neg_hi:[0,1]
	v_pk_add_f32 v[136:137], v[108:109], v[88:89]
	v_pk_add_f32 v[70:71], v[74:75], v[78:79]
	v_pk_add_f32 v[74:75], v[74:75], v[78:79] neg_lo:[0,1] neg_hi:[0,1]
	v_pk_add_f32 v[88:89], v[108:109], v[88:89] neg_lo:[0,1] neg_hi:[0,1]
	v_pk_mul_f32 v[78:79], v[74:75], s[10:11]
	v_pk_add_f32 v[108:109], v[86:87], v[70:71]
	v_pk_fma_f32 v[74:75], v[74:75], s[8:9], v[78:79] op_sel:[0,0,1] op_sel_hi:[1,0,0]
	v_pk_add_f32 v[78:79], v[90:91], v[132:133]
	v_pk_add_f32 v[90:91], v[90:91], v[132:133] neg_lo:[0,1] neg_hi:[0,1]
	v_pk_add_f32 v[132:133], v[130:131], v[120:121]
	v_pk_add_f32 v[130:131], v[130:131], v[120:121] op_sel:[1,1] op_sel_hi:[0,0] neg_lo:[1,0] neg_hi:[0,1]
	v_pk_add_f32 v[138:139], v[80:81], v[72:73] neg_lo:[0,1] neg_hi:[0,1]
	v_pk_add_f32 v[120:121], v[122:123], v[128:129]
	v_pk_add_f32 v[122:123], v[122:123], v[128:129] neg_lo:[0,1] neg_hi:[0,1]
	v_pk_add_f32 v[128:129], v[84:85], v[118:119]
	v_pk_add_f32 v[118:119], v[84:85], v[118:119] op_sel:[1,1] op_sel_hi:[0,0] neg_lo:[1,0] neg_hi:[0,1]
	v_pk_add_f32 v[140:141], v[82:83], v[74:75]
	v_pk_add_f32 v[84:85], v[126:127], v[98:99]
	v_pk_add_f32 v[98:99], v[126:127], v[98:99] neg_lo:[0,1] neg_hi:[0,1]
	v_pk_add_f32 v[126:127], v[114:115], v[94:95]
	v_pk_add_f32 v[114:115], v[114:115], v[94:95] op_sel:[1,1] op_sel_hi:[0,0] neg_lo:[1,0] neg_hi:[0,1]
	v_pk_add_f32 v[142:143], v[78:79], v[132:133]
	v_pk_add_f32 v[94:95], v[102:103], v[106:107]
	v_pk_add_f32 v[102:103], v[102:103], v[106:107] neg_lo:[0,1] neg_hi:[0,1]
	v_pk_add_f32 v[106:107], v[68:69], v[110:111]
	v_pk_add_f32 v[110:111], v[68:69], v[110:111] op_sel:[1,1] op_sel_hi:[0,0] neg_lo:[1,0] neg_hi:[0,1]
	v_pk_add_f32 v[132:133], v[78:79], v[132:133] neg_lo:[0,1] neg_hi:[0,1]
	v_pk_add_f32 v[92:93], v[124:125], v[92:93] op_sel:[1,1] op_sel_hi:[0,0] neg_lo:[1,0] neg_hi:[0,1]
	v_pk_add_f32 v[124:125], v[76:77], v[96:97]
	v_pk_add_f32 v[76:77], v[76:77], v[96:97] neg_lo:[0,1] neg_hi:[0,1]
	v_pk_add_f32 v[96:97], v[66:67], v[100:101]
	v_pk_add_f32 v[100:101], v[66:67], v[100:101] op_sel:[1,1] op_sel_hi:[0,0] neg_lo:[1,0] neg_hi:[0,1]
	v_pk_add_f32 v[70:71], v[86:87], v[70:71] op_sel:[1,1] op_sel_hi:[0,0] neg_lo:[1,0] neg_hi:[0,1]
	v_pk_add_f32 v[74:75], v[82:83], v[74:75] op_sel:[1,1] op_sel_hi:[0,0] neg_lo:[1,0] neg_hi:[0,1]
	v_pk_add_f32 v[86:87], v[80:81], v[72:73]
	v_pk_add_f32 v[144:145], v[90:91], v[130:131]
	v_pk_add_f32 v[82:83], v[90:91], v[130:131] neg_lo:[0,1] neg_hi:[0,1]
	v_pk_add_f32 v[90:91], v[120:121], v[128:129]
	v_pk_add_f32 v[120:121], v[120:121], v[128:129] neg_lo:[0,1] neg_hi:[0,1]
	v_pk_add_f32 v[128:129], v[122:123], v[118:119]
	v_pk_add_f32 v[68:69], v[122:123], v[118:119] neg_lo:[0,1] neg_hi:[0,1]
	v_pk_add_f32 v[118:119], v[84:85], v[126:127]
	v_pk_add_f32 v[122:123], v[84:85], v[126:127] neg_lo:[0,1] neg_hi:[0,1]
	v_pk_add_f32 v[126:127], v[98:99], v[114:115]
	v_pk_add_f32 v[78:79], v[98:99], v[114:115] neg_lo:[0,1] neg_hi:[0,1]
	v_pk_add_f32 v[98:99], v[94:95], v[106:107]
	v_pk_add_f32 v[94:95], v[94:95], v[106:107] neg_lo:[0,1] neg_hi:[0,1]
	v_pk_add_f32 v[106:107], v[102:103], v[110:111]
	v_pk_add_f32 v[66:67], v[102:103], v[110:111] neg_lo:[0,1] neg_hi:[0,1]
	v_pk_add_f32 v[102:103], v[134:135], v[116:117]
	v_pk_add_f32 v[110:111], v[134:135], v[116:117] neg_lo:[0,1] neg_hi:[0,1]
	v_pk_add_f32 v[116:117], v[88:89], v[70:71]
	v_pk_add_f32 v[80:81], v[88:89], v[70:71] neg_lo:[0,1] neg_hi:[0,1]
	v_lshlrev_b32_e32 v70, 4, v0
	v_and_b32_e32 v70, 0x1f0, v70
	v_pk_add_f32 v[114:115], v[112:113], v[92:93]
	v_pk_add_f32 v[84:85], v[112:113], v[92:93] neg_lo:[0,1] neg_hi:[0,1]
	v_pk_add_f32 v[112:113], v[76:77], v[100:101]
	v_pk_add_f32 v[72:73], v[76:77], v[100:101] neg_lo:[0,1] neg_hi:[0,1]
	v_cvt_f32_u32_e32 v76, v70
	v_pk_add_f32 v[92:93], v[124:125], v[96:97]
	v_pk_add_f32 v[96:97], v[124:125], v[96:97] neg_lo:[0,1] neg_hi:[0,1]
	v_pk_add_f32 v[124:125], v[138:139], v[74:75]
	v_mul_f32_e32 v76, 0x38800000, v76
	v_pk_add_f32 v[70:71], v[138:139], v[74:75] neg_lo:[0,1] neg_hi:[0,1]
	v_sin_f32_e32 v75, v76
	v_ashrrev_i32_e32 v74, 2, v105
	v_lshlrev_b32_e32 v0, 8, v0
	v_add3_u32 v0, 0, v74, v0
	v_cos_f32_e32 v74, v76
	v_xor_b32_e32 v76, 0x80000000, v75
	v_mov_b32_e32 v77, v75
	v_pk_mul_f32 v[130:131], v[76:77], v[102:103] op_sel:[0,1] op_sel_hi:[1,0]
	v_pk_add_f32 v[100:101], v[136:137], v[108:109]
	v_pk_fma_f32 v[102:103], v[102:103], v[74:75], v[130:131] op_sel_hi:[1,0,1]
	ds_write2_b64 v0, v[142:143], v[102:103] offset1:1
	v_pk_mul_f32 v[102:103], v[76:77], v[74:75] op_sel:[0,1] op_sel_hi:[1,0]
	v_pk_add_f32 v[88:89], v[86:87], v[140:141]
	v_pk_fma_f32 v[102:103], v[74:75], v[74:75], v[102:103] op_sel_hi:[1,0,1]
	v_pk_add_f32 v[108:109], v[136:137], v[108:109] neg_lo:[0,1] neg_hi:[0,1]
	v_pk_mul_f32 v[130:131], v[118:119], v[102:103] op_sel:[1,1] op_sel_hi:[0,1] neg_lo:[0,1]
	v_pk_fma_f32 v[118:119], v[118:119], v[102:103], v[130:131] op_sel_hi:[1,0,1]
	v_pk_mul_f32 v[130:131], v[76:77], v[102:103] op_sel:[0,1] op_sel_hi:[1,0]
	v_pk_add_f32 v[86:87], v[86:87], v[140:141] neg_lo:[0,1] neg_hi:[0,1]
	v_pk_fma_f32 v[102:103], v[102:103], v[74:75], v[130:131] op_sel_hi:[1,0,1]
	s_nop 0
	v_pk_mul_f32 v[130:131], v[100:101], v[102:103] op_sel:[1,1] op_sel_hi:[0,1] neg_lo:[0,1]
	v_pk_fma_f32 v[100:101], v[100:101], v[102:103], v[130:131] op_sel_hi:[1,0,1]
	ds_write2_b64 v0, v[118:119], v[100:101] offset0:2 offset1:3
	v_pk_mul_f32 v[100:101], v[76:77], v[102:103] op_sel:[0,1] op_sel_hi:[1,0]
	s_nop 0
	v_pk_fma_f32 v[100:101], v[102:103], v[74:75], v[100:101] op_sel_hi:[1,0,1]
	s_nop 0
	v_pk_mul_f32 v[102:103], v[90:91], v[100:101] op_sel:[1,1] op_sel_hi:[0,1] neg_lo:[0,1]
	v_pk_fma_f32 v[90:91], v[90:91], v[100:101], v[102:103] op_sel_hi:[1,0,1]
	v_pk_mul_f32 v[102:103], v[76:77], v[100:101] op_sel:[0,1] op_sel_hi:[1,0]
	s_nop 0
	v_pk_fma_f32 v[100:101], v[100:101], v[74:75], v[102:103] op_sel_hi:[1,0,1]
	s_nop 0
	v_pk_mul_f32 v[102:103], v[92:93], v[100:101] op_sel:[1,1] op_sel_hi:[0,1] neg_lo:[0,1]
	v_pk_fma_f32 v[92:93], v[92:93], v[100:101], v[102:103] op_sel_hi:[1,0,1]
	ds_write2_b64 v0, v[90:91], v[92:93] offset0:4 offset1:5
	v_pk_mul_f32 v[90:91], v[76:77], v[100:101] op_sel:[0,1] op_sel_hi:[1,0]
	s_nop 0
	v_pk_fma_f32 v[90:91], v[100:101], v[74:75], v[90:91] op_sel_hi:[1,0,1]
	s_nop 0
	v_pk_mul_f32 v[92:93], v[98:99], v[90:91] op_sel:[1,1] op_sel_hi:[0,1] neg_lo:[0,1]
	v_pk_fma_f32 v[92:93], v[98:99], v[90:91], v[92:93] op_sel_hi:[1,0,1]
	v_pk_mul_f32 v[98:99], v[76:77], v[90:91] op_sel:[0,1] op_sel_hi:[1,0]
	s_nop 0
	v_pk_fma_f32 v[90:91], v[90:91], v[74:75], v[98:99] op_sel_hi:[1,0,1]
	s_nop 0
	v_pk_mul_f32 v[98:99], v[88:89], v[90:91] op_sel:[1,1] op_sel_hi:[0,1] neg_lo:[0,1]
	v_pk_fma_f32 v[88:89], v[88:89], v[90:91], v[98:99] op_sel_hi:[1,0,1]
	ds_write2_b64 v0, v[92:93], v[88:89] offset0:6 offset1:7
	v_pk_mul_f32 v[88:89], v[76:77], v[90:91] op_sel:[0,1] op_sel_hi:[1,0]
	s_nop 0
	v_pk_fma_f32 v[88:89], v[90:91], v[74:75], v[88:89] op_sel_hi:[1,0,1]
	s_nop 0
	v_pk_mul_f32 v[90:91], v[144:145], v[88:89] op_sel:[1,1] op_sel_hi:[0,1] neg_lo:[0,1]
	v_pk_mul_f32 v[92:93], v[76:77], v[88:89] op_sel:[0,1] op_sel_hi:[1,0]
	v_pk_fma_f32 v[90:91], v[144:145], v[88:89], v[90:91] op_sel_hi:[1,0,1]
	v_pk_fma_f32 v[88:89], v[88:89], v[74:75], v[92:93] op_sel_hi:[1,0,1]
	s_nop 0
	v_pk_mul_f32 v[92:93], v[114:115], v[88:89] op_sel:[1,1] op_sel_hi:[0,1] neg_lo:[0,1]
	v_pk_fma_f32 v[92:93], v[114:115], v[88:89], v[92:93] op_sel_hi:[1,0,1]
	ds_write2_b64 v0, v[90:91], v[92:93] offset0:8 offset1:9
	v_pk_mul_f32 v[90:91], v[76:77], v[88:89] op_sel:[0,1] op_sel_hi:[1,0]
	s_nop 0
	v_pk_fma_f32 v[88:89], v[88:89], v[74:75], v[90:91] op_sel_hi:[1,0,1]
	s_nop 0
	v_pk_mul_f32 v[90:91], v[126:127], v[88:89] op_sel:[1,1] op_sel_hi:[0,1] neg_lo:[0,1]
	v_pk_mul_f32 v[92:93], v[76:77], v[88:89] op_sel:[0,1] op_sel_hi:[1,0]
	v_pk_fma_f32 v[90:91], v[126:127], v[88:89], v[90:91] op_sel_hi:[1,0,1]
	v_pk_fma_f32 v[88:89], v[88:89], v[74:75], v[92:93] op_sel_hi:[1,0,1]
	s_nop 0
	v_pk_mul_f32 v[92:93], v[116:117], v[88:89] op_sel:[1,1] op_sel_hi:[0,1] neg_lo:[0,1]
	v_pk_fma_f32 v[92:93], v[116:117], v[88:89], v[92:93] op_sel_hi:[1,0,1]
	ds_write2_b64 v0, v[90:91], v[92:93] offset0:10 offset1:11
	v_pk_mul_f32 v[90:91], v[76:77], v[88:89] op_sel:[0,1] op_sel_hi:[1,0]
	s_nop 0
	v_pk_fma_f32 v[88:89], v[88:89], v[74:75], v[90:91] op_sel_hi:[1,0,1]
	s_nop 0
	v_pk_mul_f32 v[90:91], v[128:129], v[88:89] op_sel:[1,1] op_sel_hi:[0,1] neg_lo:[0,1]
	v_pk_mul_f32 v[92:93], v[76:77], v[88:89] op_sel:[0,1] op_sel_hi:[1,0]
	v_pk_fma_f32 v[90:91], v[128:129], v[88:89], v[90:91] op_sel_hi:[1,0,1]
	v_pk_fma_f32 v[88:89], v[88:89], v[74:75], v[92:93] op_sel_hi:[1,0,1]
	s_nop 0
	v_pk_mul_f32 v[92:93], v[112:113], v[88:89] op_sel:[1,1] op_sel_hi:[0,1] neg_lo:[0,1]
	v_pk_fma_f32 v[92:93], v[112:113], v[88:89], v[92:93] op_sel_hi:[1,0,1]
	ds_write2_b64 v0, v[90:91], v[92:93] offset0:12 offset1:13
	v_pk_mul_f32 v[90:91], v[76:77], v[88:89] op_sel:[0,1] op_sel_hi:[1,0]
	s_nop 0
	v_pk_fma_f32 v[88:89], v[88:89], v[74:75], v[90:91] op_sel_hi:[1,0,1]
	s_nop 0
	v_pk_mul_f32 v[90:91], v[106:107], v[88:89] op_sel:[1,1] op_sel_hi:[0,1] neg_lo:[0,1]
	v_pk_mul_f32 v[92:93], v[76:77], v[88:89] op_sel:[0,1] op_sel_hi:[1,0]
	v_pk_fma_f32 v[90:91], v[106:107], v[88:89], v[90:91] op_sel_hi:[1,0,1]
	v_pk_fma_f32 v[88:89], v[88:89], v[74:75], v[92:93] op_sel_hi:[1,0,1]
	s_nop 0
	v_pk_mul_f32 v[92:93], v[124:125], v[88:89] op_sel:[1,1] op_sel_hi:[0,1] neg_lo:[0,1]
	v_pk_fma_f32 v[92:93], v[124:125], v[88:89], v[92:93] op_sel_hi:[1,0,1]
	ds_write2_b64 v0, v[90:91], v[92:93] offset0:14 offset1:15
	v_pk_mul_f32 v[90:91], v[76:77], v[88:89] op_sel:[0,1] op_sel_hi:[1,0]
	s_nop 0
	v_pk_fma_f32 v[88:89], v[88:89], v[74:75], v[90:91] op_sel_hi:[1,0,1]
	s_nop 0
	v_pk_mul_f32 v[90:91], v[132:133], v[88:89] op_sel:[1,1] op_sel_hi:[0,1] neg_lo:[0,1]
	v_pk_mul_f32 v[92:93], v[76:77], v[88:89] op_sel:[0,1] op_sel_hi:[1,0]
	v_pk_fma_f32 v[90:91], v[132:133], v[88:89], v[90:91] op_sel_hi:[1,0,1]
	v_pk_fma_f32 v[88:89], v[88:89], v[74:75], v[92:93] op_sel_hi:[1,0,1]
	s_nop 0
	v_pk_mul_f32 v[92:93], v[110:111], v[88:89] op_sel:[1,1] op_sel_hi:[0,1] neg_lo:[0,1]
	v_pk_fma_f32 v[92:93], v[110:111], v[88:89], v[92:93] op_sel_hi:[1,0,1]
	ds_write2_b64 v0, v[90:91], v[92:93] offset0:16 offset1:17
	v_pk_mul_f32 v[90:91], v[76:77], v[88:89] op_sel:[0,1] op_sel_hi:[1,0]
	s_nop 0
	v_pk_fma_f32 v[88:89], v[88:89], v[74:75], v[90:91] op_sel_hi:[1,0,1]
	s_nop 0
	v_pk_mul_f32 v[90:91], v[122:123], v[88:89] op_sel:[1,1] op_sel_hi:[0,1] neg_lo:[0,1]
	v_pk_mul_f32 v[92:93], v[76:77], v[88:89] op_sel:[0,1] op_sel_hi:[1,0]
	v_pk_fma_f32 v[90:91], v[122:123], v[88:89], v[90:91] op_sel_hi:[1,0,1]
	v_pk_fma_f32 v[88:89], v[88:89], v[74:75], v[92:93] op_sel_hi:[1,0,1]
	s_nop 0
	v_pk_mul_f32 v[92:93], v[108:109], v[88:89] op_sel:[1,1] op_sel_hi:[0,1] neg_lo:[0,1]
	v_pk_fma_f32 v[92:93], v[108:109], v[88:89], v[92:93] op_sel_hi:[1,0,1]
	ds_write2_b64 v0, v[90:91], v[92:93] offset0:18 offset1:19
	v_pk_mul_f32 v[90:91], v[76:77], v[88:89] op_sel:[0,1] op_sel_hi:[1,0]
	s_nop 0
	v_pk_fma_f32 v[88:89], v[88:89], v[74:75], v[90:91] op_sel_hi:[1,0,1]
	s_nop 0
	v_pk_mul_f32 v[90:91], v[120:121], v[88:89] op_sel:[1,1] op_sel_hi:[0,1] neg_lo:[0,1]
	v_pk_mul_f32 v[92:93], v[76:77], v[88:89] op_sel:[0,1] op_sel_hi:[1,0]
	v_pk_fma_f32 v[90:91], v[120:121], v[88:89], v[90:91] op_sel_hi:[1,0,1]
	v_pk_fma_f32 v[88:89], v[88:89], v[74:75], v[92:93] op_sel_hi:[1,0,1]
	s_nop 0
	v_pk_mul_f32 v[92:93], v[96:97], v[88:89] op_sel:[1,1] op_sel_hi:[0,1] neg_lo:[0,1]
	v_pk_fma_f32 v[92:93], v[96:97], v[88:89], v[92:93] op_sel_hi:[1,0,1]
	ds_write2_b64 v0, v[90:91], v[92:93] offset0:20 offset1:21
	v_pk_mul_f32 v[90:91], v[76:77], v[88:89] op_sel:[0,1] op_sel_hi:[1,0]
	s_nop 0
	v_pk_fma_f32 v[88:89], v[88:89], v[74:75], v[90:91] op_sel_hi:[1,0,1]
	s_nop 0
	v_pk_mul_f32 v[90:91], v[94:95], v[88:89] op_sel:[1,1] op_sel_hi:[0,1] neg_lo:[0,1]
	v_pk_mul_f32 v[92:93], v[76:77], v[88:89] op_sel:[0,1] op_sel_hi:[1,0]
	v_pk_fma_f32 v[90:91], v[94:95], v[88:89], v[90:91] op_sel_hi:[1,0,1]
	v_pk_fma_f32 v[88:89], v[88:89], v[74:75], v[92:93] op_sel_hi:[1,0,1]
	s_nop 0
	v_pk_mul_f32 v[92:93], v[86:87], v[88:89] op_sel:[1,1] op_sel_hi:[0,1] neg_lo:[0,1]
	v_pk_fma_f32 v[86:87], v[86:87], v[88:89], v[92:93] op_sel_hi:[1,0,1]
	ds_write2_b64 v0, v[90:91], v[86:87] offset0:22 offset1:23
	v_pk_mul_f32 v[86:87], v[76:77], v[88:89] op_sel:[0,1] op_sel_hi:[1,0]
	s_nop 0
	v_pk_fma_f32 v[86:87], v[88:89], v[74:75], v[86:87] op_sel_hi:[1,0,1]
	s_nop 0
	v_pk_mul_f32 v[88:89], v[82:83], v[86:87] op_sel:[1,1] op_sel_hi:[0,1] neg_lo:[0,1]
	v_pk_fma_f32 v[82:83], v[82:83], v[86:87], v[88:89] op_sel_hi:[1,0,1]
	v_pk_mul_f32 v[88:89], v[76:77], v[86:87] op_sel:[0,1] op_sel_hi:[1,0]
	s_nop 0
	v_pk_fma_f32 v[86:87], v[86:87], v[74:75], v[88:89] op_sel_hi:[1,0,1]
	s_nop 0
	v_pk_mul_f32 v[88:89], v[84:85], v[86:87] op_sel:[1,1] op_sel_hi:[0,1] neg_lo:[0,1]
	v_pk_fma_f32 v[84:85], v[84:85], v[86:87], v[88:89] op_sel_hi:[1,0,1]
	ds_write2_b64 v0, v[82:83], v[84:85] offset0:24 offset1:25
	v_pk_mul_f32 v[82:83], v[76:77], v[86:87] op_sel:[0,1] op_sel_hi:[1,0]
	s_nop 0
	v_pk_fma_f32 v[82:83], v[86:87], v[74:75], v[82:83] op_sel_hi:[1,0,1]
	s_nop 0
	v_pk_mul_f32 v[84:85], v[78:79], v[82:83] op_sel:[1,1] op_sel_hi:[0,1] neg_lo:[0,1]
	v_pk_fma_f32 v[78:79], v[78:79], v[82:83], v[84:85] op_sel_hi:[1,0,1]
	v_pk_mul_f32 v[84:85], v[76:77], v[82:83] op_sel:[0,1] op_sel_hi:[1,0]
	s_nop 0
	v_pk_fma_f32 v[82:83], v[82:83], v[74:75], v[84:85] op_sel_hi:[1,0,1]
	s_nop 0
	v_pk_mul_f32 v[84:85], v[80:81], v[82:83] op_sel:[1,1] op_sel_hi:[0,1] neg_lo:[0,1]
	v_pk_fma_f32 v[80:81], v[80:81], v[82:83], v[84:85] op_sel_hi:[1,0,1]
	ds_write2_b64 v0, v[78:79], v[80:81] offset0:26 offset1:27
	v_pk_mul_f32 v[78:79], v[76:77], v[82:83] op_sel:[0,1] op_sel_hi:[1,0]
	s_nop 0
	v_pk_fma_f32 v[78:79], v[82:83], v[74:75], v[78:79] op_sel_hi:[1,0,1]
	s_nop 0
	v_pk_mul_f32 v[80:81], v[68:69], v[78:79] op_sel:[1,1] op_sel_hi:[0,1] neg_lo:[0,1]
	v_pk_fma_f32 v[68:69], v[68:69], v[78:79], v[80:81] op_sel_hi:[1,0,1]
	v_pk_mul_f32 v[80:81], v[76:77], v[78:79] op_sel:[0,1] op_sel_hi:[1,0]
	s_nop 0
	v_pk_fma_f32 v[78:79], v[78:79], v[74:75], v[80:81] op_sel_hi:[1,0,1]
	s_nop 0
	v_pk_mul_f32 v[80:81], v[72:73], v[78:79] op_sel:[1,1] op_sel_hi:[0,1] neg_lo:[0,1]
	v_pk_fma_f32 v[72:73], v[72:73], v[78:79], v[80:81] op_sel_hi:[1,0,1]
	ds_write2_b64 v0, v[68:69], v[72:73] offset0:28 offset1:29
	v_pk_mul_f32 v[68:69], v[76:77], v[78:79] op_sel:[0,1] op_sel_hi:[1,0]
	s_nop 0
	v_pk_fma_f32 v[68:69], v[78:79], v[74:75], v[68:69] op_sel_hi:[1,0,1]
	s_nop 0
	v_pk_mul_f32 v[72:73], v[66:67], v[68:69] op_sel:[1,1] op_sel_hi:[0,1] neg_lo:[0,1]
	v_pk_fma_f32 v[66:67], v[66:67], v[68:69], v[72:73] op_sel_hi:[1,0,1]
	v_pk_mul_f32 v[72:73], v[76:77], v[68:69] op_sel:[0,1] op_sel_hi:[1,0]
	s_nop 0
	v_pk_fma_f32 v[68:69], v[68:69], v[74:75], v[72:73] op_sel_hi:[1,0,1]
	s_nop 0
	v_pk_mul_f32 v[72:73], v[70:71], v[68:69] op_sel:[1,1] op_sel_hi:[0,1] neg_lo:[0,1]
	v_pk_fma_f32 v[68:69], v[70:71], v[68:69], v[72:73] op_sel_hi:[1,0,1]
	ds_write2_b64 v0, v[66:67], v[68:69] offset0:30 offset1:31
	s_waitcnt lgkmcnt(0)
	s_barrier
	v_mov_b32 v0, 0
	s_nop 0
	v_add_u32_e32 v71, v0, v170
	v_ashrrev_i32_e32 v105, 5, v71
	v_lshlrev_b32_e32 v0, 10, v105
	v_and_b32_e32 v140, 31, v71
	v_ashrrev_i32_e32 v0, 2, v0
	v_lshlrev_b32_e32 v67, 13, v105
	v_lshlrev_b32_e32 v68, 3, v140
	v_add_u32_e32 v0, 0, v0
	v_lshl_add_u32 v66, v105, 8, 0
	v_add3_u32 v0, v0, v67, v68
	v_add3_u32 v142, v66, v67, v68
	v_add_u32_e32 v143, 0x400, v0
	v_add_u32_e32 v144, 0x800, v0
	v_add_u32_e32 v145, 0xc00, v0
	ds_read_b64 v[130:131], v142
	ds_read2_b64 v[66:69], v0 offset0:33 offset1:66
	ds_read2_b64 v[72:75], v0 offset0:99 offset1:132
	ds_read2_b64 v[76:79], v0 offset0:165 offset1:198
	ds_read2_b64 v[80:83], v143 offset0:103 offset1:136
	ds_read2_b64 v[84:87], v144 offset0:41 offset1:74
	ds_read2_b64 v[88:91], v144 offset0:107 offset1:140
	ds_read2_b64 v[92:95], v144 offset0:173 offset1:206
	ds_read2_b64 v[96:99], v145 offset0:111 offset1:144
	v_add_u32_e32 v146, 0x1000, v0
	ds_read2_b64 v[100:103], v146 offset0:49 offset1:82
	ds_read2_b64 v[106:109], v146 offset0:115 offset1:148
	ds_read2_b64 v[110:113], v146 offset0:181 offset1:214
	v_add_u32_e32 v147, 0x1400, v0
	ds_read2_b64 v[114:117], v147 offset0:119 offset1:152
	s_waitcnt lgkmcnt(4)
	v_pk_add_f32 v[134:135], v[130:131], v[98:99]
	v_pk_add_f32 v[98:99], v[130:131], v[98:99] neg_lo:[0,1] neg_hi:[0,1]
	s_waitcnt lgkmcnt(3)
	v_pk_add_f32 v[130:131], v[66:67], v[100:101]
	v_pk_add_f32 v[66:67], v[66:67], v[100:101] neg_lo:[0,1] neg_hi:[0,1]
	v_add_u32_e32 v70, 0x1800, v0
	v_pk_mul_f32 v[100:101], v[66:67], s[50:51]
	ds_read2_b64 v[118:121], v70 offset0:57 offset1:90
	ds_read2_b64 v[122:125], v70 offset0:123 offset1:156
	ds_read2_b64 v[126:129], v70 offset0:189 offset1:222
	ds_read_b64 v[132:133], v0 offset:8184
	v_pk_fma_f32 v[66:67], v[66:67], s[20:21], v[100:101] op_sel:[0,0,1] op_sel_hi:[1,0,0]
	v_pk_add_f32 v[100:101], v[68:69], v[102:103]
	v_pk_add_f32 v[68:69], v[68:69], v[102:103] neg_lo:[0,1] neg_hi:[0,1]
	v_mul_lo_u32 v105, v140, v105
	v_pk_mul_f32 v[102:103], v[68:69], s[14:15]
	v_cvt_f32_i32_e32 v105, v105
	v_pk_fma_f32 v[68:69], v[68:69], s[6:7], v[102:103] op_sel:[0,0,1] op_sel_hi:[1,0,0]
	s_waitcnt lgkmcnt(6)
	v_pk_add_f32 v[102:103], v[72:73], v[106:107]
	v_pk_add_f32 v[72:73], v[72:73], v[106:107] neg_lo:[0,1] neg_hi:[0,1]
	v_and_b32_e32 v71, 0xffffffe0, v71
	v_pk_mul_f32 v[106:107], v[72:73], s[52:53]
	v_cvt_f32_i32_e32 v71, v71
	v_pk_fma_f32 v[72:73], v[72:73], s[24:25], v[106:107] op_sel:[0,0,1] op_sel_hi:[1,0,0]
	v_pk_add_f32 v[106:107], v[74:75], v[108:109]
	v_pk_add_f32 v[74:75], v[74:75], v[108:109] neg_lo:[0,1] neg_hi:[0,1]
	v_mul_f32_e32 v71, 0x38800000, v71
	v_pk_mul_f32 v[108:109], v[74:75], s[10:11]
	s_nop 0
	v_pk_fma_f32 v[74:75], v[74:75], s[10:11], v[108:109] op_sel:[0,0,1] op_sel_hi:[1,0,0]
	s_waitcnt lgkmcnt(5)
	v_pk_add_f32 v[108:109], v[76:77], v[110:111]
	v_pk_add_f32 v[76:77], v[76:77], v[110:111] neg_lo:[0,1] neg_hi:[0,1]
	s_nop 0
	v_pk_mul_f32 v[110:111], v[76:77], s[24:25]
	s_nop 0
	v_pk_fma_f32 v[76:77], v[76:77], s[0:1], v[110:111] op_sel:[0,0,1] op_sel_hi:[1,0,0]
	v_pk_add_f32 v[110:111], v[78:79], v[112:113]
	v_pk_add_f32 v[78:79], v[78:79], v[112:113] neg_lo:[0,1] neg_hi:[0,1]
	s_nop 0
	v_pk_mul_f32 v[112:113], v[78:79], s[6:7]
	s_nop 0
	v_pk_fma_f32 v[78:79], v[78:79], s[14:15], v[112:113] op_sel:[0,0,1] op_sel_hi:[1,0,0]
	s_waitcnt lgkmcnt(4)
	v_pk_add_f32 v[112:113], v[80:81], v[114:115]
	v_pk_add_f32 v[80:81], v[80:81], v[114:115] neg_lo:[0,1] neg_hi:[0,1]
	s_nop 0
	v_pk_mul_f32 v[114:115], v[80:81], s[20:21]
	s_nop 0
	v_pk_fma_f32 v[80:81], v[80:81], s[48:49], v[114:115] op_sel:[0,0,1] op_sel_hi:[1,0,0]
	v_pk_add_f32 v[114:115], v[82:83], v[116:117]
	v_pk_add_f32 v[116:117], v[82:83], v[116:117] op_sel:[1,1] op_sel_hi:[0,0] neg_lo:[1,0] neg_hi:[0,1]
	s_mov_b64 s[48:49], -1
	s_waitcnt lgkmcnt(3)
	v_pk_add_f32 v[82:83], v[84:85], v[118:119]
	v_pk_add_f32 v[84:85], v[84:85], v[118:119] neg_lo:[0,1] neg_hi:[0,1]
	s_nop 0
	v_pk_mul_f32 v[118:119], v[84:85], s[20:21]
	s_nop 0
	v_pk_fma_f32 v[84:85], v[84:85], s[18:19], v[118:119] op_sel:[0,0,1] op_sel_hi:[1,0,0]
	v_pk_add_f32 v[118:119], v[86:87], v[120:121]
	v_pk_add_f32 v[86:87], v[86:87], v[120:121] neg_lo:[0,1] neg_hi:[0,1]
	s_nop 0
	v_pk_mul_f32 v[120:121], v[86:87], s[6:7]
	s_nop 0
	v_pk_fma_f32 v[86:87], v[86:87], s[4:5], v[120:121] op_sel:[0,0,1] op_sel_hi:[1,0,0]
	s_waitcnt lgkmcnt(2)
	v_pk_add_f32 v[120:121], v[88:89], v[122:123]
	v_pk_add_f32 v[88:89], v[88:89], v[122:123] neg_lo:[0,1] neg_hi:[0,1]
	s_nop 0
	v_pk_mul_f32 v[122:123], v[88:89], s[24:25]
	s_nop 0
	v_pk_fma_f32 v[88:89], v[88:89], s[22:23], v[122:123] op_sel:[0,0,1] op_sel_hi:[1,0,0]
	v_pk_add_f32 v[122:123], v[90:91], v[124:125]
	v_pk_add_f32 v[90:91], v[90:91], v[124:125] neg_lo:[0,1] neg_hi:[0,1]
	s_nop 0
	v_pk_mul_f32 v[124:125], v[90:91], s[10:11]
	s_nop 0
	v_pk_fma_f32 v[90:91], v[90:91], s[8:9], v[124:125] op_sel:[0,0,1] op_sel_hi:[1,0,0]
	s_waitcnt lgkmcnt(1)
	v_pk_add_f32 v[124:125], v[92:93], v[126:127]
	v_pk_add_f32 v[92:93], v[92:93], v[126:127] neg_lo:[0,1] neg_hi:[0,1]
	s_nop 0
	v_pk_mul_f32 v[126:127], v[92:93], s[52:53]
	s_nop 0
	v_pk_fma_f32 v[92:93], v[92:93], s[26:27], v[126:127] op_sel:[0,0,1] op_sel_hi:[1,0,0]
	v_pk_add_f32 v[126:127], v[94:95], v[128:129]
	v_pk_add_f32 v[94:95], v[94:95], v[128:129] neg_lo:[0,1] neg_hi:[0,1]
	s_nop 0
	v_pk_mul_f32 v[128:129], v[94:95], s[14:15]
	s_nop 0
	v_pk_fma_f32 v[94:95], v[94:95], s[12:13], v[128:129] op_sel:[0,0,1] op_sel_hi:[1,0,0]
	s_waitcnt lgkmcnt(0)
	v_pk_add_f32 v[128:129], v[96:97], v[132:133]
	v_pk_add_f32 v[96:97], v[96:97], v[132:133] neg_lo:[0,1] neg_hi:[0,1]
	s_nop 0
	v_pk_mul_f32 v[132:133], v[96:97], s[50:51]
	s_nop 0
	v_pk_fma_f32 v[96:97], v[96:97], s[34:35], v[132:133] op_sel:[0,0,1] op_sel_hi:[1,0,0]
	v_pk_add_f32 v[132:133], v[134:135], v[114:115]
	v_pk_add_f32 v[114:115], v[134:135], v[114:115] neg_lo:[0,1] neg_hi:[0,1]
	v_pk_add_f32 v[134:135], v[130:131], v[82:83]
	v_pk_add_f32 v[82:83], v[130:131], v[82:83] neg_lo:[0,1] neg_hi:[0,1]
	s_nop 0
	v_pk_mul_f32 v[130:131], v[82:83], s[14:15]
	s_nop 0
	v_pk_fma_f32 v[82:83], v[82:83], s[6:7], v[130:131] op_sel:[0,0,1] op_sel_hi:[1,0,0]
	v_pk_add_f32 v[130:131], v[100:101], v[118:119]
	v_pk_add_f32 v[100:101], v[100:101], v[118:119] neg_lo:[0,1] neg_hi:[0,1]
	s_nop 0
	v_pk_mul_f32 v[118:119], v[100:101], s[10:11]
	s_nop 0
	v_pk_fma_f32 v[100:101], v[100:101], s[10:11], v[118:119] op_sel:[0,0,1] op_sel_hi:[1,0,0]
	v_pk_add_f32 v[118:119], v[102:103], v[120:121]
	v_pk_add_f32 v[102:103], v[102:103], v[120:121] neg_lo:[0,1] neg_hi:[0,1]
	s_nop 0
	v_pk_mul_f32 v[120:121], v[102:103], s[6:7]
	s_nop 0
	v_pk_fma_f32 v[102:103], v[102:103], s[14:15], v[120:121] op_sel:[0,0,1] op_sel_hi:[1,0,0]
	v_pk_add_f32 v[120:121], v[106:107], v[122:123]
	v_pk_add_f32 v[122:123], v[106:107], v[122:123] op_sel:[1,1] op_sel_hi:[0,0] neg_lo:[1,0] neg_hi:[0,1]
	s_nop 0
	v_pk_add_f32 v[106:107], v[108:109], v[124:125]
	v_pk_add_f32 v[108:109], v[108:109], v[124:125] neg_lo:[0,1] neg_hi:[0,1]
	s_nop 0
	v_pk_mul_f32 v[124:125], v[108:109], s[6:7]
	s_nop 0
	v_pk_fma_f32 v[108:109], v[108:109], s[4:5], v[124:125] op_sel:[0,0,1] op_sel_hi:[1,0,0]
	v_pk_add_f32 v[124:125], v[110:111], v[126:127]
	v_pk_add_f32 v[110:111], v[110:111], v[126:127] neg_lo:[0,1] neg_hi:[0,1]
	s_nop 0
	v_pk_mul_f32 v[126:127], v[110:111], s[10:11]
	s_nop 0
	v_pk_fma_f32 v[110:111], v[110:111], s[8:9], v[126:127] op_sel:[0,0,1] op_sel_hi:[1,0,0]
	v_pk_add_f32 v[126:127], v[112:113], v[128:129]
	v_pk_add_f32 v[112:113], v[112:113], v[128:129] neg_lo:[0,1] neg_hi:[0,1]
	s_nop 0
	v_pk_mul_f32 v[128:129], v[112:113], s[14:15]
	s_nop 0
	v_pk_fma_f32 v[112:113], v[112:113], s[12:13], v[128:129] op_sel:[0,0,1] op_sel_hi:[1,0,0]
	v_pk_add_f32 v[128:129], v[98:99], v[116:117]
	v_pk_add_f32 v[98:99], v[98:99], v[116:117] neg_lo:[0,1] neg_hi:[0,1]
	v_pk_add_f32 v[116:117], v[66:67], v[84:85]
	v_pk_add_f32 v[66:67], v[66:67], v[84:85] neg_lo:[0,1] neg_hi:[0,1]
	s_nop 0
	v_pk_mul_f32 v[84:85], v[66:67], s[14:15]
	s_nop 0
	v_pk_fma_f32 v[66:67], v[66:67], s[6:7], v[84:85] op_sel:[0,0,1] op_sel_hi:[1,0,0]
	v_pk_add_f32 v[84:85], v[68:69], v[86:87]
	v_pk_add_f32 v[68:69], v[68:69], v[86:87] neg_lo:[0,1] neg_hi:[0,1]
	s_nop 0
	v_pk_mul_f32 v[86:87], v[68:69], s[10:11]
	s_nop 0
	v_pk_fma_f32 v[68:69], v[68:69], s[10:11], v[86:87] op_sel:[0,0,1] op_sel_hi:[1,0,0]
	v_pk_add_f32 v[86:87], v[72:73], v[88:89]
	v_pk_add_f32 v[72:73], v[72:73], v[88:89] neg_lo:[0,1] neg_hi:[0,1]
	s_nop 0
	v_pk_mul_f32 v[88:89], v[72:73], s[6:7]
	s_nop 0
	v_pk_fma_f32 v[72:73], v[72:73], s[14:15], v[88:89] op_sel:[0,0,1] op_sel_hi:[1,0,0]
	v_pk_add_f32 v[88:89], v[74:75], v[90:91]
	v_pk_add_f32 v[90:91], v[74:75], v[90:91] op_sel:[1,1] op_sel_hi:[0,0] neg_lo:[1,0] neg_hi:[0,1]
	s_nop 0
	v_pk_add_f32 v[74:75], v[76:77], v[92:93]
	v_pk_add_f32 v[76:77], v[76:77], v[92:93] neg_lo:[0,1] neg_hi:[0,1]
	s_nop 0
	v_pk_mul_f32 v[92:93], v[76:77], s[6:7]
	s_nop 0
	v_pk_fma_f32 v[76:77], v[76:77], s[4:5], v[92:93] op_sel:[0,0,1] op_sel_hi:[1,0,0]
	v_pk_add_f32 v[92:93], v[78:79], v[94:95]
	v_pk_add_f32 v[78:79], v[78:79], v[94:95] neg_lo:[0,1] neg_hi:[0,1]
	s_mov_b32 s5, 0
	v_pk_mul_f32 v[94:95], v[78:79], s[10:11]
	s_nop 0
	v_pk_fma_f32 v[78:79], v[78:79], s[8:9], v[94:95] op_sel:[0,0,1] op_sel_hi:[1,0,0]
	v_pk_add_f32 v[94:95], v[80:81], v[96:97]
	v_pk_add_f32 v[80:81], v[80:81], v[96:97] neg_lo:[0,1] neg_hi:[0,1]
	s_nop 0
	v_pk_mul_f32 v[96:97], v[80:81], s[14:15]
	s_nop 0
	v_pk_fma_f32 v[80:81], v[80:81], s[12:13], v[96:97] op_sel:[0,0,1] op_sel_hi:[1,0,0]
	v_pk_add_f32 v[96:97], v[132:133], v[120:121]
	v_pk_add_f32 v[120:121], v[132:133], v[120:121] neg_lo:[0,1] neg_hi:[0,1]
	v_pk_add_f32 v[132:133], v[134:135], v[106:107]
	v_pk_add_f32 v[106:107], v[134:135], v[106:107] neg_lo:[0,1] neg_hi:[0,1]
	s_nop 0
	v_pk_mul_f32 v[134:135], v[106:107], s[10:11]
	s_nop 0
	v_pk_fma_f32 v[106:107], v[106:107], s[10:11], v[134:135] op_sel:[0,0,1] op_sel_hi:[1,0,0]
	v_pk_add_f32 v[134:135], v[130:131], v[124:125]
	v_pk_add_f32 v[130:131], v[130:131], v[124:125] op_sel:[1,1] op_sel_hi:[0,0] neg_lo:[1,0] neg_hi:[0,1]
	s_nop 0
	v_pk_add_f32 v[124:125], v[118:119], v[126:127]
	v_pk_add_f32 v[118:119], v[118:119], v[126:127] neg_lo:[0,1] neg_hi:[0,1]
	s_nop 0
	v_pk_mul_f32 v[126:127], v[118:119], s[10:11]
	s_nop 0
	v_pk_fma_f32 v[118:119], v[118:119], s[8:9], v[126:127] op_sel:[0,0,1] op_sel_hi:[1,0,0]
	v_pk_add_f32 v[126:127], v[114:115], v[122:123]
	v_pk_add_f32 v[114:115], v[114:115], v[122:123] neg_lo:[0,1] neg_hi:[0,1]
	v_pk_add_f32 v[122:123], v[82:83], v[108:109]
	v_pk_add_f32 v[82:83], v[82:83], v[108:109] neg_lo:[0,1] neg_hi:[0,1]
	s_nop 0
	v_pk_mul_f32 v[108:109], v[82:83], s[10:11]
	s_nop 0
	v_pk_fma_f32 v[82:83], v[82:83], s[10:11], v[108:109] op_sel:[0,0,1] op_sel_hi:[1,0,0]
	v_pk_add_f32 v[108:109], v[100:101], v[110:111]
	v_pk_add_f32 v[110:111], v[100:101], v[110:111] op_sel:[1,1] op_sel_hi:[0,0] neg_lo:[1,0] neg_hi:[0,1]
	s_nop 0
	v_pk_add_f32 v[100:101], v[102:103], v[112:113]
	v_pk_add_f32 v[102:103], v[102:103], v[112:113] neg_lo:[0,1] neg_hi:[0,1]
	s_nop 0
	v_pk_mul_f32 v[112:113], v[102:103], s[10:11]
	s_nop 0
	v_pk_fma_f32 v[102:103], v[102:103], s[8:9], v[112:113] op_sel:[0,0,1] op_sel_hi:[1,0,0]
	v_pk_add_f32 v[112:113], v[128:129], v[88:89]
	v_pk_add_f32 v[88:89], v[128:129], v[88:89] neg_lo:[0,1] neg_hi:[0,1]
	v_pk_add_f32 v[128:129], v[116:117], v[74:75]
	v_pk_add_f32 v[74:75], v[116:117], v[74:75] neg_lo:[0,1] neg_hi:[0,1]
	s_nop 0
	v_pk_mul_f32 v[116:117], v[74:75], s[10:11]
	s_nop 0
	v_pk_fma_f32 v[74:75], v[74:75], s[10:11], v[116:117] op_sel:[0,0,1] op_sel_hi:[1,0,0]
	v_pk_add_f32 v[116:117], v[84:85], v[92:93]
	v_pk_add_f32 v[92:93], v[84:85], v[92:93] op_sel:[1,1] op_sel_hi:[0,0] neg_lo:[1,0] neg_hi:[0,1]
	s_nop 0
	v_pk_add_f32 v[84:85], v[86:87], v[94:95]
	v_pk_add_f32 v[86:87], v[86:87], v[94:95] neg_lo:[0,1] neg_hi:[0,1]
	s_nop 0
	v_pk_mul_f32 v[94:95], v[86:87], s[10:11]
	s_nop 0
	v_pk_fma_f32 v[86:87], v[86:87], s[8:9], v[94:95] op_sel:[0,0,1] op_sel_hi:[1,0,0]
	v_pk_add_f32 v[94:95], v[98:99], v[90:91]
	v_pk_add_f32 v[90:91], v[98:99], v[90:91] neg_lo:[0,1] neg_hi:[0,1]
	v_pk_add_f32 v[98:99], v[66:67], v[76:77]
	v_pk_add_f32 v[66:67], v[66:67], v[76:77] neg_lo:[0,1] neg_hi:[0,1]
	s_nop 0
	v_pk_mul_f32 v[76:77], v[66:67], s[10:11]
	s_nop 0
	v_pk_fma_f32 v[66:67], v[66:67], s[10:11], v[76:77] op_sel:[0,0,1] op_sel_hi:[1,0,0]
	v_pk_add_f32 v[76:77], v[68:69], v[78:79]
	v_pk_add_f32 v[78:79], v[68:69], v[78:79] op_sel:[1,1] op_sel_hi:[0,0] neg_lo:[1,0] neg_hi:[0,1]
	s_nop 0
	v_pk_add_f32 v[68:69], v[72:73], v[80:81]
	v_pk_add_f32 v[72:73], v[72:73], v[80:81] neg_lo:[0,1] neg_hi:[0,1]
	v_pk_add_f32 v[136:137], v[90:91], v[78:79]
	v_pk_mul_f32 v[80:81], v[72:73], s[10:11]
	v_pk_add_f32 v[78:79], v[90:91], v[78:79] neg_lo:[0,1] neg_hi:[0,1]
	v_pk_fma_f32 v[72:73], v[72:73], s[8:9], v[80:81] op_sel:[0,0,1] op_sel_hi:[1,0,0]
	v_pk_add_f32 v[80:81], v[96:97], v[134:135]
	v_pk_add_f32 v[96:97], v[96:97], v[134:135] neg_lo:[0,1] neg_hi:[0,1]
	v_pk_add_f32 v[134:135], v[132:133], v[124:125]
	v_pk_add_f32 v[132:133], v[132:133], v[124:125] op_sel:[1,1] op_sel_hi:[0,0] neg_lo:[1,0] neg_hi:[0,1]
	v_pk_add_f32 v[90:91], v[66:67], v[72:73]
	v_pk_add_f32 v[124:125], v[120:121], v[130:131]
	v_pk_add_f32 v[120:121], v[120:121], v[130:131] neg_lo:[0,1] neg_hi:[0,1]
	v_pk_add_f32 v[130:131], v[106:107], v[118:119]
	v_pk_add_f32 v[118:119], v[106:107], v[118:119] op_sel:[1,1] op_sel_hi:[0,0] neg_lo:[1,0] neg_hi:[0,1]
	v_pk_add_f32 v[66:67], v[66:67], v[72:73] neg_lo:[0,1] neg_hi:[0,1]
	v_pk_add_f32 v[106:107], v[126:127], v[108:109]
	v_pk_add_f32 v[108:109], v[126:127], v[108:109] neg_lo:[0,1] neg_hi:[0,1]
	v_pk_add_f32 v[126:127], v[122:123], v[100:101]
	v_pk_add_f32 v[122:123], v[122:123], v[100:101] op_sel:[1,1] op_sel_hi:[0,0] neg_lo:[1,0] neg_hi:[0,1]
	v_xor_b32_e32 v72, 0x80000000, v67
	v_pk_add_f32 v[100:101], v[114:115], v[110:111]
	v_pk_add_f32 v[110:111], v[114:115], v[110:111] neg_lo:[0,1] neg_hi:[0,1]
	v_pk_add_f32 v[114:115], v[82:83], v[102:103]
	v_pk_add_f32 v[102:103], v[82:83], v[102:103] op_sel:[1,1] op_sel_hi:[0,0] neg_lo:[1,0] neg_hi:[0,1]
	v_mov_b32_e32 v73, v66
	v_pk_add_f32 v[82:83], v[112:113], v[116:117]
	v_pk_add_f32 v[112:113], v[112:113], v[116:117] neg_lo:[0,1] neg_hi:[0,1]
	v_pk_add_f32 v[116:117], v[128:129], v[84:85]
	v_pk_add_f32 v[128:129], v[128:129], v[84:85] op_sel:[1,1] op_sel_hi:[0,0] neg_lo:[1,0] neg_hi:[0,1]
	v_pk_add_f32 v[138:139], v[80:81], v[134:135]
	v_pk_add_f32 v[84:85], v[88:89], v[92:93]
	v_pk_add_f32 v[88:89], v[88:89], v[92:93] neg_lo:[0,1] neg_hi:[0,1]
	v_pk_add_f32 v[92:93], v[74:75], v[86:87]
	v_pk_add_f32 v[86:87], v[74:75], v[86:87] op_sel:[1,1] op_sel_hi:[0,0] neg_lo:[1,0] neg_hi:[0,1]
	v_pk_add_f32 v[80:81], v[80:81], v[134:135] neg_lo:[0,1] neg_hi:[0,1]
	v_pk_add_f32 v[74:75], v[94:95], v[76:77]
	v_pk_add_f32 v[76:77], v[94:95], v[76:77] neg_lo:[0,1] neg_hi:[0,1]
	v_pk_add_f32 v[94:95], v[98:99], v[68:69]
	v_pk_add_f32 v[98:99], v[98:99], v[68:69] op_sel:[1,1] op_sel_hi:[0,0] neg_lo:[1,0] neg_hi:[0,1]
	v_pk_add_f32 v[134:135], v[96:97], v[132:133]
	v_pk_add_f32 v[96:97], v[96:97], v[132:133] neg_lo:[0,1] neg_hi:[0,1]
	v_pk_add_f32 v[132:133], v[124:125], v[130:131]
	v_pk_add_f32 v[124:125], v[124:125], v[130:131] neg_lo:[0,1] neg_hi:[0,1]
	v_pk_add_f32 v[130:131], v[120:121], v[118:119]
	v_pk_add_f32 v[68:69], v[120:121], v[118:119] neg_lo:[0,1] neg_hi:[0,1]
	v_pk_add_f32 v[118:119], v[106:107], v[126:127]
	v_pk_add_f32 v[106:107], v[106:107], v[126:127] neg_lo:[0,1] neg_hi:[0,1]
	v_pk_add_f32 v[126:127], v[78:79], v[72:73]
	v_pk_add_f32 v[72:73], v[78:79], v[72:73] neg_lo:[0,1] neg_hi:[0,1]
	v_mul_f32_e32 v78, 0x38800000, v105
	v_sin_f32_e32 v79, v78
	v_cos_f32_e32 v78, v78
	v_pk_add_f32 v[120:121], v[108:109], v[122:123]
	v_pk_add_f32 v[108:109], v[108:109], v[122:123] neg_lo:[0,1] neg_hi:[0,1]
	v_pk_add_f32 v[122:123], v[100:101], v[114:115]
	v_pk_add_f32 v[100:101], v[100:101], v[114:115] neg_lo:[0,1] neg_hi:[0,1]
	v_pk_add_f32 v[114:115], v[110:111], v[102:103]
	v_pk_add_f32 v[66:67], v[110:111], v[102:103] neg_lo:[0,1] neg_hi:[0,1]
	v_pk_add_f32 v[102:103], v[82:83], v[116:117]
	v_pk_add_f32 v[82:83], v[82:83], v[116:117] neg_lo:[0,1] neg_hi:[0,1]
	v_pk_add_f32 v[116:117], v[84:85], v[92:93]
	v_pk_add_f32 v[84:85], v[84:85], v[92:93] neg_lo:[0,1] neg_hi:[0,1]
	v_pk_add_f32 v[92:93], v[88:89], v[86:87]
	v_pk_add_f32 v[86:87], v[88:89], v[86:87] neg_lo:[0,1] neg_hi:[0,1]
	v_pk_add_f32 v[88:89], v[74:75], v[94:95]
	v_pk_add_f32 v[74:75], v[74:75], v[94:95] neg_lo:[0,1] neg_hi:[0,1]
	v_pk_add_f32 v[94:95], v[76:77], v[98:99]
	v_pk_add_f32 v[76:77], v[76:77], v[98:99] neg_lo:[0,1] neg_hi:[0,1]
	v_pk_add_f32 v[98:99], v[136:137], v[90:91]
	v_pk_add_f32 v[90:91], v[136:137], v[90:91] neg_lo:[0,1] neg_hi:[0,1]
	v_sin_f32_e32 v136, v71
	v_pk_add_f32 v[110:111], v[112:113], v[128:129]
	v_pk_add_f32 v[112:113], v[112:113], v[128:129] neg_lo:[0,1] neg_hi:[0,1]
	v_cos_f32_e32 v128, v71
	v_pk_mul_f32 v[140:141], v[138:139], v[78:79] op_sel:[1,1] op_sel_hi:[0,1] neg_lo:[0,1]
	s_nop 0
	v_pk_fma_f32 v[138:139], v[138:139], v[78:79], v[140:141] op_sel_hi:[1,0,1]
	ds_write_b64 v142, v[138:139]
	v_pk_mul_f32 v[138:139], v[136:137], v[78:79] op_sel:[0,1] op_sel_hi:[0,0] neg_lo:[1,0]
	v_pk_fma_f32 v[78:79], v[78:79], v[128:129], v[138:139] op_sel_hi:[1,0,1]
	s_nop 0
	v_pk_mul_f32 v[138:139], v[102:103], v[78:79] op_sel:[1,1] op_sel_hi:[0,1] neg_lo:[0,1]
	s_nop 0
	v_pk_fma_f32 v[102:103], v[102:103], v[78:79], v[138:139] op_sel_hi:[1,0,1]
	v_pk_mul_f32 v[138:139], v[136:137], v[78:79] op_sel:[0,1] op_sel_hi:[0,0] neg_lo:[1,0]
	v_pk_fma_f32 v[78:79], v[78:79], v[128:129], v[138:139] op_sel_hi:[1,0,1]
	s_nop 0
	v_pk_mul_f32 v[138:139], v[118:119], v[78:79] op_sel:[1,1] op_sel_hi:[0,1] neg_lo:[0,1]
	s_nop 0
	v_pk_fma_f32 v[118:119], v[118:119], v[78:79], v[138:139] op_sel_hi:[1,0,1]
	ds_write2_b64 v0, v[102:103], v[118:119] offset0:33 offset1:66
	v_pk_mul_f32 v[102:103], v[136:137], v[78:79] op_sel:[0,1] op_sel_hi:[0,0] neg_lo:[1,0]
	v_pk_fma_f32 v[78:79], v[78:79], v[128:129], v[102:103] op_sel_hi:[1,0,1]
	s_nop 0
	v_pk_mul_f32 v[102:103], v[88:89], v[78:79] op_sel:[1,1] op_sel_hi:[0,1] neg_lo:[0,1]
	s_nop 0
	v_pk_fma_f32 v[88:89], v[88:89], v[78:79], v[102:103] op_sel_hi:[1,0,1]
	v_pk_mul_f32 v[102:103], v[136:137], v[78:79] op_sel:[0,1] op_sel_hi:[0,0] neg_lo:[1,0]
	v_pk_fma_f32 v[78:79], v[78:79], v[128:129], v[102:103] op_sel_hi:[1,0,1]
	s_nop 0
	v_pk_mul_f32 v[102:103], v[132:133], v[78:79] op_sel:[1,1] op_sel_hi:[0,1] neg_lo:[0,1]
	s_nop 0
	v_pk_fma_f32 v[102:103], v[132:133], v[78:79], v[102:103] op_sel_hi:[1,0,1]
	ds_write2_b64 v0, v[88:89], v[102:103] offset0:99 offset1:132
	v_pk_mul_f32 v[88:89], v[136:137], v[78:79] op_sel:[0,1] op_sel_hi:[0,0] neg_lo:[1,0]
	v_pk_fma_f32 v[78:79], v[78:79], v[128:129], v[88:89] op_sel_hi:[1,0,1]
	s_nop 0
	v_pk_mul_f32 v[88:89], v[116:117], v[78:79] op_sel:[1,1] op_sel_hi:[0,1] neg_lo:[0,1]
	v_pk_mul_f32 v[102:103], v[136:137], v[78:79] op_sel:[0,1] op_sel_hi:[0,0] neg_lo:[1,0]
	v_pk_fma_f32 v[88:89], v[116:117], v[78:79], v[88:89] op_sel_hi:[1,0,1]
	v_pk_fma_f32 v[78:79], v[78:79], v[128:129], v[102:103] op_sel_hi:[1,0,1]
	s_nop 0
	v_pk_mul_f32 v[102:103], v[122:123], v[78:79] op_sel:[1,1] op_sel_hi:[0,1] neg_lo:[0,1]
	s_nop 0
	v_pk_fma_f32 v[102:103], v[122:123], v[78:79], v[102:103] op_sel_hi:[1,0,1]
	ds_write2_b64 v0, v[88:89], v[102:103] offset0:165 offset1:198
	v_pk_mul_f32 v[88:89], v[136:137], v[78:79] op_sel:[0,1] op_sel_hi:[0,0] neg_lo:[1,0]
	v_pk_fma_f32 v[78:79], v[78:79], v[128:129], v[88:89] op_sel_hi:[1,0,1]
	s_nop 0
	v_pk_mul_f32 v[88:89], v[98:99], v[78:79] op_sel:[1,1] op_sel_hi:[0,1] neg_lo:[0,1]
	s_nop 0
	v_pk_fma_f32 v[88:89], v[98:99], v[78:79], v[88:89] op_sel_hi:[1,0,1]
	v_pk_mul_f32 v[98:99], v[136:137], v[78:79] op_sel:[0,1] op_sel_hi:[0,0] neg_lo:[1,0]
	v_pk_fma_f32 v[78:79], v[78:79], v[128:129], v[98:99] op_sel_hi:[1,0,1]
	s_nop 0
	v_pk_mul_f32 v[98:99], v[134:135], v[78:79] op_sel:[1,1] op_sel_hi:[0,1] neg_lo:[0,1]
	s_nop 0
	v_pk_fma_f32 v[98:99], v[134:135], v[78:79], v[98:99] op_sel_hi:[1,0,1]
	ds_write2_b64 v143, v[88:89], v[98:99] offset0:103 offset1:136
	v_pk_mul_f32 v[88:89], v[136:137], v[78:79] op_sel:[0,1] op_sel_hi:[0,0] neg_lo:[1,0]
	v_pk_fma_f32 v[78:79], v[78:79], v[128:129], v[88:89] op_sel_hi:[1,0,1]
	s_nop 0
	v_pk_mul_f32 v[88:89], v[110:111], v[78:79] op_sel:[1,1] op_sel_hi:[0,1] neg_lo:[0,1]
	v_pk_mul_f32 v[98:99], v[136:137], v[78:79] op_sel:[0,1] op_sel_hi:[0,0] neg_lo:[1,0]
	v_pk_fma_f32 v[88:89], v[110:111], v[78:79], v[88:89] op_sel_hi:[1,0,1]
	v_pk_fma_f32 v[78:79], v[78:79], v[128:129], v[98:99] op_sel_hi:[1,0,1]
	s_nop 0
	v_pk_mul_f32 v[98:99], v[120:121], v[78:79] op_sel:[1,1] op_sel_hi:[0,1] neg_lo:[0,1]
	s_nop 0
	v_pk_fma_f32 v[98:99], v[120:121], v[78:79], v[98:99] op_sel_hi:[1,0,1]
	ds_write2_b64 v144, v[88:89], v[98:99] offset0:41 offset1:74
	v_pk_mul_f32 v[88:89], v[136:137], v[78:79] op_sel:[0,1] op_sel_hi:[0,0] neg_lo:[1,0]
	v_pk_fma_f32 v[78:79], v[78:79], v[128:129], v[88:89] op_sel_hi:[1,0,1]
	s_nop 0
	v_pk_mul_f32 v[88:89], v[94:95], v[78:79] op_sel:[1,1] op_sel_hi:[0,1] neg_lo:[0,1]
	s_nop 0
	v_pk_fma_f32 v[88:89], v[94:95], v[78:79], v[88:89] op_sel_hi:[1,0,1]
	v_pk_mul_f32 v[94:95], v[136:137], v[78:79] op_sel:[0,1] op_sel_hi:[0,0] neg_lo:[1,0]
	v_pk_fma_f32 v[78:79], v[78:79], v[128:129], v[94:95] op_sel_hi:[1,0,1]
	s_nop 0
	v_pk_mul_f32 v[94:95], v[130:131], v[78:79] op_sel:[1,1] op_sel_hi:[0,1] neg_lo:[0,1]
	v_pk_fma_f32 v[94:95], v[130:131], v[78:79], v[94:95] op_sel_hi:[1,0,1]
	ds_write2_b64 v144, v[88:89], v[94:95] offset0:107 offset1:140
	v_pk_mul_f32 v[88:89], v[136:137], v[78:79] op_sel:[0,1] op_sel_hi:[0,0] neg_lo:[1,0]
	v_pk_fma_f32 v[78:79], v[78:79], v[128:129], v[88:89] op_sel_hi:[1,0,1]
	s_nop 0
	v_pk_mul_f32 v[88:89], v[92:93], v[78:79] op_sel:[1,1] op_sel_hi:[0,1] neg_lo:[0,1]
	v_pk_fma_f32 v[88:89], v[92:93], v[78:79], v[88:89] op_sel_hi:[1,0,1]
	v_pk_mul_f32 v[92:93], v[136:137], v[78:79] op_sel:[0,1] op_sel_hi:[0,0] neg_lo:[1,0]
	v_pk_fma_f32 v[78:79], v[78:79], v[128:129], v[92:93] op_sel_hi:[1,0,1]
	s_nop 0
	v_pk_mul_f32 v[92:93], v[114:115], v[78:79] op_sel:[1,1] op_sel_hi:[0,1] neg_lo:[0,1]
	v_pk_fma_f32 v[92:93], v[114:115], v[78:79], v[92:93] op_sel_hi:[1,0,1]
	ds_write2_b64 v144, v[88:89], v[92:93] offset0:173 offset1:206
	v_pk_mul_f32 v[88:89], v[136:137], v[78:79] op_sel:[0,1] op_sel_hi:[0,0] neg_lo:[1,0]
	v_pk_fma_f32 v[78:79], v[78:79], v[128:129], v[88:89] op_sel_hi:[1,0,1]
	s_nop 0
	v_pk_mul_f32 v[88:89], v[126:127], v[78:79] op_sel:[1,1] op_sel_hi:[0,1] neg_lo:[0,1]
	v_pk_mul_f32 v[92:93], v[136:137], v[78:79] op_sel:[0,1] op_sel_hi:[0,0] neg_lo:[1,0]
	v_pk_fma_f32 v[88:89], v[126:127], v[78:79], v[88:89] op_sel_hi:[1,0,1]
	v_pk_fma_f32 v[78:79], v[78:79], v[128:129], v[92:93] op_sel_hi:[1,0,1]
	s_nop 0
	v_pk_mul_f32 v[92:93], v[80:81], v[78:79] op_sel:[1,1] op_sel_hi:[0,1] neg_lo:[0,1]
	v_pk_fma_f32 v[80:81], v[80:81], v[78:79], v[92:93] op_sel_hi:[1,0,1]
	ds_write2_b64 v145, v[88:89], v[80:81] offset0:111 offset1:144
	v_pk_mul_f32 v[80:81], v[136:137], v[78:79] op_sel:[0,1] op_sel_hi:[0,0] neg_lo:[1,0]
	v_pk_fma_f32 v[78:79], v[78:79], v[128:129], v[80:81] op_sel_hi:[1,0,1]
	s_nop 0
	v_pk_mul_f32 v[80:81], v[82:83], v[78:79] op_sel:[1,1] op_sel_hi:[0,1] neg_lo:[0,1]
	v_pk_fma_f32 v[80:81], v[82:83], v[78:79], v[80:81] op_sel_hi:[1,0,1]
	v_pk_mul_f32 v[82:83], v[136:137], v[78:79] op_sel:[0,1] op_sel_hi:[0,0] neg_lo:[1,0]
	v_pk_fma_f32 v[78:79], v[78:79], v[128:129], v[82:83] op_sel_hi:[1,0,1]
	s_nop 0
	v_pk_mul_f32 v[82:83], v[106:107], v[78:79] op_sel:[1,1] op_sel_hi:[0,1] neg_lo:[0,1]
	v_pk_fma_f32 v[82:83], v[106:107], v[78:79], v[82:83] op_sel_hi:[1,0,1]
	ds_write2_b64 v146, v[80:81], v[82:83] offset0:49 offset1:82
	v_pk_mul_f32 v[80:81], v[136:137], v[78:79] op_sel:[0,1] op_sel_hi:[0,0] neg_lo:[1,0]
	v_pk_fma_f32 v[78:79], v[78:79], v[128:129], v[80:81] op_sel_hi:[1,0,1]
	s_nop 0
	v_pk_mul_f32 v[80:81], v[74:75], v[78:79] op_sel:[1,1] op_sel_hi:[0,1] neg_lo:[0,1]
	v_pk_fma_f32 v[74:75], v[74:75], v[78:79], v[80:81] op_sel_hi:[1,0,1]
	v_pk_mul_f32 v[80:81], v[136:137], v[78:79] op_sel:[0,1] op_sel_hi:[0,0] neg_lo:[1,0]
	v_pk_fma_f32 v[78:79], v[78:79], v[128:129], v[80:81] op_sel_hi:[1,0,1]
	s_nop 0
	v_pk_mul_f32 v[80:81], v[124:125], v[78:79] op_sel:[1,1] op_sel_hi:[0,1] neg_lo:[0,1]
	v_pk_fma_f32 v[80:81], v[124:125], v[78:79], v[80:81] op_sel_hi:[1,0,1]
	ds_write2_b64 v146, v[74:75], v[80:81] offset0:115 offset1:148
	v_pk_mul_f32 v[74:75], v[136:137], v[78:79] op_sel:[0,1] op_sel_hi:[0,0] neg_lo:[1,0]
	v_pk_fma_f32 v[74:75], v[78:79], v[128:129], v[74:75] op_sel_hi:[1,0,1]
	s_nop 0
	v_pk_mul_f32 v[78:79], v[84:85], v[74:75] op_sel:[1,1] op_sel_hi:[0,1] neg_lo:[0,1]
	v_pk_mul_f32 v[80:81], v[136:137], v[74:75] op_sel:[0,1] op_sel_hi:[0,0] neg_lo:[1,0]
	v_pk_fma_f32 v[78:79], v[84:85], v[74:75], v[78:79] op_sel_hi:[1,0,1]
	v_pk_fma_f32 v[74:75], v[74:75], v[128:129], v[80:81] op_sel_hi:[1,0,1]
	s_nop 0
	v_pk_mul_f32 v[80:81], v[100:101], v[74:75] op_sel:[1,1] op_sel_hi:[0,1] neg_lo:[0,1]
	v_pk_fma_f32 v[80:81], v[100:101], v[74:75], v[80:81] op_sel_hi:[1,0,1]
	ds_write2_b64 v146, v[78:79], v[80:81] offset0:181 offset1:214
	v_pk_mul_f32 v[78:79], v[136:137], v[74:75] op_sel:[0,1] op_sel_hi:[0,0] neg_lo:[1,0]
	v_pk_fma_f32 v[74:75], v[74:75], v[128:129], v[78:79] op_sel_hi:[1,0,1]
	s_nop 0
	v_pk_mul_f32 v[78:79], v[90:91], v[74:75] op_sel:[1,1] op_sel_hi:[0,1] neg_lo:[0,1]
	v_pk_mul_f32 v[80:81], v[136:137], v[74:75] op_sel:[0,1] op_sel_hi:[0,0] neg_lo:[1,0]
	v_pk_fma_f32 v[78:79], v[90:91], v[74:75], v[78:79] op_sel_hi:[1,0,1]
	v_pk_fma_f32 v[74:75], v[74:75], v[128:129], v[80:81] op_sel_hi:[1,0,1]
	s_nop 0
	v_pk_mul_f32 v[80:81], v[96:97], v[74:75] op_sel:[1,1] op_sel_hi:[0,1] neg_lo:[0,1]
	v_pk_fma_f32 v[80:81], v[96:97], v[74:75], v[80:81] op_sel_hi:[1,0,1]
	ds_write2_b64 v147, v[78:79], v[80:81] offset0:119 offset1:152
	v_pk_mul_f32 v[78:79], v[136:137], v[74:75] op_sel:[0,1] op_sel_hi:[0,0] neg_lo:[1,0]
	v_pk_fma_f32 v[74:75], v[74:75], v[128:129], v[78:79] op_sel_hi:[1,0,1]
	s_nop 0
	v_pk_mul_f32 v[78:79], v[112:113], v[74:75] op_sel:[1,1] op_sel_hi:[0,1] neg_lo:[0,1]
	v_pk_mul_f32 v[80:81], v[136:137], v[74:75] op_sel:[0,1] op_sel_hi:[0,0] neg_lo:[1,0]
	v_pk_fma_f32 v[78:79], v[112:113], v[74:75], v[78:79] op_sel_hi:[1,0,1]
	v_pk_fma_f32 v[74:75], v[74:75], v[128:129], v[80:81] op_sel_hi:[1,0,1]
	s_nop 0
	v_pk_mul_f32 v[80:81], v[108:109], v[74:75] op_sel:[1,1] op_sel_hi:[0,1] neg_lo:[0,1]
	v_pk_fma_f32 v[80:81], v[108:109], v[74:75], v[80:81] op_sel_hi:[1,0,1]
	ds_write2_b64 v70, v[78:79], v[80:81] offset0:57 offset1:90
	v_pk_mul_f32 v[78:79], v[136:137], v[74:75] op_sel:[0,1] op_sel_hi:[0,0] neg_lo:[1,0]
	v_pk_fma_f32 v[74:75], v[74:75], v[128:129], v[78:79] op_sel_hi:[1,0,1]
	s_nop 0
	v_pk_mul_f32 v[78:79], v[76:77], v[74:75] op_sel:[1,1] op_sel_hi:[0,1] neg_lo:[0,1]
	v_pk_fma_f32 v[76:77], v[76:77], v[74:75], v[78:79] op_sel_hi:[1,0,1]
	v_pk_mul_f32 v[78:79], v[136:137], v[74:75] op_sel:[0,1] op_sel_hi:[0,0] neg_lo:[1,0]
	v_pk_fma_f32 v[74:75], v[74:75], v[128:129], v[78:79] op_sel_hi:[1,0,1]
	s_nop 0
	v_pk_mul_f32 v[78:79], v[68:69], v[74:75] op_sel:[1,1] op_sel_hi:[0,1] neg_lo:[0,1]
	v_pk_fma_f32 v[68:69], v[68:69], v[74:75], v[78:79] op_sel_hi:[1,0,1]
	ds_write2_b64 v70, v[76:77], v[68:69] offset0:123 offset1:156
	v_pk_mul_f32 v[68:69], v[136:137], v[74:75] op_sel:[0,1] op_sel_hi:[0,0] neg_lo:[1,0]
	v_pk_fma_f32 v[68:69], v[74:75], v[128:129], v[68:69] op_sel_hi:[1,0,1]
	s_nop 0
	v_pk_mul_f32 v[74:75], v[86:87], v[68:69] op_sel:[1,1] op_sel_hi:[0,1] neg_lo:[0,1]
	v_pk_mul_f32 v[76:77], v[136:137], v[68:69] op_sel:[0,1] op_sel_hi:[0,0] neg_lo:[1,0]
	v_pk_fma_f32 v[74:75], v[86:87], v[68:69], v[74:75] op_sel_hi:[1,0,1]
	v_pk_fma_f32 v[68:69], v[68:69], v[128:129], v[76:77] op_sel_hi:[1,0,1]
	s_nop 0
	v_pk_mul_f32 v[76:77], v[66:67], v[68:69] op_sel:[1,1] op_sel_hi:[0,1] neg_lo:[0,1]
	v_pk_fma_f32 v[66:67], v[66:67], v[68:69], v[76:77] op_sel_hi:[1,0,1]
	ds_write2_b64 v70, v[74:75], v[66:67] offset0:189 offset1:222
	v_pk_mul_f32 v[66:67], v[136:137], v[68:69] op_sel:[0,1] op_sel_hi:[0,0] neg_lo:[1,0]
	v_pk_fma_f32 v[66:67], v[68:69], v[128:129], v[66:67] op_sel_hi:[1,0,1]
	s_nop 0
	v_pk_mul_f32 v[68:69], v[72:73], v[66:67] op_sel:[1,1] op_sel_hi:[0,1] neg_lo:[0,1]
	v_pk_fma_f32 v[66:67], v[72:73], v[66:67], v[68:69] op_sel_hi:[1,0,1]
	ds_write_b64 v0, v[66:67] offset:8184
	s_waitcnt lgkmcnt(0)
	s_barrier
